# FFN1 epilogue: the two adjacent 8-byte halves of every output row leave as one global_store_dwordx4 (8 stores per lane and tile instead of 16)
# baseline (speedup 1.0000x reference)
; #define LAS __attribute__((address_space(3)))
; __device__ __forceinline__ float sigmoidf_(float x) { return __builtin_amdgcn_rcpf(1.0f + __expf(-x)); }
;     __device__ __forceinline__ void operator()(AccRef acc, const Unit& u, int wr, int wc, int fr, int fq) const {
;     ...
;                 f32x4 h2v = (f32x4){0.f, 0.f, 0.f, 0.f}, h3v = h2v, h2g = h2v, h3g = h2v;
;                 const int pb = ai * 2 + wr - 1;
;                 if (pb >= 0 && fr == 0) { const LAS float* xp = xch + (pb * 2) * 256 + clb + 4 * n;
;                     h2v = *(const LAS f32x4*)(xp); h3v = *(const LAS f32x4*)(xp + 256); h2g = *(const LAS f32x4*)(xp + 128); h3g = *(const LAS f32x4*)(xp + 256 + 128); }
;                 float o[4][4];
; #pragma unroll
;                 for (int j = 0; j < 4; ++j) {
;                     const float v0 = acc[ai][0][0][n][j], v1 = acc[ai][0][1][n][j], v2 = acc[ai][0][2][n][j], v3 = acc[ai][0][3][n][j];
;                     const float g0 = acc[ai][1][0][n][j], g1 = acc[ai][1][1][n][j], g2 = acc[ai][1][2][n][j], g3 = acc[ai][1][3][n][j];
;                     const float pv3 = dpp_upd<0x111>(h3v[j], v3), pv2 = dpp_upd<0x111>(h2v[j], v2), pg3 = dpp_upd<0x111>(h3g[j], g3), pg2 = dpp_upd<0x111>(h2g[j], g2);
;                     const float hv0 = bvv[j] + w2v[j] * v0 + w1v[j] * pv3 + w0v[j] * pv2, hv1 = bvv[j] + w2v[j] * v1 + w1v[j] * v0 + w0v[j] * pv3;
;                     const float hv2 = bvv[j] + w2v[j] * v2 + w1v[j] * v1 + w0v[j] * v0, hv3 = bvv[j] + w2v[j] * v3 + w1v[j] * v2 + w0v[j] * v1;
;                     const float hg0 = bvg[j] + w2g[j] * g0 + w1g[j] * pg3 + w0g[j] * pg2, hg1 = bvg[j] + w2g[j] * g1 + w1g[j] * g0 + w0g[j] * pg3;
;                     const float hg2 = bvg[j] + w2g[j] * g2 + w1g[j] * g1 + w0g[j] * g0, hg3 = bvg[j] + w2g[j] * g3 + w1g[j] * g2 + w0g[j] * g1;
;                     o[0][j] = hg0 * sigmoidf_(hg0) * hv0; o[1][j] = hg1 * sigmoidf_(hg1) * hv1; o[2][j] = hg2 * sigmoidf_(hg2) * hv2; o[3][j] = hg3 * sigmoidf_(hg3) * hv3; }
; #pragma unroll
;                 for (int m = 0; m < 4; ++m) { u32x2 w; w.x = cvt_pk_bf16(o[m][0], o[m][1]); w.y = cvt_pk_bf16(o[m][2], o[m][3]);
;                     *(u32x2*)(Aout + (size_t)(row0 + ai * 128 + m) * FH + hc0 + 4 * n) = w; } } }
.LBB0_305:
	s_or_b64 exec, exec, s[34:35]
	s_waitcnt lgkmcnt(0)
	v_mov_b32_dpp v64, v8 row_shr:1 row_mask:0xf bank_mask:0xf
	v_mov_b32_dpp v65, v9 row_shr:1 row_mask:0xf bank_mask:0xf
	v_pk_fma_f32 v[44:45], v[24:25], v[120:121], v[124:125]
	v_mov_b32_dpp v40, v0 row_shr:1 row_mask:0xf bank_mask:0xf
	v_mov_b32_dpp v41, v1 row_shr:1 row_mask:0xf bank_mask:0xf
	v_pk_fma_f32 v[44:45], v[116:117], v[64:65], v[44:45]
	v_mov_b32_dpp v32, v20 row_shr:1 row_mask:0xf bank_mask:0xf
	v_pk_fma_f32 v[40:41], v[112:113], v[40:41], v[44:45]
	v_mov_b32_dpp v33, v21 row_shr:1 row_mask:0xf bank_mask:0xf
	v_mul_f32_e32 v44, 0xbfb8aa3b, v40
	v_mul_f32_e32 v45, 0xbfb8aa3b, v41
	v_exp_f32_e32 v44, v44
	v_exp_f32_e32 v45, v45
	v_pk_fma_f32 v[46:47], v[28:29], v[104:105], v[108:109]
	v_mov_b32_dpp v36, v12 row_shr:1 row_mask:0xf bank_mask:0xf
	v_add_f32_e32 v44, 1.0, v44
	v_add_f32_e32 v45, 1.0, v45
	v_rcp_f32_e32 v44, v44
	v_rcp_f32_e32 v45, v45
	v_mov_b32_dpp v37, v13 row_shr:1 row_mask:0xf bank_mask:0xf
	v_pk_fma_f32 v[46:47], v[100:101], v[32:33], v[46:47]
	v_mov_b32_dpp v66, v10 row_shr:1 row_mask:0xf bank_mask:0xf
	v_pk_fma_f32 v[36:37], v[96:97], v[36:37], v[46:47]
	v_pk_mul_f32 v[40:41], v[40:41], v[44:45]
	v_mov_b32_dpp v67, v11 row_shr:1 row_mask:0xf bank_mask:0xf
	v_pk_mul_f32 v[36:37], v[36:37], v[40:41]
	v_pk_fma_f32 v[40:41], v[26:27], v[122:123], v[126:127]
	v_mov_b32_dpp v42, v2 row_shr:1 row_mask:0xf bank_mask:0xf
	v_mov_b32_dpp v43, v3 row_shr:1 row_mask:0xf bank_mask:0xf
	v_pk_fma_f32 v[40:41], v[118:119], v[66:67], v[40:41]
	v_cvt_pk_bf16_f32 v36, v36, v37
	v_pk_fma_f32 v[40:41], v[114:115], v[42:43], v[40:41]
	v_mov_b32_dpp v34, v22 row_shr:1 row_mask:0xf bank_mask:0xf
	v_mul_f32_e32 v42, 0xbfb8aa3b, v40
	v_exp_f32_e32 v42, v42
	v_mul_f32_e32 v43, 0xbfb8aa3b, v41
	v_exp_f32_e32 v43, v43
	v_mov_b32_dpp v35, v23 row_shr:1 row_mask:0xf bank_mask:0xf
	v_add_f32_e32 v37, 1.0, v42
	v_rcp_f32_e32 v42, v37
	v_add_f32_e32 v37, 1.0, v43
	v_rcp_f32_e32 v43, v37
	v_pk_fma_f32 v[44:45], v[30:31], v[106:107], v[110:111]
	v_mov_b32_dpp v38, v14 row_shr:1 row_mask:0xf bank_mask:0xf
	v_mov_b32_dpp v39, v15 row_shr:1 row_mask:0xf bank_mask:0xf
	v_pk_fma_f32 v[44:45], v[102:103], v[34:35], v[44:45]
	v_pk_mul_f32 v[40:41], v[40:41], v[42:43]
	v_pk_fma_f32 v[38:39], v[98:99], v[38:39], v[44:45]
	v_pk_fma_f32 v[8:9], v[8:9], v[120:121], v[124:125]
	v_pk_mul_f32 v[38:39], v[38:39], v[40:41]
	v_pk_fma_f32 v[20:21], v[20:21], v[104:105], v[108:109]
	v_cvt_pk_bf16_f32 v37, v38, v39
	v_pk_fma_f32 v[38:39], v[4:5], v[120:121], v[124:125]
	v_mov_b32_e32 v146, v36
	v_mov_b32_e32 v147, v37
	global_store_dwordx4 v[132:133], v[144:147], off
	v_pk_fma_f32 v[38:39], v[24:25], v[116:117], v[38:39]
	s_and_b64 vcc, exec, s[12:13]
	v_pk_fma_f32 v[38:39], v[112:113], v[64:65], v[38:39]
	s_mov_b32 s35, s24
	v_mul_f32_e32 v40, 0xbfb8aa3b, v38
	v_mul_f32_e32 v41, 0xbfb8aa3b, v39
	v_exp_f32_e32 v40, v40
	v_exp_f32_e32 v41, v41
	s_mov_b32 s34, s26
	s_mov_b64 s[38:39], s[30:31]
	v_add_f32_e32 v36, 1.0, v40
	v_add_f32_e32 v37, 1.0, v41
	v_rcp_f32_e32 v36, v36
	v_rcp_f32_e32 v37, v37
	v_pk_fma_f32 v[40:41], v[16:17], v[104:105], v[108:109]
	s_mov_b64 s[36:37], s[28:29]
	v_pk_fma_f32 v[40:41], v[28:29], v[100:101], v[40:41]
	v_pk_mul_f32 v[36:37], v[38:39], v[36:37]
	v_pk_fma_f32 v[32:33], v[96:97], v[32:33], v[40:41]
	v_pk_fma_f32 v[40:41], v[18:19], v[106:107], v[110:111]
	v_pk_mul_f32 v[32:33], v[32:33], v[36:37]
	v_pk_fma_f32 v[36:37], v[6:7], v[122:123], v[126:127]
	v_cvt_pk_bf16_f32 v32, v32, v33
	v_pk_fma_f32 v[36:37], v[26:27], v[118:119], v[36:37]
	v_pk_fma_f32 v[40:41], v[30:31], v[102:103], v[40:41]
	v_pk_fma_f32 v[36:37], v[114:115], v[66:67], v[36:37]
	v_pk_fma_f32 v[34:35], v[98:99], v[34:35], v[40:41]
	v_mul_f32_e32 v38, 0xbfb8aa3b, v36
	v_exp_f32_e32 v38, v38
	v_mul_f32_e32 v39, 0xbfb8aa3b, v37
	v_exp_f32_e32 v39, v39
	v_add_f32_e32 v33, 1.0, v38
	v_rcp_f32_e32 v38, v33
	v_add_f32_e32 v33, 1.0, v39
	v_rcp_f32_e32 v39, v33
	s_nop 0
	v_pk_mul_f32 v[36:37], v[36:37], v[38:39]
	s_nop 0
	v_pk_mul_f32 v[34:35], v[34:35], v[36:37]
	s_nop 0
	v_cvt_pk_bf16_f32 v33, v34, v35
	v_pk_fma_f32 v[34:35], v[0:1], v[120:121], v[124:125]
	v_mov_b32_e32 v156, v32
	v_mov_b32_e32 v157, v33
	global_store_dwordx4 v[128:129], v[154:157], off
	v_pk_fma_f32 v[34:35], v[4:5], v[116:117], v[34:35]
	v_pk_fma_f32 v[0:1], v[0:1], v[116:117], v[8:9]
	v_pk_fma_f32 v[24:25], v[24:25], v[112:113], v[34:35]
	v_pk_fma_f32 v[0:1], v[4:5], v[112:113], v[0:1]
	v_mul_f32_e32 v34, 0xbfb8aa3b, v24
	v_mul_f32_e32 v35, 0xbfb8aa3b, v25
	v_exp_f32_e32 v34, v34
	v_exp_f32_e32 v35, v35
	v_mul_f32_e32 v4, 0xbfb8aa3b, v0
	v_exp_f32_e32 v8, v4
	v_add_f32_e32 v32, 1.0, v34
	v_add_f32_e32 v33, 1.0, v35
	v_rcp_f32_e32 v32, v32
	v_rcp_f32_e32 v33, v33
	v_pk_fma_f32 v[34:35], v[12:13], v[104:105], v[108:109]
	v_pk_fma_f32 v[4:5], v[10:11], v[122:123], v[126:127]
	v_pk_fma_f32 v[34:35], v[16:17], v[100:101], v[34:35]
	v_pk_mul_f32 v[24:25], v[24:25], v[32:33]
	v_pk_fma_f32 v[28:29], v[28:29], v[96:97], v[34:35]
	v_mul_f32_e32 v9, 0xbfb8aa3b, v1
	v_pk_mul_f32 v[24:25], v[28:29], v[24:25]
	v_pk_fma_f32 v[28:29], v[2:3], v[122:123], v[126:127]
	v_pk_fma_f32 v[2:3], v[2:3], v[118:119], v[4:5]
	v_pk_fma_f32 v[28:29], v[6:7], v[118:119], v[28:29]
	v_pk_fma_f32 v[2:3], v[6:7], v[114:115], v[2:3]
	v_pk_fma_f32 v[26:27], v[26:27], v[114:115], v[28:29]
	v_mul_f32_e32 v4, 0xbfb8aa3b, v2
	v_mul_f32_e32 v28, 0xbfb8aa3b, v26
	v_exp_f32_e32 v28, v28
	v_mul_f32_e32 v29, 0xbfb8aa3b, v27
	v_mul_f32_e32 v5, 0xbfb8aa3b, v3
	v_exp_f32_e32 v29, v29
	v_exp_f32_e32 v9, v9
	v_exp_f32_e32 v4, v4
	v_exp_f32_e32 v5, v5
	v_cvt_pk_bf16_f32 v24, v24, v25
	v_add_f32_e32 v25, 1.0, v28
	v_rcp_f32_e32 v28, v25
	v_add_f32_e32 v25, 1.0, v29
	v_add_f32_e32 v8, 1.0, v8
	v_add_f32_e32 v9, 1.0, v9
	v_add_f32_e32 v4, 1.0, v4
	v_add_f32_e32 v5, 1.0, v5
	v_rcp_f32_e32 v29, v25
	v_rcp_f32_e32 v8, v8
	v_rcp_f32_e32 v9, v9
	v_rcp_f32_e32 v4, v4
	v_rcp_f32_e32 v5, v5
	v_pk_fma_f32 v[32:33], v[14:15], v[106:107], v[110:111]
	v_pk_fma_f32 v[10:11], v[22:23], v[106:107], v[110:111]
	v_pk_fma_f32 v[32:33], v[18:19], v[102:103], v[32:33]
	v_pk_fma_f32 v[12:13], v[12:13], v[100:101], v[20:21]
	v_pk_fma_f32 v[6:7], v[14:15], v[102:103], v[10:11]
	v_pk_fma_f32 v[30:31], v[30:31], v[98:99], v[32:33]
	v_pk_mul_f32 v[26:27], v[26:27], v[28:29]
	v_pk_fma_f32 v[12:13], v[16:17], v[96:97], v[12:13]
	v_pk_mul_f32 v[0:1], v[0:1], v[8:9]
	v_pk_fma_f32 v[6:7], v[18:19], v[98:99], v[6:7]
	v_pk_mul_f32 v[2:3], v[2:3], v[4:5]
	v_pk_mul_f32 v[26:27], v[30:31], v[26:27]
	v_pk_mul_f32 v[0:1], v[12:13], v[0:1]
	v_pk_mul_f32 v[2:3], v[6:7], v[2:3]
	v_cvt_pk_bf16_f32 v25, v26, v27
	v_cvt_pk_bf16_f32 v0, v0, v1
	v_cvt_pk_bf16_f32 v1, v2, v3
	v_mov_b32_e32 v200, v24
	v_mov_b32_e32 v201, v25
	global_store_dwordx4 v[88:89], v[198:201], off
	v_mov_b32_e32 v150, v0
	v_mov_b32_e32 v151, v1
	global_store_dwordx4 v[82:83], v[148:151], off
	s_cbranch_vccnz .LBB0_324

; #define LAS __attribute__((address_space(3)))
; __device__ __forceinline__ float sigmoidf_(float x) { return __builtin_amdgcn_rcpf(1.0f + __expf(-x)); }
;     __device__ __forceinline__ void operator()(AccRef acc, const Unit& u, int wr, int wc, int fr, int fq) const {
;     ...
;                 f32x4 h2v = (f32x4){0.f, 0.f, 0.f, 0.f}, h3v = h2v, h2g = h2v, h3g = h2v;
;                 const int pb = ai * 2 + wr - 1;
;                 if (pb >= 0 && fr == 0) { const LAS float* xp = xch + (pb * 2) * 256 + clb + 4 * n;
;                     h2v = *(const LAS f32x4*)(xp); h3v = *(const LAS f32x4*)(xp + 256); h2g = *(const LAS f32x4*)(xp + 128); h3g = *(const LAS f32x4*)(xp + 256 + 128); }
;                 float o[4][4];
; #pragma unroll
;                 for (int j = 0; j < 4; ++j) {
;                     const float v0 = acc[ai][0][0][n][j], v1 = acc[ai][0][1][n][j], v2 = acc[ai][0][2][n][j], v3 = acc[ai][0][3][n][j];
;                     const float g0 = acc[ai][1][0][n][j], g1 = acc[ai][1][1][n][j], g2 = acc[ai][1][2][n][j], g3 = acc[ai][1][3][n][j];
;                     const float pv3 = dpp_upd<0x111>(h3v[j], v3), pv2 = dpp_upd<0x111>(h2v[j], v2), pg3 = dpp_upd<0x111>(h3g[j], g3), pg2 = dpp_upd<0x111>(h2g[j], g2);
;                     const float hv0 = bvv[j] + w2v[j] * v0 + w1v[j] * pv3 + w0v[j] * pv2, hv1 = bvv[j] + w2v[j] * v1 + w1v[j] * v0 + w0v[j] * pv3;
;                     const float hv2 = bvv[j] + w2v[j] * v2 + w1v[j] * v1 + w0v[j] * v0, hv3 = bvv[j] + w2v[j] * v3 + w1v[j] * v2 + w0v[j] * v1;
;                     const float hg0 = bvg[j] + w2g[j] * g0 + w1g[j] * pg3 + w0g[j] * pg2, hg1 = bvg[j] + w2g[j] * g1 + w1g[j] * g0 + w0g[j] * pg3;
;                     const float hg2 = bvg[j] + w2g[j] * g2 + w1g[j] * g1 + w0g[j] * g0, hg3 = bvg[j] + w2g[j] * g3 + w1g[j] * g2 + w0g[j] * g1;
;                     o[0][j] = hg0 * sigmoidf_(hg0) * hv0; o[1][j] = hg1 * sigmoidf_(hg1) * hv1; o[2][j] = hg2 * sigmoidf_(hg2) * hv2; o[3][j] = hg3 * sigmoidf_(hg3) * hv3; }
; #pragma unroll
;                 for (int m = 0; m < 4; ++m) { u32x2 w; w.x = cvt_pk_bf16(o[m][0], o[m][1]); w.y = cvt_pk_bf16(o[m][2], o[m][3]);
;                     *(u32x2*)(Aout + (size_t)(row0 + ai * 128 + m) * FH + hc0 + 4 * n) = w; } } }
.LBB0_316:
	s_or_b64 exec, exec, s[40:41]
	v_pk_fma_f32 v[248:249], v[152:153], v[184:185], v[188:189]
	v_mov_b32_dpp v206, v128 row_shr:1 row_mask:0xf bank_mask:0xf
	v_mov_b32_dpp v207, v129 row_shr:1 row_mask:0xf bank_mask:0xf
	v_pk_fma_f32 v[248:249], v[180:181], v[198:199], v[248:249]
	v_mov_b32_dpp v194, v148 row_shr:1 row_mask:0xf bank_mask:0xf
	v_pk_fma_f32 v[206:207], v[176:177], v[206:207], v[248:249]
	v_mov_b32_dpp v195, v149 row_shr:1 row_mask:0xf bank_mask:0xf
	v_mul_f32_e32 v193, 0xbfb8aa3b, v206
	v_exp_f32_e32 v193, v193
	v_mul_f32_e32 v247, 0xbfb8aa3b, v207
	v_exp_f32_e32 v247, v247
	v_pk_fma_f32 v[250:251], v[156:157], v[168:169], v[172:173]
	v_add_f32_e32 v193, 1.0, v193
	v_rcp_f32_e32 v248, v193
	v_add_f32_e32 v193, 1.0, v247
	v_rcp_f32_e32 v249, v193
	v_mov_b32_dpp v202, v136 row_shr:1 row_mask:0xf bank_mask:0xf
	v_mov_b32_dpp v203, v137 row_shr:1 row_mask:0xf bank_mask:0xf
	v_pk_fma_f32 v[250:251], v[164:165], v[194:195], v[250:251]
	v_pk_mul_f32 v[206:207], v[206:207], v[248:249]
	v_pk_fma_f32 v[202:203], v[160:161], v[202:203], v[250:251]
	v_mov_b32_dpp v200, v142 row_shr:1 row_mask:0xf bank_mask:0xf
	v_mov_b32_dpp v201, v143 row_shr:1 row_mask:0xf bank_mask:0xf
	v_pk_mul_f32 v[202:203], v[202:203], v[206:207]
	v_pk_fma_f32 v[206:207], v[154:155], v[186:187], v[190:191]
	v_mov_b32_dpp v208, v130 row_shr:1 row_mask:0xf bank_mask:0xf
	v_mov_b32_dpp v209, v131 row_shr:1 row_mask:0xf bank_mask:0xf
	v_pk_fma_f32 v[206:207], v[182:183], v[200:201], v[206:207]
	v_mov_b32_dpp v196, v150 row_shr:1 row_mask:0xf bank_mask:0xf
	v_pk_fma_f32 v[206:207], v[178:179], v[208:209], v[206:207]
	v_mov_b32_dpp v197, v151 row_shr:1 row_mask:0xf bank_mask:0xf
	v_mul_f32_e32 v193, 0xbfb8aa3b, v206
	v_exp_f32_e32 v193, v193
	v_mul_f32_e32 v208, 0xbfb8aa3b, v207
	v_exp_f32_e32 v209, v208
	v_cvt_pk_bf16_f32 v208, v202, v203
	v_add_f32_e32 v193, 1.0, v193
	v_rcp_f32_e32 v202, v193
	v_add_f32_e32 v193, 1.0, v209
	v_rcp_f32_e32 v203, v193
	v_pk_fma_f32 v[248:249], v[158:159], v[170:171], v[174:175]
	v_mov_b32_dpp v204, v138 row_shr:1 row_mask:0xf bank_mask:0xf
	v_mov_b32_dpp v205, v139 row_shr:1 row_mask:0xf bank_mask:0xf
	v_pk_fma_f32 v[248:249], v[166:167], v[196:197], v[248:249]
	v_pk_mul_f32 v[202:203], v[206:207], v[202:203]
	v_pk_fma_f32 v[204:205], v[162:163], v[204:205], v[248:249]
	v_lshl_add_u32 v246, s34, 8, v236
	v_pk_mul_f32 v[202:203], v[204:205], v[202:203]
	v_lshlrev_b64 v[204:205], 1, v[232:233]
	v_pk_fma_f32 v[232:233], v[132:133], v[184:185], v[188:189]
	v_mov_b64_e32 v[206:207], s[60:61]
	v_pk_fma_f32 v[232:233], v[152:153], v[180:181], v[232:233]
	v_cvt_pk_bf16_f32 v209, v202, v203
	v_pk_fma_f32 v[198:199], v[176:177], v[198:199], v[232:233]
	v_mad_i64_i32 v[202:203], s[34:35], v246, s74, v[206:207]
	v_mul_f32_e32 v193, 0xbfb8aa3b, v198
	v_exp_f32_e32 v193, v193
	v_mul_f32_e32 v232, 0xbfb8aa3b, v199
	v_exp_f32_e32 v232, v232
	v_lshl_add_u64 v[202:203], v[202:203], 0, v[204:205]
	v_add_f32_e32 v193, 1.0, v193
	v_mov_b32_e32 v247, v208
	v_mov_b32_e32 v248, v209
	v_rcp_f32_e32 v208, v193
	v_add_f32_e32 v193, 1.0, v232
	v_rcp_f32_e32 v209, v193
	v_pk_fma_f32 v[232:233], v[144:145], v[168:169], v[172:173]
	v_pk_fma_f32 v[140:141], v[140:141], v[184:185], v[188:189]
	v_pk_fma_f32 v[232:233], v[156:157], v[164:165], v[232:233]
	v_pk_mul_f32 v[198:199], v[198:199], v[208:209]
	v_pk_fma_f32 v[194:195], v[160:161], v[194:195], v[232:233]
	v_pk_fma_f32 v[208:209], v[146:147], v[170:171], v[174:175]
	v_pk_mul_f32 v[194:195], v[194:195], v[198:199]
	v_pk_fma_f32 v[198:199], v[134:135], v[186:187], v[190:191]
	v_pk_fma_f32 v[208:209], v[158:159], v[166:167], v[208:209]
	v_pk_fma_f32 v[198:199], v[154:155], v[182:183], v[198:199]
	v_pk_fma_f32 v[196:197], v[162:163], v[196:197], v[208:209]
	v_pk_fma_f32 v[198:199], v[178:179], v[200:201], v[198:199]
	v_cvt_pk_bf16_f32 v194, v194, v195
	v_mul_f32_e32 v193, 0xbfb8aa3b, v198
	v_exp_f32_e32 v193, v193
	v_mul_f32_e32 v200, 0xbfb8aa3b, v199
	v_exp_f32_e32 v201, v200
	v_pk_fma_f32 v[148:149], v[148:149], v[168:169], v[172:173]
	v_add_f32_e32 v193, 1.0, v193
	v_rcp_f32_e32 v200, v193
	v_add_f32_e32 v193, 1.0, v201
	v_rcp_f32_e32 v201, v193
	v_or_b32_e32 v193, 1, v246
	v_pk_mul_f32 v[198:199], v[198:199], v[200:201]
	s_nop 0
	v_pk_mul_f32 v[196:197], v[196:197], v[198:199]
	v_pk_fma_f32 v[198:199], v[128:129], v[184:185], v[188:189]
	v_cvt_pk_bf16_f32 v195, v196, v197
	v_pk_fma_f32 v[198:199], v[132:133], v[180:181], v[198:199]
	v_mad_i64_i32 v[196:197], s[34:35], v193, s74, v[206:207]
	v_pk_fma_f32 v[152:153], v[152:153], v[176:177], v[198:199]
	v_lshl_add_u64 v[196:197], v[196:197], 0, v[204:205]
	v_mul_f32_e32 v193, 0xbfb8aa3b, v152
	v_exp_f32_e32 v193, v193
	v_mul_f32_e32 v198, 0xbfb8aa3b, v153
	v_exp_f32_e32 v198, v198
	v_mov_b32_e32 v249, v194
	v_mov_b32_e32 v250, v195
	v_add_f32_e32 v193, 1.0, v193
	v_rcp_f32_e32 v194, v193
	v_add_f32_e32 v193, 1.0, v198
	v_rcp_f32_e32 v195, v193
	v_pk_fma_f32 v[198:199], v[136:137], v[168:169], v[172:173]
	v_pk_fma_f32 v[128:129], v[128:129], v[180:181], v[140:141]
	v_pk_fma_f32 v[198:199], v[144:145], v[164:165], v[198:199]
	v_pk_fma_f32 v[128:129], v[132:133], v[176:177], v[128:129]
	v_pk_fma_f32 v[156:157], v[156:157], v[160:161], v[198:199]
	v_pk_mul_f32 v[152:153], v[152:153], v[194:195]
	v_mul_f32_e32 v132, 0xbfb8aa3b, v128
	v_pk_mul_f32 v[152:153], v[156:157], v[152:153]
	v_pk_fma_f32 v[156:157], v[130:131], v[186:187], v[190:191]
	v_exp_f32_e32 v140, v132
	v_pk_fma_f32 v[132:133], v[142:143], v[186:187], v[190:191]
	v_pk_fma_f32 v[156:157], v[134:135], v[182:183], v[156:157]
	v_pk_fma_f32 v[130:131], v[130:131], v[182:183], v[132:133]
; #define LAS __attribute__((address_space(3)))
; __device__ __forceinline__ float sigmoidf_(float x) { return __builtin_amdgcn_rcpf(1.0f + __expf(-x)); }
;     __device__ __forceinline__ void operator()(AccRef acc, const Unit& u, int wr, int wc, int fr, int fq) const {
;     ...
;                 f32x4 h2v = (f32x4){0.f, 0.f, 0.f, 0.f}, h3v = h2v, h2g = h2v, h3g = h2v;
;                 const int pb = ai * 2 + wr - 1;
;                 if (pb >= 0 && fr == 0) { const LAS float* xp = xch + (pb * 2) * 256 + clb + 4 * n;
;                     h2v = *(const LAS f32x4*)(xp); h3v = *(const LAS f32x4*)(xp + 256); h2g = *(const LAS f32x4*)(xp + 128); h3g = *(const LAS f32x4*)(xp + 256 + 128); }
;                 float o[4][4];
; #pragma unroll
;                 for (int j = 0; j < 4; ++j) {
;                     const float v0 = acc[ai][0][0][n][j], v1 = acc[ai][0][1][n][j], v2 = acc[ai][0][2][n][j], v3 = acc[ai][0][3][n][j];
;                     const float g0 = acc[ai][1][0][n][j], g1 = acc[ai][1][1][n][j], g2 = acc[ai][1][2][n][j], g3 = acc[ai][1][3][n][j];
;                     const float pv3 = dpp_upd<0x111>(h3v[j], v3), pv2 = dpp_upd<0x111>(h2v[j], v2), pg3 = dpp_upd<0x111>(h3g[j], g3), pg2 = dpp_upd<0x111>(h2g[j], g2);
;                     const float hv0 = bvv[j] + w2v[j] * v0 + w1v[j] * pv3 + w0v[j] * pv2, hv1 = bvv[j] + w2v[j] * v1 + w1v[j] * v0 + w0v[j] * pv3;
;                     const float hv2 = bvv[j] + w2v[j] * v2 + w1v[j] * v1 + w0v[j] * v0, hv3 = bvv[j] + w2v[j] * v3 + w1v[j] * v2 + w0v[j] * v1;
;                     const float hg0 = bvg[j] + w2g[j] * g0 + w1g[j] * pg3 + w0g[j] * pg2, hg1 = bvg[j] + w2g[j] * g1 + w1g[j] * g0 + w0g[j] * pg3;
;                     const float hg2 = bvg[j] + w2g[j] * g2 + w1g[j] * g1 + w0g[j] * g0, hg3 = bvg[j] + w2g[j] * g3 + w1g[j] * g2 + w0g[j] * g1;
;                     o[0][j] = hg0 * sigmoidf_(hg0) * hv0; o[1][j] = hg1 * sigmoidf_(hg1) * hv1; o[2][j] = hg2 * sigmoidf_(hg2) * hv2; o[3][j] = hg3 * sigmoidf_(hg3) * hv3; }
; #pragma unroll
;                 for (int m = 0; m < 4; ++m) { u32x2 w; w.x = cvt_pk_bf16(o[m][0], o[m][1]); w.y = cvt_pk_bf16(o[m][2], o[m][3]);
;                     *(u32x2*)(Aout + (size_t)(row0 + ai * 128 + m) * FH + hc0 + 4 * n) = w; } } }
	v_pk_fma_f32 v[154:155], v[154:155], v[178:179], v[156:157]
	v_pk_fma_f32 v[130:131], v[134:135], v[178:179], v[130:131]
	v_mul_f32_e32 v156, 0xbfb8aa3b, v154
	v_mul_f32_e32 v141, 0xbfb8aa3b, v129
	v_mul_f32_e32 v132, 0xbfb8aa3b, v130
	v_mul_f32_e32 v133, 0xbfb8aa3b, v131
	v_exp_f32_e32 v157, v156
	v_mul_f32_e32 v156, 0xbfb8aa3b, v155
	v_exp_f32_e32 v141, v141
	v_exp_f32_e32 v132, v132
	v_exp_f32_e32 v133, v133
	v_exp_f32_e32 v193, v156
	v_add_f32_e32 v140, 1.0, v140
	v_add_f32_e32 v141, 1.0, v141
	v_add_f32_e32 v132, 1.0, v132
	v_add_f32_e32 v133, 1.0, v133
	v_cvt_pk_bf16_f32 v156, v152, v153
	v_add_f32_e32 v152, 1.0, v157
	v_add_f32_e32 v153, 1.0, v193
	v_rcp_f32_e32 v140, v140
	v_rcp_f32_e32 v141, v141
	v_rcp_f32_e32 v132, v132
	v_rcp_f32_e32 v133, v133
	v_rcp_f32_e32 v152, v152
	v_rcp_f32_e32 v153, v153
	v_pk_fma_f32 v[142:143], v[150:151], v[170:171], v[174:175]
	v_pk_fma_f32 v[194:195], v[138:139], v[170:171], v[174:175]
	v_pk_fma_f32 v[136:137], v[136:137], v[164:165], v[148:149]
	v_pk_fma_f32 v[134:135], v[138:139], v[166:167], v[142:143]
	v_pk_fma_f32 v[194:195], v[146:147], v[166:167], v[194:195]
	v_pk_fma_f32 v[136:137], v[144:145], v[160:161], v[136:137]
	v_pk_mul_f32 v[128:129], v[128:129], v[140:141]
	v_pk_fma_f32 v[134:135], v[146:147], v[162:163], v[134:135]
	v_pk_mul_f32 v[130:131], v[130:131], v[132:133]
	v_pk_fma_f32 v[158:159], v[158:159], v[162:163], v[194:195]
	v_pk_mul_f32 v[152:153], v[154:155], v[152:153]
	v_pk_mul_f32 v[128:129], v[136:137], v[128:129]
	v_pk_mul_f32 v[130:131], v[134:135], v[130:131]
	v_pk_mul_f32 v[152:153], v[158:159], v[152:153]
	v_cvt_pk_bf16_f32 v128, v128, v129
	v_cvt_pk_bf16_f32 v129, v130, v131
	v_or_b32_e32 v130, 3, v246
	v_cvt_pk_bf16_f32 v157, v152, v153
	v_or_b32_e32 v152, 2, v246
	v_mad_i64_i32 v[130:131], s[34:35], v130, s74, v[206:207]
	v_mad_i64_i32 v[152:153], s[34:35], v152, s74, v[206:207]
	v_lshl_add_u64 v[140:141], v[130:131], 0, v[204:205]
	v_lshl_add_u64 v[152:153], v[152:153], 0, v[204:205]
	v_mov_b32_e32 v251, v128
	v_mov_b32_e32 v253, v129
	v_mov_b32_e32 v193, 0
	v_mov_b32_e32 v194, 0
	v_mov_b32_e32 v195, 0
	v_mov_b32_e32 v136, 0
	v_mov_b32_e32 v137, 0
	v_mov_b32_e32 v138, 0
	v_mov_b32_e32 v139, 0
	v_mov_b32_e32 v128, 0
	v_mov_b32_e32 v129, 0
	v_mov_b32_e32 v130, 0
	v_mov_b32_e32 v131, 0
	v_mov_b32_e32 v132, 0
	v_mov_b32_e32 v133, 0
	v_mov_b32_e32 v134, 0
	v_mov_b32_e32 v135, 0
	v_mov_b32_e32 v254, v156
	v_mov_b32_e32 v255, v157
	s_and_saveexec_b64 s[34:35], s[22:23]
	s_cbranch_execz .LBB0_320
	ds_read_b128 v[132:135], v237 offset:2048
	ds_read_b128 v[136:139], v237 offset:2560
	ds_read_b128 v[128:131], v237 offset:3072
	ds_read_b128 v[192:195], v237 offset:3584
.LBB0_320:
	s_or_b64 exec, exec, s[34:35]
	s_waitcnt lgkmcnt(0)
	v_mov_b32_dpp v192, v72 row_shr:1 row_mask:0xf bank_mask:0xf
	v_mov_b32_dpp v193, v73 row_shr:1 row_mask:0xf bank_mask:0xf
	v_pk_fma_f32 v[142:143], v[88:89], v[184:185], v[188:189]
	v_mov_b32_dpp v136, v64 row_shr:1 row_mask:0xf bank_mask:0xf
	v_mov_b32_dpp v137, v65 row_shr:1 row_mask:0xf bank_mask:0xf
	v_pk_fma_f32 v[142:143], v[180:181], v[192:193], v[142:143]
	v_mov_b32_dpp v128, v84 row_shr:1 row_mask:0xf bank_mask:0xf
	v_pk_fma_f32 v[136:137], v[176:177], v[136:137], v[142:143]
	v_mov_b32_dpp v129, v85 row_shr:1 row_mask:0xf bank_mask:0xf
	v_mul_f32_e32 v142, 0xbfb8aa3b, v136
	v_mul_f32_e32 v143, 0xbfb8aa3b, v137
	v_exp_f32_e32 v142, v142
	v_exp_f32_e32 v143, v143
	v_pk_fma_f32 v[144:145], v[92:93], v[168:169], v[172:173]
	v_mov_b32_dpp v132, v76 row_shr:1 row_mask:0xf bank_mask:0xf
	v_add_f32_e32 v142, 1.0, v142
	v_add_f32_e32 v143, 1.0, v143
	v_rcp_f32_e32 v142, v142
	v_rcp_f32_e32 v143, v143
	v_mov_b32_dpp v133, v77 row_shr:1 row_mask:0xf bank_mask:0xf
	v_pk_fma_f32 v[144:145], v[164:165], v[128:129], v[144:145]
	v_mov_b32_dpp v194, v74 row_shr:1 row_mask:0xf bank_mask:0xf
	v_pk_fma_f32 v[132:133], v[160:161], v[132:133], v[144:145]
	v_pk_mul_f32 v[136:137], v[136:137], v[142:143]
	v_mov_b32_dpp v195, v75 row_shr:1 row_mask:0xf bank_mask:0xf
	v_pk_mul_f32 v[132:133], v[132:133], v[136:137]
	v_pk_fma_f32 v[136:137], v[90:91], v[186:187], v[190:191]
	v_mov_b32_dpp v138, v66 row_shr:1 row_mask:0xf bank_mask:0xf
	v_mov_b32_dpp v139, v67 row_shr:1 row_mask:0xf bank_mask:0xf
	v_pk_fma_f32 v[136:137], v[182:183], v[194:195], v[136:137]
	v_mov_b32_dpp v130, v86 row_shr:1 row_mask:0xf bank_mask:0xf
	v_pk_fma_f32 v[136:137], v[178:179], v[138:139], v[136:137]
	v_mov_b32_dpp v131, v87 row_shr:1 row_mask:0xf bank_mask:0xf
	v_mul_f32_e32 v138, 0xbfb8aa3b, v136
	v_exp_f32_e32 v139, v138
	v_mul_f32_e32 v138, 0xbfb8aa3b, v137
	v_exp_f32_e32 v142, v138
	v_cvt_pk_bf16_f32 v138, v132, v133
	v_add_f32_e32 v132, 1.0, v139
	v_rcp_f32_e32 v132, v132
	v_add_f32_e32 v133, 1.0, v142
	v_rcp_f32_e32 v133, v133
	v_pk_fma_f32 v[142:143], v[94:95], v[170:171], v[174:175]
	v_mov_b32_dpp v134, v78 row_shr:1 row_mask:0xf bank_mask:0xf
	v_mov_b32_dpp v135, v79 row_shr:1 row_mask:0xf bank_mask:0xf
	v_pk_mul_f32 v[132:133], v[136:137], v[132:133]
	v_pk_fma_f32 v[136:137], v[68:69], v[184:185], v[188:189]
	v_pk_fma_f32 v[142:143], v[166:167], v[130:131], v[142:143]
	v_pk_fma_f32 v[136:137], v[88:89], v[180:181], v[136:137]
	v_pk_fma_f32 v[134:135], v[162:163], v[134:135], v[142:143]
	v_pk_fma_f32 v[136:137], v[176:177], v[192:193], v[136:137]
	v_add_u32_e32 v146, 0x80, v246
	v_mul_f32_e32 v142, 0xbfb8aa3b, v136
	v_mul_f32_e32 v143, 0xbfb8aa3b, v137
	v_exp_f32_e32 v142, v142
	v_exp_f32_e32 v143, v143
	v_pk_mul_f32 v[132:133], v[134:135], v[132:133]
	v_mov_b64_e32 v[134:135], s[60:61]
	v_cvt_pk_bf16_f32 v139, v132, v133
	v_mad_i64_i32 v[132:133], s[34:35], v146, s74, v[134:135]
; #define LAS __attribute__((address_space(3)))
; __device__ __forceinline__ float sigmoidf_(float x) { return __builtin_amdgcn_rcpf(1.0f + __expf(-x)); }
;     __device__ __forceinline__ void operator()(AccRef acc, const Unit& u, int wr, int wc, int fr, int fq) const {
;     ...
;                 f32x4 h2v = (f32x4){0.f, 0.f, 0.f, 0.f}, h3v = h2v, h2g = h2v, h3g = h2v;
;                 const int pb = ai * 2 + wr - 1;
;                 if (pb >= 0 && fr == 0) { const LAS float* xp = xch + (pb * 2) * 256 + clb + 4 * n;
;                     h2v = *(const LAS f32x4*)(xp); h3v = *(const LAS f32x4*)(xp + 256); h2g = *(const LAS f32x4*)(xp + 128); h3g = *(const LAS f32x4*)(xp + 256 + 128); }
;                 float o[4][4];
; #pragma unroll
;                 for (int j = 0; j < 4; ++j) {
;                     const float v0 = acc[ai][0][0][n][j], v1 = acc[ai][0][1][n][j], v2 = acc[ai][0][2][n][j], v3 = acc[ai][0][3][n][j];
;                     const float g0 = acc[ai][1][0][n][j], g1 = acc[ai][1][1][n][j], g2 = acc[ai][1][2][n][j], g3 = acc[ai][1][3][n][j];
;                     const float pv3 = dpp_upd<0x111>(h3v[j], v3), pv2 = dpp_upd<0x111>(h2v[j], v2), pg3 = dpp_upd<0x111>(h3g[j], g3), pg2 = dpp_upd<0x111>(h2g[j], g2);
;                     const float hv0 = bvv[j] + w2v[j] * v0 + w1v[j] * pv3 + w0v[j] * pv2, hv1 = bvv[j] + w2v[j] * v1 + w1v[j] * v0 + w0v[j] * pv3;
;                     const float hv2 = bvv[j] + w2v[j] * v2 + w1v[j] * v1 + w0v[j] * v0, hv3 = bvv[j] + w2v[j] * v3 + w1v[j] * v2 + w0v[j] * v1;
;                     const float hg0 = bvg[j] + w2g[j] * g0 + w1g[j] * pg3 + w0g[j] * pg2, hg1 = bvg[j] + w2g[j] * g1 + w1g[j] * g0 + w0g[j] * pg3;
;                     const float hg2 = bvg[j] + w2g[j] * g2 + w1g[j] * g1 + w0g[j] * g0, hg3 = bvg[j] + w2g[j] * g3 + w1g[j] * g2 + w0g[j] * g1;
;                     o[0][j] = hg0 * sigmoidf_(hg0) * hv0; o[1][j] = hg1 * sigmoidf_(hg1) * hv1; o[2][j] = hg2 * sigmoidf_(hg2) * hv2; o[3][j] = hg3 * sigmoidf_(hg3) * hv3; }
; #pragma unroll
;                 for (int m = 0; m < 4; ++m) { u32x2 w; w.x = cvt_pk_bf16(o[m][0], o[m][1]); w.y = cvt_pk_bf16(o[m][2], o[m][3]);
;                     *(u32x2*)(Aout + (size_t)(row0 + ai * 128 + m) * FH + hc0 + 4 * n) = w; } } }
	v_lshl_add_u64 v[132:133], v[132:133], 0, v[204:205]
	v_mov_b32_e32 v144, v138
	v_mov_b32_e32 v145, v139
	v_add_f32_e32 v138, 1.0, v142
	v_add_f32_e32 v139, 1.0, v143
	v_rcp_f32_e32 v138, v138
	v_rcp_f32_e32 v139, v139
	v_pk_fma_f32 v[142:143], v[80:81], v[168:169], v[172:173]
	v_pk_fma_f32 v[72:73], v[72:73], v[184:185], v[188:189]
	v_pk_fma_f32 v[142:143], v[92:93], v[164:165], v[142:143]
	v_pk_mul_f32 v[136:137], v[136:137], v[138:139]
	v_pk_fma_f32 v[128:129], v[160:161], v[128:129], v[142:143]
	v_pk_fma_f32 v[84:85], v[84:85], v[168:169], v[172:173]
	v_pk_mul_f32 v[128:129], v[128:129], v[136:137]
	v_pk_fma_f32 v[136:137], v[70:71], v[186:187], v[190:191]
	s_nop 0
	v_pk_fma_f32 v[136:137], v[90:91], v[182:183], v[136:137]
	s_nop 0
	v_pk_fma_f32 v[136:137], v[178:179], v[194:195], v[136:137]
	s_nop 0
	v_mul_f32_e32 v138, 0xbfb8aa3b, v136
	v_exp_f32_e32 v139, v138
	v_mul_f32_e32 v138, 0xbfb8aa3b, v137
	v_exp_f32_e32 v142, v138
	v_cvt_pk_bf16_f32 v138, v128, v129
	v_add_f32_e32 v128, 1.0, v139
	v_rcp_f32_e32 v128, v128
	v_add_f32_e32 v129, 1.0, v142
	v_rcp_f32_e32 v129, v129
	v_pk_fma_f32 v[142:143], v[82:83], v[170:171], v[174:175]
	v_pk_mul_f32 v[128:129], v[136:137], v[128:129]
	v_pk_fma_f32 v[142:143], v[94:95], v[166:167], v[142:143]
	v_pk_fma_f32 v[136:137], v[76:77], v[168:169], v[172:173]
	v_pk_fma_f32 v[130:131], v[162:163], v[130:131], v[142:143]
	v_pk_fma_f32 v[136:137], v[80:81], v[164:165], v[136:137]
	v_pk_mul_f32 v[128:129], v[130:131], v[128:129]
	v_pk_fma_f32 v[130:131], v[64:65], v[184:185], v[188:189]
	v_pk_fma_f32 v[64:65], v[64:65], v[180:181], v[72:73]
	v_pk_fma_f32 v[130:131], v[68:69], v[180:181], v[130:131]
	v_pk_fma_f32 v[64:65], v[68:69], v[176:177], v[64:65]
	v_pk_fma_f32 v[88:89], v[88:89], v[176:177], v[130:131]
	v_pk_fma_f32 v[92:93], v[92:93], v[160:161], v[136:137]
	v_mul_f32_e32 v130, 0xbfb8aa3b, v88
	v_mul_f32_e32 v131, 0xbfb8aa3b, v89
	v_exp_f32_e32 v130, v130
	v_exp_f32_e32 v131, v131
	v_mul_f32_e32 v68, 0xbfb8aa3b, v64
	v_exp_f32_e32 v72, v68
	v_add_f32_e32 v130, 1.0, v130
	v_add_f32_e32 v131, 1.0, v131
	v_rcp_f32_e32 v130, v130
	v_rcp_f32_e32 v131, v131
	v_pk_fma_f32 v[68:69], v[74:75], v[186:187], v[190:191]
	v_mul_f32_e32 v73, 0xbfb8aa3b, v65
	v_exp_f32_e32 v73, v73
	v_pk_mul_f32 v[88:89], v[88:89], v[130:131]
	v_add_f32_e32 v72, 1.0, v72
	v_pk_mul_f32 v[88:89], v[92:93], v[88:89]
	v_pk_fma_f32 v[92:93], v[66:67], v[186:187], v[190:191]
	v_pk_fma_f32 v[66:67], v[66:67], v[182:183], v[68:69]
	v_pk_fma_f32 v[92:93], v[70:71], v[182:183], v[92:93]
	v_pk_fma_f32 v[66:67], v[70:71], v[178:179], v[66:67]
	v_pk_fma_f32 v[90:91], v[90:91], v[178:179], v[92:93]
	v_mul_f32_e32 v68, 0xbfb8aa3b, v66
	v_mul_f32_e32 v92, 0xbfb8aa3b, v90
	v_mul_f32_e32 v69, 0xbfb8aa3b, v67
	v_exp_f32_e32 v93, v92
	v_mul_f32_e32 v92, 0xbfb8aa3b, v91
	v_exp_f32_e32 v68, v68
	v_exp_f32_e32 v69, v69
	v_exp_f32_e32 v130, v92
	v_add_f32_e32 v73, 1.0, v73
	v_add_f32_e32 v68, 1.0, v68
	v_add_f32_e32 v69, 1.0, v69
	v_cvt_pk_bf16_f32 v92, v88, v89
	v_add_f32_e32 v88, 1.0, v93
	v_add_f32_e32 v89, 1.0, v130
	v_rcp_f32_e32 v72, v72
	v_rcp_f32_e32 v73, v73
	v_rcp_f32_e32 v68, v68
	v_rcp_f32_e32 v69, v69
	v_rcp_f32_e32 v88, v88
	v_rcp_f32_e32 v89, v89
	v_pk_fma_f32 v[74:75], v[86:87], v[170:171], v[174:175]
	v_pk_fma_f32 v[130:131], v[78:79], v[170:171], v[174:175]
	v_pk_fma_f32 v[76:77], v[76:77], v[164:165], v[84:85]
	v_pk_fma_f32 v[70:71], v[78:79], v[166:167], v[74:75]
	v_pk_fma_f32 v[130:131], v[82:83], v[166:167], v[130:131]
	v_pk_fma_f32 v[76:77], v[80:81], v[160:161], v[76:77]
	v_pk_mul_f32 v[64:65], v[64:65], v[72:73]
	v_pk_fma_f32 v[70:71], v[82:83], v[162:163], v[70:71]
	v_pk_mul_f32 v[66:67], v[66:67], v[68:69]
	v_pk_fma_f32 v[94:95], v[94:95], v[162:163], v[130:131]
	v_pk_mul_f32 v[88:89], v[90:91], v[88:89]
	v_pk_mul_f32 v[64:65], v[76:77], v[64:65]
	v_pk_mul_f32 v[66:67], v[70:71], v[66:67]
	v_pk_mul_f32 v[88:89], v[94:95], v[88:89]
	v_cvt_pk_bf16_f32 v64, v64, v65
	v_cvt_pk_bf16_f32 v65, v66, v67
	v_add_u32_e32 v66, 0x83, v246
	v_cvt_pk_bf16_f32 v139, v128, v129
	v_add_u32_e32 v128, 0x81, v246
	v_cvt_pk_bf16_f32 v93, v88, v89
	v_add_u32_e32 v88, 0x82, v246
	v_mad_i64_i32 v[66:67], s[34:35], v66, s74, v[134:135]
	v_mad_i64_i32 v[128:129], s[34:35], v128, s74, v[134:135]
	v_mad_i64_i32 v[88:89], s[34:35], v88, s74, v[134:135]
	v_lshl_add_u64 v[82:83], v[66:67], 0, v[204:205]
	v_lshl_add_u64 v[128:129], v[128:129], 0, v[204:205]
	v_lshl_add_u64 v[88:89], v[88:89], 0, v[204:205]
	v_mov_b32_e32 v148, v64
	v_mov_b32_e32 v149, v65
	v_mov_b32_e32 v64, 0
	v_mov_b32_e32 v70, 0
	v_mov_b32_e32 v71, 0
	v_mov_b32_e32 v72, 0
	v_mov_b32_e32 v73, 0
	v_mov_b32_e32 v78, 0
	v_mov_b32_e32 v79, 0
	v_mov_b32_e32 v80, 0
	v_mov_b32_e32 v81, 0
	v_mov_b32_e32 v66, 0
	v_mov_b32_e32 v67, 0
	v_mov_b32_e32 v68, 0
	v_mov_b32_e32 v69, 0
	v_mov_b32_e32 v74, 0
	v_mov_b32_e32 v75, 0
	v_mov_b32_e32 v76, 0
	v_mov_b32_e32 v77, 0
	v_mov_b32_e32 v154, v138
	v_mov_b32_e32 v155, v139
	v_mov_b32_e32 v198, v92
	v_mov_b32_e32 v199, v93
	s_and_saveexec_b64 s[34:35], s[18:19]
	s_cbranch_execz .LBB0_322
	ds_read_b128 v[74:77], v242
	ds_read_b128 v[66:69], v241
	ds_read_b128 v[78:81], v240
	ds_read_b128 v[70:73], v239
; #define LAS __attribute__((address_space(3)))
; __device__ __forceinline__ float sigmoidf_(float x) { return __builtin_amdgcn_rcpf(1.0f + __expf(-x)); }
;     __device__ __forceinline__ void operator()(AccRef acc, const Unit& u, int wr, int wc, int fr, int fq) const {
;     ...
;                 f32x4 h2v = (f32x4){0.f, 0.f, 0.f, 0.f}, h3v = h2v, h2g = h2v, h3g = h2v;
;                 const int pb = ai * 2 + wr - 1;
;                 if (pb >= 0 && fr == 0) { const LAS float* xp = xch + (pb * 2) * 256 + clb + 4 * n;
;                     h2v = *(const LAS f32x4*)(xp); h3v = *(const LAS f32x4*)(xp + 256); h2g = *(const LAS f32x4*)(xp + 128); h3g = *(const LAS f32x4*)(xp + 256 + 128); }
;                 float o[4][4];
; #pragma unroll
;                 for (int j = 0; j < 4; ++j) {
;                     const float v0 = acc[ai][0][0][n][j], v1 = acc[ai][0][1][n][j], v2 = acc[ai][0][2][n][j], v3 = acc[ai][0][3][n][j];
;                     const float g0 = acc[ai][1][0][n][j], g1 = acc[ai][1][1][n][j], g2 = acc[ai][1][2][n][j], g3 = acc[ai][1][3][n][j];
;                     const float pv3 = dpp_upd<0x111>(h3v[j], v3), pv2 = dpp_upd<0x111>(h2v[j], v2), pg3 = dpp_upd<0x111>(h3g[j], g3), pg2 = dpp_upd<0x111>(h2g[j], g2);
;                     const float hv0 = bvv[j] + w2v[j] * v0 + w1v[j] * pv3 + w0v[j] * pv2, hv1 = bvv[j] + w2v[j] * v1 + w1v[j] * v0 + w0v[j] * pv3;
;                     const float hv2 = bvv[j] + w2v[j] * v2 + w1v[j] * v1 + w0v[j] * v0, hv3 = bvv[j] + w2v[j] * v3 + w1v[j] * v2 + w0v[j] * v1;
;                     const float hg0 = bvg[j] + w2g[j] * g0 + w1g[j] * pg3 + w0g[j] * pg2, hg1 = bvg[j] + w2g[j] * g1 + w1g[j] * g0 + w0g[j] * pg3;
;                     const float hg2 = bvg[j] + w2g[j] * g2 + w1g[j] * g1 + w0g[j] * g0, hg3 = bvg[j] + w2g[j] * g3 + w1g[j] * g2 + w0g[j] * g1;
;                     o[0][j] = hg0 * sigmoidf_(hg0) * hv0; o[1][j] = hg1 * sigmoidf_(hg1) * hv1; o[2][j] = hg2 * sigmoidf_(hg2) * hv2; o[3][j] = hg3 * sigmoidf_(hg3) * hv3; }
; #pragma unroll
;                 for (int m = 0; m < 4; ++m) { u32x2 w; w.x = cvt_pk_bf16(o[m][0], o[m][1]); w.y = cvt_pk_bf16(o[m][2], o[m][3]);
;                     *(u32x2*)(Aout + (size_t)(row0 + ai * 128 + m) * FH + hc0 + 4 * n) = w; } } }
.LBB0_322:
	s_or_b64 exec, exec, s[34:35]
	s_waitcnt lgkmcnt(0)
	v_mov_b32_dpp v70, v44 row_shr:1 row_mask:0xf bank_mask:0xf
	v_mov_b32_dpp v71, v45 row_shr:1 row_mask:0xf bank_mask:0xf
	s_waitcnt vmcnt(0)
	v_pk_fma_f32 v[84:85], v[56:57], v[120:121], v[124:125]
	v_mov_b32_dpp v78, v32 row_shr:1 row_mask:0xf bank_mask:0xf
	v_mov_b32_dpp v79, v33 row_shr:1 row_mask:0xf bank_mask:0xf
	v_pk_fma_f32 v[84:85], v[116:117], v[70:71], v[84:85]
	v_mov_b32_dpp v66, v52 row_shr:1 row_mask:0xf bank_mask:0xf
	v_pk_fma_f32 v[78:79], v[112:113], v[78:79], v[84:85]
	v_mov_b32_dpp v67, v53 row_shr:1 row_mask:0xf bank_mask:0xf
	v_mul_f32_e32 v65, 0xbfb8aa3b, v78
	v_exp_f32_e32 v65, v65
	v_mul_f32_e32 v84, 0xbfb8aa3b, v79
	v_exp_f32_e32 v85, v84
	v_pk_fma_f32 v[86:87], v[60:61], v[104:105], v[108:109]
	v_add_f32_e32 v65, 1.0, v65
	v_rcp_f32_e32 v84, v65
	v_add_f32_e32 v65, 1.0, v85
	v_rcp_f32_e32 v85, v65
	v_mov_b32_dpp v74, v40 row_shr:1 row_mask:0xf bank_mask:0xf
	v_mov_b32_dpp v75, v41 row_shr:1 row_mask:0xf bank_mask:0xf
	v_pk_fma_f32 v[86:87], v[100:101], v[66:67], v[86:87]
	v_pk_mul_f32 v[78:79], v[78:79], v[84:85]
	v_pk_fma_f32 v[74:75], v[96:97], v[74:75], v[86:87]
	v_mov_b32_dpp v72, v46 row_shr:1 row_mask:0xf bank_mask:0xf
	v_mov_b32_dpp v73, v47 row_shr:1 row_mask:0xf bank_mask:0xf
	v_pk_mul_f32 v[74:75], v[74:75], v[78:79]
	v_pk_fma_f32 v[78:79], v[58:59], v[122:123], v[126:127]
	v_mov_b32_dpp v80, v34 row_shr:1 row_mask:0xf bank_mask:0xf
	v_mov_b32_dpp v81, v35 row_shr:1 row_mask:0xf bank_mask:0xf
	v_pk_fma_f32 v[78:79], v[118:119], v[72:73], v[78:79]
	v_mov_b32_dpp v68, v54 row_shr:1 row_mask:0xf bank_mask:0xf
	v_pk_fma_f32 v[78:79], v[114:115], v[80:81], v[78:79]
	v_mov_b32_dpp v69, v55 row_shr:1 row_mask:0xf bank_mask:0xf
	v_mul_f32_e32 v65, 0xbfb8aa3b, v78
	v_exp_f32_e32 v65, v65
	v_mul_f32_e32 v80, 0xbfb8aa3b, v79
	v_exp_f32_e32 v81, v80
	v_pk_fma_f32 v[84:85], v[62:63], v[106:107], v[110:111]
	v_add_f32_e32 v65, 1.0, v65
	v_rcp_f32_e32 v80, v65
	v_add_f32_e32 v65, 1.0, v81
	v_rcp_f32_e32 v81, v65
	v_mov_b32_dpp v76, v42 row_shr:1 row_mask:0xf bank_mask:0xf
	v_mov_b32_dpp v77, v43 row_shr:1 row_mask:0xf bank_mask:0xf
	v_pk_fma_f32 v[84:85], v[102:103], v[68:69], v[84:85]
	v_pk_mul_f32 v[78:79], v[78:79], v[80:81]
	v_pk_fma_f32 v[76:77], v[98:99], v[76:77], v[84:85]
	v_cvt_pk_bf16_f32 v74, v74, v75
	v_pk_mul_f32 v[76:77], v[76:77], v[78:79]
	v_pk_fma_f32 v[44:45], v[44:45], v[120:121], v[124:125]
	v_cvt_pk_bf16_f32 v75, v76, v77
	v_pk_fma_f32 v[76:77], v[36:37], v[120:121], v[124:125]
	v_mov_b32_e32 v90, v247
	v_mov_b32_e32 v91, v248
	v_mov_b32_e32 v92, v74
	v_mov_b32_e32 v93, v75
	global_store_dwordx4 v[202:203], v[90:93], off
	v_pk_fma_f32 v[76:77], v[56:57], v[116:117], v[76:77]
	v_pk_fma_f32 v[52:53], v[52:53], v[104:105], v[108:109]
	v_pk_fma_f32 v[70:71], v[112:113], v[70:71], v[76:77]
	s_nop 0
	v_mul_f32_e32 v65, 0xbfb8aa3b, v70
	v_exp_f32_e32 v65, v65
	v_mul_f32_e32 v76, 0xbfb8aa3b, v71
	v_exp_f32_e32 v76, v76
	v_add_f32_e32 v65, 1.0, v65
	v_rcp_f32_e32 v74, v65
	v_add_f32_e32 v65, 1.0, v76
	v_rcp_f32_e32 v75, v65
	v_pk_fma_f32 v[76:77], v[48:49], v[104:105], v[108:109]
	v_pk_mul_f32 v[70:71], v[70:71], v[74:75]
	v_pk_fma_f32 v[76:77], v[60:61], v[100:101], v[76:77]
	v_pk_fma_f32 v[74:75], v[50:51], v[106:107], v[110:111]
	v_pk_fma_f32 v[66:67], v[96:97], v[66:67], v[76:77]
	v_pk_fma_f32 v[74:75], v[62:63], v[102:103], v[74:75]
	v_pk_mul_f32 v[66:67], v[66:67], v[70:71]
	v_pk_fma_f32 v[70:71], v[38:39], v[122:123], v[126:127]
	v_pk_fma_f32 v[68:69], v[98:99], v[68:69], v[74:75]
	v_pk_fma_f32 v[70:71], v[58:59], v[118:119], v[70:71]
	v_cvt_pk_bf16_f32 v66, v66, v67
	v_pk_fma_f32 v[70:71], v[114:115], v[72:73], v[70:71]
	s_nop 0
	v_mul_f32_e32 v65, 0xbfb8aa3b, v70
	v_exp_f32_e32 v65, v65
	v_mul_f32_e32 v72, 0xbfb8aa3b, v71
	v_exp_f32_e32 v73, v72
	v_add_f32_e32 v65, 1.0, v65
; #define LAS __attribute__((address_space(3)))
; __device__ __forceinline__ float sigmoidf_(float x) { return __builtin_amdgcn_rcpf(1.0f + __expf(-x)); }
;     __device__ __forceinline__ void operator()(AccRef acc, const Unit& u, int wr, int wc, int fr, int fq) const {
;     ...
;                 f32x4 h2v = (f32x4){0.f, 0.f, 0.f, 0.f}, h3v = h2v, h2g = h2v, h3g = h2v;
;                 const int pb = ai * 2 + wr - 1;
;                 if (pb >= 0 && fr == 0) { const LAS float* xp = xch + (pb * 2) * 256 + clb + 4 * n;
;                     h2v = *(const LAS f32x4*)(xp); h3v = *(const LAS f32x4*)(xp + 256); h2g = *(const LAS f32x4*)(xp + 128); h3g = *(const LAS f32x4*)(xp + 256 + 128); }
;                 float o[4][4];
; #pragma unroll
;                 for (int j = 0; j < 4; ++j) {
;                     const float v0 = acc[ai][0][0][n][j], v1 = acc[ai][0][1][n][j], v2 = acc[ai][0][2][n][j], v3 = acc[ai][0][3][n][j];
;                     const float g0 = acc[ai][1][0][n][j], g1 = acc[ai][1][1][n][j], g2 = acc[ai][1][2][n][j], g3 = acc[ai][1][3][n][j];
;                     const float pv3 = dpp_upd<0x111>(h3v[j], v3), pv2 = dpp_upd<0x111>(h2v[j], v2), pg3 = dpp_upd<0x111>(h3g[j], g3), pg2 = dpp_upd<0x111>(h2g[j], g2);
;                     const float hv0 = bvv[j] + w2v[j] * v0 + w1v[j] * pv3 + w0v[j] * pv2, hv1 = bvv[j] + w2v[j] * v1 + w1v[j] * v0 + w0v[j] * pv3;
;                     const float hv2 = bvv[j] + w2v[j] * v2 + w1v[j] * v1 + w0v[j] * v0, hv3 = bvv[j] + w2v[j] * v3 + w1v[j] * v2 + w0v[j] * v1;
;                     const float hg0 = bvg[j] + w2g[j] * g0 + w1g[j] * pg3 + w0g[j] * pg2, hg1 = bvg[j] + w2g[j] * g1 + w1g[j] * g0 + w0g[j] * pg3;
;                     const float hg2 = bvg[j] + w2g[j] * g2 + w1g[j] * g1 + w0g[j] * g0, hg3 = bvg[j] + w2g[j] * g3 + w1g[j] * g2 + w0g[j] * g1;
;                     o[0][j] = hg0 * sigmoidf_(hg0) * hv0; o[1][j] = hg1 * sigmoidf_(hg1) * hv1; o[2][j] = hg2 * sigmoidf_(hg2) * hv2; o[3][j] = hg3 * sigmoidf_(hg3) * hv3; }
; #pragma unroll
;                 for (int m = 0; m < 4; ++m) { u32x2 w; w.x = cvt_pk_bf16(o[m][0], o[m][1]); w.y = cvt_pk_bf16(o[m][2], o[m][3]);
;                     *(u32x2*)(Aout + (size_t)(row0 + ai * 128 + m) * FH + hc0 + 4 * n) = w; } } }
	v_rcp_f32_e32 v72, v65
	v_add_f32_e32 v65, 1.0, v73
	v_rcp_f32_e32 v73, v65
	s_nop 0
	v_pk_mul_f32 v[70:71], v[70:71], v[72:73]
	s_nop 0
	v_pk_mul_f32 v[68:69], v[68:69], v[70:71]
	s_nop 0
	v_cvt_pk_bf16_f32 v67, v68, v69
	v_pk_fma_f32 v[68:69], v[32:33], v[120:121], v[124:125]
	v_mov_b32_e32 v134, v249
	v_mov_b32_e32 v135, v250
	v_mov_b32_e32 v136, v66
	v_mov_b32_e32 v137, v67
	global_store_dwordx4 v[196:197], v[134:137], off
	v_pk_fma_f32 v[68:69], v[36:37], v[116:117], v[68:69]
	v_pk_fma_f32 v[32:33], v[32:33], v[116:117], v[44:45]
	v_pk_fma_f32 v[56:57], v[56:57], v[112:113], v[68:69]
	v_pk_fma_f32 v[32:33], v[36:37], v[112:113], v[32:33]
	v_mul_f32_e32 v65, 0xbfb8aa3b, v56
	v_exp_f32_e32 v65, v65
	v_mul_f32_e32 v68, 0xbfb8aa3b, v57
	v_exp_f32_e32 v68, v68
	v_mul_f32_e32 v36, 0xbfb8aa3b, v32
	v_add_f32_e32 v65, 1.0, v65
	v_rcp_f32_e32 v66, v65
	v_add_f32_e32 v65, 1.0, v68
	v_rcp_f32_e32 v67, v65
	v_pk_fma_f32 v[68:69], v[40:41], v[104:105], v[108:109]
	v_exp_f32_e32 v44, v36
	v_pk_fma_f32 v[68:69], v[48:49], v[100:101], v[68:69]
	v_pk_mul_f32 v[56:57], v[56:57], v[66:67]
	v_pk_fma_f32 v[60:61], v[60:61], v[96:97], v[68:69]
	v_pk_fma_f32 v[36:37], v[46:47], v[122:123], v[126:127]
	v_pk_mul_f32 v[56:57], v[60:61], v[56:57]
	v_pk_fma_f32 v[60:61], v[34:35], v[122:123], v[126:127]
	v_pk_fma_f32 v[34:35], v[34:35], v[118:119], v[36:37]
	v_pk_fma_f32 v[60:61], v[38:39], v[118:119], v[60:61]
	v_pk_fma_f32 v[34:35], v[38:39], v[114:115], v[34:35]
	v_pk_fma_f32 v[58:59], v[58:59], v[114:115], v[60:61]
	v_mul_f32_e32 v45, 0xbfb8aa3b, v33
	v_mul_f32_e32 v60, 0xbfb8aa3b, v58
	v_mul_f32_e32 v36, 0xbfb8aa3b, v34
	v_mul_f32_e32 v37, 0xbfb8aa3b, v35
	v_exp_f32_e32 v60, v60
	v_mul_f32_e32 v61, 0xbfb8aa3b, v59
	v_exp_f32_e32 v45, v45
	v_exp_f32_e32 v36, v36
	v_exp_f32_e32 v37, v37
	v_exp_f32_e32 v61, v61
	v_cvt_pk_bf16_f32 v56, v56, v57
	v_add_f32_e32 v57, 1.0, v60
	v_add_f32_e32 v44, 1.0, v44
	v_add_f32_e32 v45, 1.0, v45
	v_add_f32_e32 v36, 1.0, v36
	v_add_f32_e32 v37, 1.0, v37
	v_rcp_f32_e32 v60, v57
	v_add_f32_e32 v57, 1.0, v61
	v_rcp_f32_e32 v44, v44
	v_rcp_f32_e32 v45, v45
	v_rcp_f32_e32 v36, v36
	v_rcp_f32_e32 v37, v37
	v_rcp_f32_e32 v61, v57
	v_pk_fma_f32 v[46:47], v[54:55], v[106:107], v[110:111]
	v_pk_fma_f32 v[66:67], v[42:43], v[106:107], v[110:111]
	v_pk_fma_f32 v[40:41], v[40:41], v[100:101], v[52:53]
	v_pk_fma_f32 v[38:39], v[42:43], v[102:103], v[46:47]
	v_pk_fma_f32 v[66:67], v[50:51], v[102:103], v[66:67]
	v_pk_fma_f32 v[40:41], v[48:49], v[96:97], v[40:41]
	v_pk_mul_f32 v[32:33], v[32:33], v[44:45]
	v_pk_fma_f32 v[38:39], v[50:51], v[98:99], v[38:39]
	v_pk_mul_f32 v[34:35], v[34:35], v[36:37]
	v_pk_fma_f32 v[62:63], v[62:63], v[98:99], v[66:67]
	v_pk_mul_f32 v[58:59], v[58:59], v[60:61]
	v_pk_mul_f32 v[32:33], v[40:41], v[32:33]
	v_pk_mul_f32 v[34:35], v[38:39], v[34:35]
	v_pk_mul_f32 v[58:59], v[62:63], v[58:59]
	v_cvt_pk_bf16_f32 v32, v32, v33
	v_cvt_pk_bf16_f32 v33, v34, v35
	v_cvt_pk_bf16_f32 v57, v58, v59
	v_mov_b32_e32 v158, v251
	v_mov_b32_e32 v159, v253
	v_mov_b32_e32 v160, v32
	v_mov_b32_e32 v161, v33
	global_store_dwordx4 v[140:141], v[158:161], off
	v_mov_b32_e32 v65, 0
	v_mov_b32_e32 v66, 0
	v_mov_b32_e32 v67, 0
	v_mov_b32_e32 v40, 0
	v_mov_b32_e32 v41, 0
	v_mov_b32_e32 v42, 0
	v_mov_b32_e32 v43, 0
	v_mov_b32_e32 v32, 0
	v_mov_b32_e32 v33, 0
	v_mov_b32_e32 v34, 0
	v_mov_b32_e32 v35, 0
	v_mov_b32_e32 v36, 0
	v_mov_b32_e32 v37, 0
	v_mov_b32_e32 v38, 0
	v_mov_b32_e32 v39, 0
	v_mov_b32_e32 v162, v254
	v_mov_b32_e32 v163, v255
	v_mov_b32_e32 v164, v56
	v_mov_b32_e32 v165, v57
	global_store_dwordx4 v[152:153], v[162:165], off
	s_and_saveexec_b64 s[34:35], s[22:23]
	s_cbranch_execz .LBB0_305
	ds_read_b128 v[36:39], v237 offset:2064
	ds_read_b128 v[40:43], v237 offset:2576
	ds_read_b128 v[32:35], v237 offset:3088
	ds_read_b128 v[64:67], v237 offset:3600
	s_branch .LBB0_305

; #define LAS __attribute__((address_space(3)))
; __device__ __forceinline__ float sigmoidf_(float x) { return __builtin_amdgcn_rcpf(1.0f + __expf(-x)); }
;     __device__ __forceinline__ void operator()(AccRef acc, const Unit& u, int wr, int wc, int fr, int fq) const {
;     ...
;                 f32x4 h2v = (f32x4){0.f, 0.f, 0.f, 0.f}, h3v = h2v, h2g = h2v, h3g = h2v;
;                 const int pb = ai * 2 + wr - 1;
;                 if (pb >= 0 && fr == 0) { const LAS float* xp = xch + (pb * 2) * 256 + clb + 4 * n;
;                     h2v = *(const LAS f32x4*)(xp); h3v = *(const LAS f32x4*)(xp + 256); h2g = *(const LAS f32x4*)(xp + 128); h3g = *(const LAS f32x4*)(xp + 256 + 128); }
;                 float o[4][4];
; #pragma unroll
;                 for (int j = 0; j < 4; ++j) {
;                     const float v0 = acc[ai][0][0][n][j], v1 = acc[ai][0][1][n][j], v2 = acc[ai][0][2][n][j], v3 = acc[ai][0][3][n][j];
;                     const float g0 = acc[ai][1][0][n][j], g1 = acc[ai][1][1][n][j], g2 = acc[ai][1][2][n][j], g3 = acc[ai][1][3][n][j];
;                     const float pv3 = dpp_upd<0x111>(h3v[j], v3), pv2 = dpp_upd<0x111>(h2v[j], v2), pg3 = dpp_upd<0x111>(h3g[j], g3), pg2 = dpp_upd<0x111>(h2g[j], g2);
;                     const float hv0 = bvv[j] + w2v[j] * v0 + w1v[j] * pv3 + w0v[j] * pv2, hv1 = bvv[j] + w2v[j] * v1 + w1v[j] * v0 + w0v[j] * pv3;
;                     const float hv2 = bvv[j] + w2v[j] * v2 + w1v[j] * v1 + w0v[j] * v0, hv3 = bvv[j] + w2v[j] * v3 + w1v[j] * v2 + w0v[j] * v1;
;                     const float hg0 = bvg[j] + w2g[j] * g0 + w1g[j] * pg3 + w0g[j] * pg2, hg1 = bvg[j] + w2g[j] * g1 + w1g[j] * g0 + w0g[j] * pg3;
;                     const float hg2 = bvg[j] + w2g[j] * g2 + w1g[j] * g1 + w0g[j] * g0, hg3 = bvg[j] + w2g[j] * g3 + w1g[j] * g2 + w0g[j] * g1;
;                     o[0][j] = hg0 * sigmoidf_(hg0) * hv0; o[1][j] = hg1 * sigmoidf_(hg1) * hv1; o[2][j] = hg2 * sigmoidf_(hg2) * hv2; o[3][j] = hg3 * sigmoidf_(hg3) * hv3; }
; #pragma unroll
;                 for (int m = 0; m < 4; ++m) { u32x2 w; w.x = cvt_pk_bf16(o[m][0], o[m][1]); w.y = cvt_pk_bf16(o[m][2], o[m][3]);
;                     *(u32x2*)(Aout + (size_t)(row0 + ai * 128 + m) * FH + hc0 + 4 * n) = w; } } }
.LBB0_754:
	s_or_b64 exec, exec, s[40:41]
	s_waitcnt lgkmcnt(0)
	v_mov_b32_dpp v64, v8 row_shr:1 row_mask:0xf bank_mask:0xf
	v_mov_b32_dpp v65, v9 row_shr:1 row_mask:0xf bank_mask:0xf
	v_pk_fma_f32 v[44:45], v[24:25], v[120:121], v[124:125]
	v_mov_b32_dpp v40, v0 row_shr:1 row_mask:0xf bank_mask:0xf
	v_mov_b32_dpp v41, v1 row_shr:1 row_mask:0xf bank_mask:0xf
	v_pk_fma_f32 v[44:45], v[116:117], v[64:65], v[44:45]
	v_mov_b32_dpp v32, v20 row_shr:1 row_mask:0xf bank_mask:0xf
	v_pk_fma_f32 v[40:41], v[112:113], v[40:41], v[44:45]
	v_mov_b32_dpp v33, v21 row_shr:1 row_mask:0xf bank_mask:0xf
	v_mul_f32_e32 v44, 0xbfb8aa3b, v40
	v_mul_f32_e32 v45, 0xbfb8aa3b, v41
	v_exp_f32_e32 v44, v44
	v_exp_f32_e32 v45, v45
	v_pk_fma_f32 v[46:47], v[28:29], v[104:105], v[108:109]
	v_mov_b32_dpp v36, v12 row_shr:1 row_mask:0xf bank_mask:0xf
	v_add_f32_e32 v44, 1.0, v44
	v_add_f32_e32 v45, 1.0, v45
	v_rcp_f32_e32 v44, v44
	v_rcp_f32_e32 v45, v45
	v_mov_b32_dpp v37, v13 row_shr:1 row_mask:0xf bank_mask:0xf
	v_pk_fma_f32 v[46:47], v[100:101], v[32:33], v[46:47]
	v_mov_b32_dpp v66, v10 row_shr:1 row_mask:0xf bank_mask:0xf
	v_pk_fma_f32 v[36:37], v[96:97], v[36:37], v[46:47]
	v_pk_mul_f32 v[40:41], v[40:41], v[44:45]
	v_mov_b32_dpp v67, v11 row_shr:1 row_mask:0xf bank_mask:0xf
	v_pk_mul_f32 v[36:37], v[36:37], v[40:41]
	v_pk_fma_f32 v[40:41], v[26:27], v[122:123], v[126:127]
	v_mov_b32_dpp v42, v2 row_shr:1 row_mask:0xf bank_mask:0xf
	v_mov_b32_dpp v43, v3 row_shr:1 row_mask:0xf bank_mask:0xf
	v_pk_fma_f32 v[40:41], v[118:119], v[66:67], v[40:41]
	v_cvt_pk_bf16_f32 v36, v36, v37
	v_pk_fma_f32 v[40:41], v[114:115], v[42:43], v[40:41]
	v_mov_b32_dpp v34, v22 row_shr:1 row_mask:0xf bank_mask:0xf
	v_mul_f32_e32 v42, 0xbfb8aa3b, v40
	v_exp_f32_e32 v42, v42
	v_mul_f32_e32 v43, 0xbfb8aa3b, v41
	v_exp_f32_e32 v43, v43
	v_mov_b32_dpp v35, v23 row_shr:1 row_mask:0xf bank_mask:0xf
	v_add_f32_e32 v37, 1.0, v42
	v_rcp_f32_e32 v42, v37
	v_add_f32_e32 v37, 1.0, v43
	v_rcp_f32_e32 v43, v37
	v_pk_fma_f32 v[44:45], v[30:31], v[106:107], v[110:111]
	v_mov_b32_dpp v38, v14 row_shr:1 row_mask:0xf bank_mask:0xf
	v_mov_b32_dpp v39, v15 row_shr:1 row_mask:0xf bank_mask:0xf
	v_pk_fma_f32 v[44:45], v[102:103], v[34:35], v[44:45]
	v_pk_mul_f32 v[40:41], v[40:41], v[42:43]
	v_pk_fma_f32 v[38:39], v[98:99], v[38:39], v[44:45]
	v_pk_fma_f32 v[8:9], v[8:9], v[120:121], v[124:125]
	v_pk_mul_f32 v[38:39], v[38:39], v[40:41]
	v_pk_fma_f32 v[20:21], v[20:21], v[104:105], v[108:109]
	v_cvt_pk_bf16_f32 v37, v38, v39
	v_pk_fma_f32 v[38:39], v[4:5], v[120:121], v[124:125]
	v_mov_b32_e32 v146, v36
	v_mov_b32_e32 v147, v37
	global_store_dwordx4 v[132:133], v[144:147], off
	v_pk_fma_f32 v[38:39], v[24:25], v[116:117], v[38:39]
	s_and_b64 vcc, exec, s[14:15]
	v_pk_fma_f32 v[38:39], v[112:113], v[64:65], v[38:39]
	s_mov_b32 s41, s30
	v_mul_f32_e32 v40, 0xbfb8aa3b, v38
	v_mul_f32_e32 v41, 0xbfb8aa3b, v39
	v_exp_f32_e32 v40, v40
	v_exp_f32_e32 v41, v41
	s_mov_b32 s40, s34
	s_mov_b64 s[44:45], s[38:39]
	v_add_f32_e32 v36, 1.0, v40
	v_add_f32_e32 v37, 1.0, v41
	v_rcp_f32_e32 v36, v36
	v_rcp_f32_e32 v37, v37
	v_pk_fma_f32 v[40:41], v[16:17], v[104:105], v[108:109]
	s_mov_b64 s[42:43], s[36:37]
	v_pk_fma_f32 v[40:41], v[28:29], v[100:101], v[40:41]
	v_pk_mul_f32 v[36:37], v[38:39], v[36:37]
	v_pk_fma_f32 v[32:33], v[96:97], v[32:33], v[40:41]
	v_pk_fma_f32 v[40:41], v[18:19], v[106:107], v[110:111]
	v_pk_mul_f32 v[32:33], v[32:33], v[36:37]
	v_pk_fma_f32 v[36:37], v[6:7], v[122:123], v[126:127]
	v_cvt_pk_bf16_f32 v32, v32, v33
	v_pk_fma_f32 v[36:37], v[26:27], v[118:119], v[36:37]
	v_pk_fma_f32 v[40:41], v[30:31], v[102:103], v[40:41]
	v_pk_fma_f32 v[36:37], v[114:115], v[66:67], v[36:37]
	v_pk_fma_f32 v[34:35], v[98:99], v[34:35], v[40:41]
	v_mul_f32_e32 v38, 0xbfb8aa3b, v36
	v_exp_f32_e32 v38, v38
	v_mul_f32_e32 v39, 0xbfb8aa3b, v37
	v_exp_f32_e32 v39, v39
	v_add_f32_e32 v33, 1.0, v38
	v_rcp_f32_e32 v38, v33
	v_add_f32_e32 v33, 1.0, v39
	v_rcp_f32_e32 v39, v33
	s_nop 0
	v_pk_mul_f32 v[36:37], v[36:37], v[38:39]
	s_nop 0
	v_pk_mul_f32 v[34:35], v[34:35], v[36:37]
	s_nop 0
	v_cvt_pk_bf16_f32 v33, v34, v35
	v_pk_fma_f32 v[34:35], v[0:1], v[120:121], v[124:125]
	v_mov_b32_e32 v156, v32
	v_mov_b32_e32 v157, v33
	global_store_dwordx4 v[128:129], v[154:157], off
	v_pk_fma_f32 v[34:35], v[4:5], v[116:117], v[34:35]
	v_pk_fma_f32 v[0:1], v[0:1], v[116:117], v[8:9]
	v_pk_fma_f32 v[24:25], v[24:25], v[112:113], v[34:35]
	v_pk_fma_f32 v[0:1], v[4:5], v[112:113], v[0:1]
	v_mul_f32_e32 v34, 0xbfb8aa3b, v24
	v_mul_f32_e32 v35, 0xbfb8aa3b, v25
	v_exp_f32_e32 v34, v34
	v_exp_f32_e32 v35, v35
	v_mul_f32_e32 v4, 0xbfb8aa3b, v0
	v_exp_f32_e32 v8, v4
	v_add_f32_e32 v32, 1.0, v34
	v_add_f32_e32 v33, 1.0, v35
	v_rcp_f32_e32 v32, v32
	v_rcp_f32_e32 v33, v33
	v_pk_fma_f32 v[34:35], v[12:13], v[104:105], v[108:109]
	v_pk_fma_f32 v[4:5], v[10:11], v[122:123], v[126:127]
	v_pk_fma_f32 v[34:35], v[16:17], v[100:101], v[34:35]
	v_pk_mul_f32 v[24:25], v[24:25], v[32:33]
	v_pk_fma_f32 v[28:29], v[28:29], v[96:97], v[34:35]
	v_mul_f32_e32 v9, 0xbfb8aa3b, v1
	v_pk_mul_f32 v[24:25], v[28:29], v[24:25]
	v_pk_fma_f32 v[28:29], v[2:3], v[122:123], v[126:127]
	v_pk_fma_f32 v[2:3], v[2:3], v[118:119], v[4:5]
	v_pk_fma_f32 v[28:29], v[6:7], v[118:119], v[28:29]
	v_pk_fma_f32 v[2:3], v[6:7], v[114:115], v[2:3]
	v_pk_fma_f32 v[26:27], v[26:27], v[114:115], v[28:29]
	v_mul_f32_e32 v4, 0xbfb8aa3b, v2
	v_mul_f32_e32 v28, 0xbfb8aa3b, v26
	v_exp_f32_e32 v28, v28
	v_mul_f32_e32 v29, 0xbfb8aa3b, v27
	v_mul_f32_e32 v5, 0xbfb8aa3b, v3
	v_exp_f32_e32 v29, v29
	v_exp_f32_e32 v9, v9
	v_exp_f32_e32 v4, v4
	v_exp_f32_e32 v5, v5
	v_cvt_pk_bf16_f32 v24, v24, v25
	v_add_f32_e32 v25, 1.0, v28
	v_rcp_f32_e32 v28, v25
	v_add_f32_e32 v25, 1.0, v29
	v_add_f32_e32 v8, 1.0, v8
	v_add_f32_e32 v9, 1.0, v9
	v_add_f32_e32 v4, 1.0, v4
	v_add_f32_e32 v5, 1.0, v5
	v_rcp_f32_e32 v29, v25
	v_rcp_f32_e32 v8, v8
	v_rcp_f32_e32 v9, v9
	v_rcp_f32_e32 v4, v4
	v_rcp_f32_e32 v5, v5
	v_pk_fma_f32 v[32:33], v[14:15], v[106:107], v[110:111]
	v_pk_fma_f32 v[10:11], v[22:23], v[106:107], v[110:111]
	v_pk_fma_f32 v[32:33], v[18:19], v[102:103], v[32:33]
	v_pk_fma_f32 v[12:13], v[12:13], v[100:101], v[20:21]
	v_pk_fma_f32 v[6:7], v[14:15], v[102:103], v[10:11]
	v_pk_fma_f32 v[30:31], v[30:31], v[98:99], v[32:33]
	v_pk_mul_f32 v[26:27], v[26:27], v[28:29]
	v_pk_fma_f32 v[12:13], v[16:17], v[96:97], v[12:13]
	v_pk_mul_f32 v[0:1], v[0:1], v[8:9]
	v_pk_fma_f32 v[6:7], v[18:19], v[98:99], v[6:7]
	v_pk_mul_f32 v[2:3], v[2:3], v[4:5]
	v_pk_mul_f32 v[26:27], v[30:31], v[26:27]
	v_pk_mul_f32 v[0:1], v[12:13], v[0:1]
	v_pk_mul_f32 v[2:3], v[6:7], v[2:3]
	v_cvt_pk_bf16_f32 v25, v26, v27
	v_cvt_pk_bf16_f32 v0, v0, v1
	v_cvt_pk_bf16_f32 v1, v2, v3
	v_mov_b32_e32 v200, v24
	v_mov_b32_e32 v201, v25
	global_store_dwordx4 v[88:89], v[198:201], off
	v_mov_b32_e32 v150, v0
	v_mov_b32_e32 v151, v1
	global_store_dwordx4 v[82:83], v[148:151], off
	s_cbranch_vccnz .LBB0_773

; #define LAS __attribute__((address_space(3)))
; __device__ __forceinline__ float sigmoidf_(float x) { return __builtin_amdgcn_rcpf(1.0f + __expf(-x)); }
;     __device__ __forceinline__ void operator()(AccRef acc, const Unit& u, int wr, int wc, int fr, int fq) const {
;     ...
;                 f32x4 h2v = (f32x4){0.f, 0.f, 0.f, 0.f}, h3v = h2v, h2g = h2v, h3g = h2v;
;                 const int pb = ai * 2 + wr - 1;
;                 if (pb >= 0 && fr == 0) { const LAS float* xp = xch + (pb * 2) * 256 + clb + 4 * n;
;                     h2v = *(const LAS f32x4*)(xp); h3v = *(const LAS f32x4*)(xp + 256); h2g = *(const LAS f32x4*)(xp + 128); h3g = *(const LAS f32x4*)(xp + 256 + 128); }
;                 float o[4][4];
; #pragma unroll
;                 for (int j = 0; j < 4; ++j) {
;                     const float v0 = acc[ai][0][0][n][j], v1 = acc[ai][0][1][n][j], v2 = acc[ai][0][2][n][j], v3 = acc[ai][0][3][n][j];
;                     const float g0 = acc[ai][1][0][n][j], g1 = acc[ai][1][1][n][j], g2 = acc[ai][1][2][n][j], g3 = acc[ai][1][3][n][j];
;                     const float pv3 = dpp_upd<0x111>(h3v[j], v3), pv2 = dpp_upd<0x111>(h2v[j], v2), pg3 = dpp_upd<0x111>(h3g[j], g3), pg2 = dpp_upd<0x111>(h2g[j], g2);
;                     const float hv0 = bvv[j] + w2v[j] * v0 + w1v[j] * pv3 + w0v[j] * pv2, hv1 = bvv[j] + w2v[j] * v1 + w1v[j] * v0 + w0v[j] * pv3;
;                     const float hv2 = bvv[j] + w2v[j] * v2 + w1v[j] * v1 + w0v[j] * v0, hv3 = bvv[j] + w2v[j] * v3 + w1v[j] * v2 + w0v[j] * v1;
;                     const float hg0 = bvg[j] + w2g[j] * g0 + w1g[j] * pg3 + w0g[j] * pg2, hg1 = bvg[j] + w2g[j] * g1 + w1g[j] * g0 + w0g[j] * pg3;
;                     const float hg2 = bvg[j] + w2g[j] * g2 + w1g[j] * g1 + w0g[j] * g0, hg3 = bvg[j] + w2g[j] * g3 + w1g[j] * g2 + w0g[j] * g1;
;                     o[0][j] = hg0 * sigmoidf_(hg0) * hv0; o[1][j] = hg1 * sigmoidf_(hg1) * hv1; o[2][j] = hg2 * sigmoidf_(hg2) * hv2; o[3][j] = hg3 * sigmoidf_(hg3) * hv3; }
; #pragma unroll
;                 for (int m = 0; m < 4; ++m) { u32x2 w; w.x = cvt_pk_bf16(o[m][0], o[m][1]); w.y = cvt_pk_bf16(o[m][2], o[m][3]);
;                     *(u32x2*)(Aout + (size_t)(row0 + ai * 128 + m) * FH + hc0 + 4 * n) = w; } } }
.LBB0_765:
	s_or_b64 exec, exec, s[46:47]
	v_pk_fma_f32 v[248:249], v[152:153], v[184:185], v[188:189]
	v_mov_b32_dpp v206, v128 row_shr:1 row_mask:0xf bank_mask:0xf
	v_mov_b32_dpp v207, v129 row_shr:1 row_mask:0xf bank_mask:0xf
	v_pk_fma_f32 v[248:249], v[180:181], v[198:199], v[248:249]
	v_mov_b32_dpp v194, v148 row_shr:1 row_mask:0xf bank_mask:0xf
	v_pk_fma_f32 v[206:207], v[176:177], v[206:207], v[248:249]
	v_mov_b32_dpp v195, v149 row_shr:1 row_mask:0xf bank_mask:0xf
	v_mul_f32_e32 v193, 0xbfb8aa3b, v206
	v_exp_f32_e32 v193, v193
	v_mul_f32_e32 v247, 0xbfb8aa3b, v207
	v_exp_f32_e32 v247, v247
	v_pk_fma_f32 v[250:251], v[156:157], v[168:169], v[172:173]
	v_add_f32_e32 v193, 1.0, v193
	v_rcp_f32_e32 v248, v193
	v_add_f32_e32 v193, 1.0, v247
	v_rcp_f32_e32 v249, v193
	v_mov_b32_dpp v202, v136 row_shr:1 row_mask:0xf bank_mask:0xf
	v_mov_b32_dpp v203, v137 row_shr:1 row_mask:0xf bank_mask:0xf
	v_pk_fma_f32 v[250:251], v[164:165], v[194:195], v[250:251]
	v_pk_mul_f32 v[206:207], v[206:207], v[248:249]
	v_pk_fma_f32 v[202:203], v[160:161], v[202:203], v[250:251]
	v_mov_b32_dpp v200, v142 row_shr:1 row_mask:0xf bank_mask:0xf
	v_mov_b32_dpp v201, v143 row_shr:1 row_mask:0xf bank_mask:0xf
	v_pk_mul_f32 v[202:203], v[202:203], v[206:207]
	v_pk_fma_f32 v[206:207], v[154:155], v[186:187], v[190:191]
	v_mov_b32_dpp v208, v130 row_shr:1 row_mask:0xf bank_mask:0xf
	v_mov_b32_dpp v209, v131 row_shr:1 row_mask:0xf bank_mask:0xf
	v_pk_fma_f32 v[206:207], v[182:183], v[200:201], v[206:207]
	v_mov_b32_dpp v196, v150 row_shr:1 row_mask:0xf bank_mask:0xf
	v_pk_fma_f32 v[206:207], v[178:179], v[208:209], v[206:207]
	v_mov_b32_dpp v197, v151 row_shr:1 row_mask:0xf bank_mask:0xf
	v_mul_f32_e32 v193, 0xbfb8aa3b, v206
	v_exp_f32_e32 v193, v193
	v_mul_f32_e32 v208, 0xbfb8aa3b, v207
	v_exp_f32_e32 v209, v208
	v_cvt_pk_bf16_f32 v208, v202, v203
	v_add_f32_e32 v193, 1.0, v193
	v_rcp_f32_e32 v202, v193
	v_add_f32_e32 v193, 1.0, v209
	v_rcp_f32_e32 v203, v193
	v_pk_fma_f32 v[248:249], v[158:159], v[170:171], v[174:175]
	v_mov_b32_dpp v204, v138 row_shr:1 row_mask:0xf bank_mask:0xf
	v_mov_b32_dpp v205, v139 row_shr:1 row_mask:0xf bank_mask:0xf
	v_pk_fma_f32 v[248:249], v[166:167], v[196:197], v[248:249]
	v_pk_mul_f32 v[202:203], v[206:207], v[202:203]
	v_pk_fma_f32 v[204:205], v[162:163], v[204:205], v[248:249]
	v_lshl_add_u32 v246, s40, 8, v236
	v_pk_mul_f32 v[202:203], v[204:205], v[202:203]
	v_lshlrev_b64 v[204:205], 1, v[232:233]
	v_pk_fma_f32 v[232:233], v[132:133], v[184:185], v[188:189]
	v_mov_b64_e32 v[206:207], s[60:61]
	v_pk_fma_f32 v[232:233], v[152:153], v[180:181], v[232:233]
	v_cvt_pk_bf16_f32 v209, v202, v203
	v_pk_fma_f32 v[198:199], v[176:177], v[198:199], v[232:233]
	v_mad_i64_i32 v[202:203], s[40:41], v246, s76, v[206:207]
	v_mul_f32_e32 v193, 0xbfb8aa3b, v198
	v_exp_f32_e32 v193, v193
	v_mul_f32_e32 v232, 0xbfb8aa3b, v199
	v_exp_f32_e32 v232, v232
	v_lshl_add_u64 v[202:203], v[202:203], 0, v[204:205]
	v_add_f32_e32 v193, 1.0, v193
	v_mov_b32_e32 v247, v208
	v_mov_b32_e32 v248, v209
	v_rcp_f32_e32 v208, v193
	v_add_f32_e32 v193, 1.0, v232
	v_rcp_f32_e32 v209, v193
	v_pk_fma_f32 v[232:233], v[144:145], v[168:169], v[172:173]
	v_pk_fma_f32 v[140:141], v[140:141], v[184:185], v[188:189]
	v_pk_fma_f32 v[232:233], v[156:157], v[164:165], v[232:233]
	v_pk_mul_f32 v[198:199], v[198:199], v[208:209]
	v_pk_fma_f32 v[194:195], v[160:161], v[194:195], v[232:233]
	v_pk_fma_f32 v[208:209], v[146:147], v[170:171], v[174:175]
	v_pk_mul_f32 v[194:195], v[194:195], v[198:199]
	v_pk_fma_f32 v[198:199], v[134:135], v[186:187], v[190:191]
	v_pk_fma_f32 v[208:209], v[158:159], v[166:167], v[208:209]
	v_pk_fma_f32 v[198:199], v[154:155], v[182:183], v[198:199]
	v_pk_fma_f32 v[196:197], v[162:163], v[196:197], v[208:209]
	v_pk_fma_f32 v[198:199], v[178:179], v[200:201], v[198:199]
	v_cvt_pk_bf16_f32 v194, v194, v195
	v_mul_f32_e32 v193, 0xbfb8aa3b, v198
	v_exp_f32_e32 v193, v193
	v_mul_f32_e32 v200, 0xbfb8aa3b, v199
	v_exp_f32_e32 v201, v200
	v_pk_fma_f32 v[148:149], v[148:149], v[168:169], v[172:173]
	v_add_f32_e32 v193, 1.0, v193
	v_rcp_f32_e32 v200, v193
	v_add_f32_e32 v193, 1.0, v201
	v_rcp_f32_e32 v201, v193
	v_or_b32_e32 v193, 1, v246
	v_pk_mul_f32 v[198:199], v[198:199], v[200:201]
	s_nop 0
	v_pk_mul_f32 v[196:197], v[196:197], v[198:199]
	v_pk_fma_f32 v[198:199], v[128:129], v[184:185], v[188:189]
	v_cvt_pk_bf16_f32 v195, v196, v197
	v_pk_fma_f32 v[198:199], v[132:133], v[180:181], v[198:199]
	v_mad_i64_i32 v[196:197], s[40:41], v193, s76, v[206:207]
	v_pk_fma_f32 v[152:153], v[152:153], v[176:177], v[198:199]
	v_lshl_add_u64 v[196:197], v[196:197], 0, v[204:205]
	v_mul_f32_e32 v193, 0xbfb8aa3b, v152
	v_exp_f32_e32 v193, v193
	v_mul_f32_e32 v198, 0xbfb8aa3b, v153
	v_exp_f32_e32 v198, v198
	v_mov_b32_e32 v249, v194
	v_mov_b32_e32 v250, v195
	v_add_f32_e32 v193, 1.0, v193
	v_rcp_f32_e32 v194, v193
	v_add_f32_e32 v193, 1.0, v198
	v_rcp_f32_e32 v195, v193
	v_pk_fma_f32 v[198:199], v[136:137], v[168:169], v[172:173]
	v_pk_fma_f32 v[128:129], v[128:129], v[180:181], v[140:141]
	v_pk_fma_f32 v[198:199], v[144:145], v[164:165], v[198:199]
	v_pk_fma_f32 v[128:129], v[132:133], v[176:177], v[128:129]
	v_pk_fma_f32 v[156:157], v[156:157], v[160:161], v[198:199]
	v_pk_mul_f32 v[152:153], v[152:153], v[194:195]
	v_mul_f32_e32 v132, 0xbfb8aa3b, v128
	v_pk_mul_f32 v[152:153], v[156:157], v[152:153]
	v_pk_fma_f32 v[156:157], v[130:131], v[186:187], v[190:191]
	v_exp_f32_e32 v140, v132
	v_pk_fma_f32 v[132:133], v[142:143], v[186:187], v[190:191]
	v_pk_fma_f32 v[156:157], v[134:135], v[182:183], v[156:157]
	v_pk_fma_f32 v[130:131], v[130:131], v[182:183], v[132:133]
; #define LAS __attribute__((address_space(3)))
; __device__ __forceinline__ float sigmoidf_(float x) { return __builtin_amdgcn_rcpf(1.0f + __expf(-x)); }
;     __device__ __forceinline__ void operator()(AccRef acc, const Unit& u, int wr, int wc, int fr, int fq) const {
;     ...
;                 f32x4 h2v = (f32x4){0.f, 0.f, 0.f, 0.f}, h3v = h2v, h2g = h2v, h3g = h2v;
;                 const int pb = ai * 2 + wr - 1;
;                 if (pb >= 0 && fr == 0) { const LAS float* xp = xch + (pb * 2) * 256 + clb + 4 * n;
;                     h2v = *(const LAS f32x4*)(xp); h3v = *(const LAS f32x4*)(xp + 256); h2g = *(const LAS f32x4*)(xp + 128); h3g = *(const LAS f32x4*)(xp + 256 + 128); }
;                 float o[4][4];
; #pragma unroll
;                 for (int j = 0; j < 4; ++j) {
;                     const float v0 = acc[ai][0][0][n][j], v1 = acc[ai][0][1][n][j], v2 = acc[ai][0][2][n][j], v3 = acc[ai][0][3][n][j];
;                     const float g0 = acc[ai][1][0][n][j], g1 = acc[ai][1][1][n][j], g2 = acc[ai][1][2][n][j], g3 = acc[ai][1][3][n][j];
;                     const float pv3 = dpp_upd<0x111>(h3v[j], v3), pv2 = dpp_upd<0x111>(h2v[j], v2), pg3 = dpp_upd<0x111>(h3g[j], g3), pg2 = dpp_upd<0x111>(h2g[j], g2);
;                     const float hv0 = bvv[j] + w2v[j] * v0 + w1v[j] * pv3 + w0v[j] * pv2, hv1 = bvv[j] + w2v[j] * v1 + w1v[j] * v0 + w0v[j] * pv3;
;                     const float hv2 = bvv[j] + w2v[j] * v2 + w1v[j] * v1 + w0v[j] * v0, hv3 = bvv[j] + w2v[j] * v3 + w1v[j] * v2 + w0v[j] * v1;
;                     const float hg0 = bvg[j] + w2g[j] * g0 + w1g[j] * pg3 + w0g[j] * pg2, hg1 = bvg[j] + w2g[j] * g1 + w1g[j] * g0 + w0g[j] * pg3;
;                     const float hg2 = bvg[j] + w2g[j] * g2 + w1g[j] * g1 + w0g[j] * g0, hg3 = bvg[j] + w2g[j] * g3 + w1g[j] * g2 + w0g[j] * g1;
;                     o[0][j] = hg0 * sigmoidf_(hg0) * hv0; o[1][j] = hg1 * sigmoidf_(hg1) * hv1; o[2][j] = hg2 * sigmoidf_(hg2) * hv2; o[3][j] = hg3 * sigmoidf_(hg3) * hv3; }
; #pragma unroll
;                 for (int m = 0; m < 4; ++m) { u32x2 w; w.x = cvt_pk_bf16(o[m][0], o[m][1]); w.y = cvt_pk_bf16(o[m][2], o[m][3]);
;                     *(u32x2*)(Aout + (size_t)(row0 + ai * 128 + m) * FH + hc0 + 4 * n) = w; } } }
	v_pk_fma_f32 v[154:155], v[154:155], v[178:179], v[156:157]
	v_pk_fma_f32 v[130:131], v[134:135], v[178:179], v[130:131]
	v_mul_f32_e32 v156, 0xbfb8aa3b, v154
	v_mul_f32_e32 v141, 0xbfb8aa3b, v129
	v_mul_f32_e32 v132, 0xbfb8aa3b, v130
	v_mul_f32_e32 v133, 0xbfb8aa3b, v131
	v_exp_f32_e32 v157, v156
	v_mul_f32_e32 v156, 0xbfb8aa3b, v155
	v_exp_f32_e32 v141, v141
	v_exp_f32_e32 v132, v132
	v_exp_f32_e32 v133, v133
	v_exp_f32_e32 v193, v156
	v_add_f32_e32 v140, 1.0, v140
	v_add_f32_e32 v141, 1.0, v141
	v_add_f32_e32 v132, 1.0, v132
	v_add_f32_e32 v133, 1.0, v133
	v_cvt_pk_bf16_f32 v156, v152, v153
	v_add_f32_e32 v152, 1.0, v157
	v_add_f32_e32 v153, 1.0, v193
	v_rcp_f32_e32 v140, v140
	v_rcp_f32_e32 v141, v141
	v_rcp_f32_e32 v132, v132
	v_rcp_f32_e32 v133, v133
	v_rcp_f32_e32 v152, v152
	v_rcp_f32_e32 v153, v153
	v_pk_fma_f32 v[142:143], v[150:151], v[170:171], v[174:175]
	v_pk_fma_f32 v[194:195], v[138:139], v[170:171], v[174:175]
	v_pk_fma_f32 v[136:137], v[136:137], v[164:165], v[148:149]
	v_pk_fma_f32 v[134:135], v[138:139], v[166:167], v[142:143]
	v_pk_fma_f32 v[194:195], v[146:147], v[166:167], v[194:195]
	v_pk_fma_f32 v[136:137], v[144:145], v[160:161], v[136:137]
	v_pk_mul_f32 v[128:129], v[128:129], v[140:141]
	v_pk_fma_f32 v[134:135], v[146:147], v[162:163], v[134:135]
	v_pk_mul_f32 v[130:131], v[130:131], v[132:133]
	v_pk_fma_f32 v[158:159], v[158:159], v[162:163], v[194:195]
	v_pk_mul_f32 v[152:153], v[154:155], v[152:153]
	v_pk_mul_f32 v[128:129], v[136:137], v[128:129]
	v_pk_mul_f32 v[130:131], v[134:135], v[130:131]
	v_pk_mul_f32 v[152:153], v[158:159], v[152:153]
	v_cvt_pk_bf16_f32 v128, v128, v129
	v_cvt_pk_bf16_f32 v129, v130, v131
	v_or_b32_e32 v130, 3, v246
	v_cvt_pk_bf16_f32 v157, v152, v153
	v_or_b32_e32 v152, 2, v246
	v_mad_i64_i32 v[130:131], s[40:41], v130, s76, v[206:207]
	v_mad_i64_i32 v[152:153], s[40:41], v152, s76, v[206:207]
	v_lshl_add_u64 v[140:141], v[130:131], 0, v[204:205]
	v_lshl_add_u64 v[152:153], v[152:153], 0, v[204:205]
	v_mov_b32_e32 v251, v128
	v_mov_b32_e32 v253, v129
	v_mov_b32_e32 v193, 0
	v_mov_b32_e32 v194, 0
	v_mov_b32_e32 v195, 0
	v_mov_b32_e32 v136, 0
	v_mov_b32_e32 v137, 0
	v_mov_b32_e32 v138, 0
	v_mov_b32_e32 v139, 0
	v_mov_b32_e32 v128, 0
	v_mov_b32_e32 v129, 0
	v_mov_b32_e32 v130, 0
	v_mov_b32_e32 v131, 0
	v_mov_b32_e32 v132, 0
	v_mov_b32_e32 v133, 0
	v_mov_b32_e32 v134, 0
	v_mov_b32_e32 v135, 0
	v_mov_b32_e32 v254, v156
	v_mov_b32_e32 v255, v157
	s_and_saveexec_b64 s[40:41], s[28:29]
	s_cbranch_execz .LBB0_769
	ds_read_b128 v[132:135], v237 offset:2048
	ds_read_b128 v[136:139], v237 offset:2560
	ds_read_b128 v[128:131], v237 offset:3072
	ds_read_b128 v[192:195], v237 offset:3584
.LBB0_769:
	s_or_b64 exec, exec, s[40:41]
	s_waitcnt lgkmcnt(0)
	v_mov_b32_dpp v192, v72 row_shr:1 row_mask:0xf bank_mask:0xf
	v_mov_b32_dpp v193, v73 row_shr:1 row_mask:0xf bank_mask:0xf
	v_pk_fma_f32 v[142:143], v[88:89], v[184:185], v[188:189]
	v_mov_b32_dpp v136, v64 row_shr:1 row_mask:0xf bank_mask:0xf
	v_mov_b32_dpp v137, v65 row_shr:1 row_mask:0xf bank_mask:0xf
	v_pk_fma_f32 v[142:143], v[180:181], v[192:193], v[142:143]
	v_mov_b32_dpp v128, v84 row_shr:1 row_mask:0xf bank_mask:0xf
	v_pk_fma_f32 v[136:137], v[176:177], v[136:137], v[142:143]
	v_mov_b32_dpp v129, v85 row_shr:1 row_mask:0xf bank_mask:0xf
	v_mul_f32_e32 v142, 0xbfb8aa3b, v136
	v_mul_f32_e32 v143, 0xbfb8aa3b, v137
	v_exp_f32_e32 v142, v142
	v_exp_f32_e32 v143, v143
	v_pk_fma_f32 v[144:145], v[92:93], v[168:169], v[172:173]
	v_mov_b32_dpp v132, v76 row_shr:1 row_mask:0xf bank_mask:0xf
	v_add_f32_e32 v142, 1.0, v142
	v_add_f32_e32 v143, 1.0, v143
	v_rcp_f32_e32 v142, v142
	v_rcp_f32_e32 v143, v143
	v_mov_b32_dpp v133, v77 row_shr:1 row_mask:0xf bank_mask:0xf
	v_pk_fma_f32 v[144:145], v[164:165], v[128:129], v[144:145]
	v_mov_b32_dpp v194, v74 row_shr:1 row_mask:0xf bank_mask:0xf
	v_pk_fma_f32 v[132:133], v[160:161], v[132:133], v[144:145]
	v_pk_mul_f32 v[136:137], v[136:137], v[142:143]
	v_mov_b32_dpp v195, v75 row_shr:1 row_mask:0xf bank_mask:0xf
	v_pk_mul_f32 v[132:133], v[132:133], v[136:137]
	v_pk_fma_f32 v[136:137], v[90:91], v[186:187], v[190:191]
	v_mov_b32_dpp v138, v66 row_shr:1 row_mask:0xf bank_mask:0xf
	v_mov_b32_dpp v139, v67 row_shr:1 row_mask:0xf bank_mask:0xf
	v_pk_fma_f32 v[136:137], v[182:183], v[194:195], v[136:137]
	v_mov_b32_dpp v130, v86 row_shr:1 row_mask:0xf bank_mask:0xf
	v_pk_fma_f32 v[136:137], v[178:179], v[138:139], v[136:137]
	v_mov_b32_dpp v131, v87 row_shr:1 row_mask:0xf bank_mask:0xf
	v_mul_f32_e32 v138, 0xbfb8aa3b, v136
	v_exp_f32_e32 v139, v138
	v_mul_f32_e32 v138, 0xbfb8aa3b, v137
	v_exp_f32_e32 v142, v138
	v_cvt_pk_bf16_f32 v138, v132, v133
	v_add_f32_e32 v132, 1.0, v139
	v_rcp_f32_e32 v132, v132
	v_add_f32_e32 v133, 1.0, v142
	v_rcp_f32_e32 v133, v133
	v_pk_fma_f32 v[142:143], v[94:95], v[170:171], v[174:175]
	v_mov_b32_dpp v134, v78 row_shr:1 row_mask:0xf bank_mask:0xf
	v_mov_b32_dpp v135, v79 row_shr:1 row_mask:0xf bank_mask:0xf
	v_pk_mul_f32 v[132:133], v[136:137], v[132:133]
	v_pk_fma_f32 v[136:137], v[68:69], v[184:185], v[188:189]
	v_pk_fma_f32 v[142:143], v[166:167], v[130:131], v[142:143]
	v_pk_fma_f32 v[136:137], v[88:89], v[180:181], v[136:137]
	v_pk_fma_f32 v[134:135], v[162:163], v[134:135], v[142:143]
	v_pk_fma_f32 v[136:137], v[176:177], v[192:193], v[136:137]
	v_add_u32_e32 v146, 0x80, v246
	v_mul_f32_e32 v142, 0xbfb8aa3b, v136
	v_mul_f32_e32 v143, 0xbfb8aa3b, v137
	v_exp_f32_e32 v142, v142
	v_exp_f32_e32 v143, v143
	v_pk_mul_f32 v[132:133], v[134:135], v[132:133]
	v_mov_b64_e32 v[134:135], s[60:61]
	v_cvt_pk_bf16_f32 v139, v132, v133
	v_mad_i64_i32 v[132:133], s[40:41], v146, s76, v[134:135]
; #define LAS __attribute__((address_space(3)))
; __device__ __forceinline__ float sigmoidf_(float x) { return __builtin_amdgcn_rcpf(1.0f + __expf(-x)); }
;     __device__ __forceinline__ void operator()(AccRef acc, const Unit& u, int wr, int wc, int fr, int fq) const {
;     ...
;                 f32x4 h2v = (f32x4){0.f, 0.f, 0.f, 0.f}, h3v = h2v, h2g = h2v, h3g = h2v;
;                 const int pb = ai * 2 + wr - 1;
;                 if (pb >= 0 && fr == 0) { const LAS float* xp = xch + (pb * 2) * 256 + clb + 4 * n;
;                     h2v = *(const LAS f32x4*)(xp); h3v = *(const LAS f32x4*)(xp + 256); h2g = *(const LAS f32x4*)(xp + 128); h3g = *(const LAS f32x4*)(xp + 256 + 128); }
;                 float o[4][4];
; #pragma unroll
;                 for (int j = 0; j < 4; ++j) {
;                     const float v0 = acc[ai][0][0][n][j], v1 = acc[ai][0][1][n][j], v2 = acc[ai][0][2][n][j], v3 = acc[ai][0][3][n][j];
;                     const float g0 = acc[ai][1][0][n][j], g1 = acc[ai][1][1][n][j], g2 = acc[ai][1][2][n][j], g3 = acc[ai][1][3][n][j];
;                     const float pv3 = dpp_upd<0x111>(h3v[j], v3), pv2 = dpp_upd<0x111>(h2v[j], v2), pg3 = dpp_upd<0x111>(h3g[j], g3), pg2 = dpp_upd<0x111>(h2g[j], g2);
;                     const float hv0 = bvv[j] + w2v[j] * v0 + w1v[j] * pv3 + w0v[j] * pv2, hv1 = bvv[j] + w2v[j] * v1 + w1v[j] * v0 + w0v[j] * pv3;
;                     const float hv2 = bvv[j] + w2v[j] * v2 + w1v[j] * v1 + w0v[j] * v0, hv3 = bvv[j] + w2v[j] * v3 + w1v[j] * v2 + w0v[j] * v1;
;                     const float hg0 = bvg[j] + w2g[j] * g0 + w1g[j] * pg3 + w0g[j] * pg2, hg1 = bvg[j] + w2g[j] * g1 + w1g[j] * g0 + w0g[j] * pg3;
;                     const float hg2 = bvg[j] + w2g[j] * g2 + w1g[j] * g1 + w0g[j] * g0, hg3 = bvg[j] + w2g[j] * g3 + w1g[j] * g2 + w0g[j] * g1;
;                     o[0][j] = hg0 * sigmoidf_(hg0) * hv0; o[1][j] = hg1 * sigmoidf_(hg1) * hv1; o[2][j] = hg2 * sigmoidf_(hg2) * hv2; o[3][j] = hg3 * sigmoidf_(hg3) * hv3; }
; #pragma unroll
;                 for (int m = 0; m < 4; ++m) { u32x2 w; w.x = cvt_pk_bf16(o[m][0], o[m][1]); w.y = cvt_pk_bf16(o[m][2], o[m][3]);
;                     *(u32x2*)(Aout + (size_t)(row0 + ai * 128 + m) * FH + hc0 + 4 * n) = w; } } }
	v_lshl_add_u64 v[132:133], v[132:133], 0, v[204:205]
	v_mov_b32_e32 v144, v138
	v_mov_b32_e32 v145, v139
	v_add_f32_e32 v138, 1.0, v142
	v_add_f32_e32 v139, 1.0, v143
	v_rcp_f32_e32 v138, v138
	v_rcp_f32_e32 v139, v139
	v_pk_fma_f32 v[142:143], v[80:81], v[168:169], v[172:173]
	v_pk_fma_f32 v[72:73], v[72:73], v[184:185], v[188:189]
	v_pk_fma_f32 v[142:143], v[92:93], v[164:165], v[142:143]
	v_pk_mul_f32 v[136:137], v[136:137], v[138:139]
	v_pk_fma_f32 v[128:129], v[160:161], v[128:129], v[142:143]
	v_pk_fma_f32 v[84:85], v[84:85], v[168:169], v[172:173]
	v_pk_mul_f32 v[128:129], v[128:129], v[136:137]
	v_pk_fma_f32 v[136:137], v[70:71], v[186:187], v[190:191]
	s_nop 0
	v_pk_fma_f32 v[136:137], v[90:91], v[182:183], v[136:137]
	s_nop 0
	v_pk_fma_f32 v[136:137], v[178:179], v[194:195], v[136:137]
	s_nop 0
	v_mul_f32_e32 v138, 0xbfb8aa3b, v136
	v_exp_f32_e32 v139, v138
	v_mul_f32_e32 v138, 0xbfb8aa3b, v137
	v_exp_f32_e32 v142, v138
	v_cvt_pk_bf16_f32 v138, v128, v129
	v_add_f32_e32 v128, 1.0, v139
	v_rcp_f32_e32 v128, v128
	v_add_f32_e32 v129, 1.0, v142
	v_rcp_f32_e32 v129, v129
	v_pk_fma_f32 v[142:143], v[82:83], v[170:171], v[174:175]
	v_pk_mul_f32 v[128:129], v[136:137], v[128:129]
	v_pk_fma_f32 v[142:143], v[94:95], v[166:167], v[142:143]
	v_pk_fma_f32 v[136:137], v[76:77], v[168:169], v[172:173]
	v_pk_fma_f32 v[130:131], v[162:163], v[130:131], v[142:143]
	v_pk_fma_f32 v[136:137], v[80:81], v[164:165], v[136:137]
	v_pk_mul_f32 v[128:129], v[130:131], v[128:129]
	v_pk_fma_f32 v[130:131], v[64:65], v[184:185], v[188:189]
	v_pk_fma_f32 v[64:65], v[64:65], v[180:181], v[72:73]
	v_pk_fma_f32 v[130:131], v[68:69], v[180:181], v[130:131]
	v_pk_fma_f32 v[64:65], v[68:69], v[176:177], v[64:65]
	v_pk_fma_f32 v[88:89], v[88:89], v[176:177], v[130:131]
	v_pk_fma_f32 v[92:93], v[92:93], v[160:161], v[136:137]
	v_mul_f32_e32 v130, 0xbfb8aa3b, v88
	v_mul_f32_e32 v131, 0xbfb8aa3b, v89
	v_exp_f32_e32 v130, v130
	v_exp_f32_e32 v131, v131
	v_mul_f32_e32 v68, 0xbfb8aa3b, v64
	v_exp_f32_e32 v72, v68
	v_add_f32_e32 v130, 1.0, v130
	v_add_f32_e32 v131, 1.0, v131
	v_rcp_f32_e32 v130, v130
	v_rcp_f32_e32 v131, v131
	v_pk_fma_f32 v[68:69], v[74:75], v[186:187], v[190:191]
	v_mul_f32_e32 v73, 0xbfb8aa3b, v65
	v_exp_f32_e32 v73, v73
	v_pk_mul_f32 v[88:89], v[88:89], v[130:131]
	v_add_f32_e32 v72, 1.0, v72
	v_pk_mul_f32 v[88:89], v[92:93], v[88:89]
	v_pk_fma_f32 v[92:93], v[66:67], v[186:187], v[190:191]
	v_pk_fma_f32 v[66:67], v[66:67], v[182:183], v[68:69]
	v_pk_fma_f32 v[92:93], v[70:71], v[182:183], v[92:93]
	v_pk_fma_f32 v[66:67], v[70:71], v[178:179], v[66:67]
	v_pk_fma_f32 v[90:91], v[90:91], v[178:179], v[92:93]
	v_mul_f32_e32 v68, 0xbfb8aa3b, v66
	v_mul_f32_e32 v92, 0xbfb8aa3b, v90
	v_mul_f32_e32 v69, 0xbfb8aa3b, v67
	v_exp_f32_e32 v93, v92
	v_mul_f32_e32 v92, 0xbfb8aa3b, v91
	v_exp_f32_e32 v68, v68
	v_exp_f32_e32 v69, v69
	v_exp_f32_e32 v130, v92
	v_add_f32_e32 v73, 1.0, v73
	v_add_f32_e32 v68, 1.0, v68
	v_add_f32_e32 v69, 1.0, v69
	v_cvt_pk_bf16_f32 v92, v88, v89
	v_add_f32_e32 v88, 1.0, v93
	v_add_f32_e32 v89, 1.0, v130
	v_rcp_f32_e32 v72, v72
	v_rcp_f32_e32 v73, v73
	v_rcp_f32_e32 v68, v68
	v_rcp_f32_e32 v69, v69
	v_rcp_f32_e32 v88, v88
	v_rcp_f32_e32 v89, v89
	v_pk_fma_f32 v[74:75], v[86:87], v[170:171], v[174:175]
	v_pk_fma_f32 v[130:131], v[78:79], v[170:171], v[174:175]
	v_pk_fma_f32 v[76:77], v[76:77], v[164:165], v[84:85]
	v_pk_fma_f32 v[70:71], v[78:79], v[166:167], v[74:75]
	v_pk_fma_f32 v[130:131], v[82:83], v[166:167], v[130:131]
	v_pk_fma_f32 v[76:77], v[80:81], v[160:161], v[76:77]
	v_pk_mul_f32 v[64:65], v[64:65], v[72:73]
	v_pk_fma_f32 v[70:71], v[82:83], v[162:163], v[70:71]
	v_pk_mul_f32 v[66:67], v[66:67], v[68:69]
	v_pk_fma_f32 v[94:95], v[94:95], v[162:163], v[130:131]
	v_pk_mul_f32 v[88:89], v[90:91], v[88:89]
	v_pk_mul_f32 v[64:65], v[76:77], v[64:65]
	v_pk_mul_f32 v[66:67], v[70:71], v[66:67]
	v_pk_mul_f32 v[88:89], v[94:95], v[88:89]
	v_cvt_pk_bf16_f32 v64, v64, v65
	v_cvt_pk_bf16_f32 v65, v66, v67
	v_add_u32_e32 v66, 0x83, v246
	v_cvt_pk_bf16_f32 v139, v128, v129
	v_add_u32_e32 v128, 0x81, v246
	v_cvt_pk_bf16_f32 v93, v88, v89
	v_add_u32_e32 v88, 0x82, v246
	v_mad_i64_i32 v[66:67], s[40:41], v66, s76, v[134:135]
	v_mad_i64_i32 v[128:129], s[40:41], v128, s76, v[134:135]
	v_mad_i64_i32 v[88:89], s[40:41], v88, s76, v[134:135]
	v_lshl_add_u64 v[82:83], v[66:67], 0, v[204:205]
	v_lshl_add_u64 v[128:129], v[128:129], 0, v[204:205]
	v_lshl_add_u64 v[88:89], v[88:89], 0, v[204:205]
	v_mov_b32_e32 v148, v64
	v_mov_b32_e32 v149, v65
	v_mov_b32_e32 v64, 0
	v_mov_b32_e32 v70, 0
	v_mov_b32_e32 v71, 0
	v_mov_b32_e32 v72, 0
	v_mov_b32_e32 v73, 0
	v_mov_b32_e32 v78, 0
	v_mov_b32_e32 v79, 0
	v_mov_b32_e32 v80, 0
	v_mov_b32_e32 v81, 0
	v_mov_b32_e32 v66, 0
	v_mov_b32_e32 v67, 0
	v_mov_b32_e32 v68, 0
	v_mov_b32_e32 v69, 0
	v_mov_b32_e32 v74, 0
	v_mov_b32_e32 v75, 0
	v_mov_b32_e32 v76, 0
	v_mov_b32_e32 v77, 0
	v_mov_b32_e32 v154, v138
	v_mov_b32_e32 v155, v139
	v_mov_b32_e32 v198, v92
	v_mov_b32_e32 v199, v93
	s_and_saveexec_b64 s[40:41], s[26:27]
	s_cbranch_execz .LBB0_771
	ds_read_b128 v[74:77], v242
	ds_read_b128 v[66:69], v241
	ds_read_b128 v[78:81], v240
	ds_read_b128 v[70:73], v239
; #define LAS __attribute__((address_space(3)))
; __device__ __forceinline__ float sigmoidf_(float x) { return __builtin_amdgcn_rcpf(1.0f + __expf(-x)); }
;     __device__ __forceinline__ void operator()(AccRef acc, const Unit& u, int wr, int wc, int fr, int fq) const {
;     ...
;                 f32x4 h2v = (f32x4){0.f, 0.f, 0.f, 0.f}, h3v = h2v, h2g = h2v, h3g = h2v;
;                 const int pb = ai * 2 + wr - 1;
;                 if (pb >= 0 && fr == 0) { const LAS float* xp = xch + (pb * 2) * 256 + clb + 4 * n;
;                     h2v = *(const LAS f32x4*)(xp); h3v = *(const LAS f32x4*)(xp + 256); h2g = *(const LAS f32x4*)(xp + 128); h3g = *(const LAS f32x4*)(xp + 256 + 128); }
;                 float o[4][4];
; #pragma unroll
;                 for (int j = 0; j < 4; ++j) {
;                     const float v0 = acc[ai][0][0][n][j], v1 = acc[ai][0][1][n][j], v2 = acc[ai][0][2][n][j], v3 = acc[ai][0][3][n][j];
;                     const float g0 = acc[ai][1][0][n][j], g1 = acc[ai][1][1][n][j], g2 = acc[ai][1][2][n][j], g3 = acc[ai][1][3][n][j];
;                     const float pv3 = dpp_upd<0x111>(h3v[j], v3), pv2 = dpp_upd<0x111>(h2v[j], v2), pg3 = dpp_upd<0x111>(h3g[j], g3), pg2 = dpp_upd<0x111>(h2g[j], g2);
;                     const float hv0 = bvv[j] + w2v[j] * v0 + w1v[j] * pv3 + w0v[j] * pv2, hv1 = bvv[j] + w2v[j] * v1 + w1v[j] * v0 + w0v[j] * pv3;
;                     const float hv2 = bvv[j] + w2v[j] * v2 + w1v[j] * v1 + w0v[j] * v0, hv3 = bvv[j] + w2v[j] * v3 + w1v[j] * v2 + w0v[j] * v1;
;                     const float hg0 = bvg[j] + w2g[j] * g0 + w1g[j] * pg3 + w0g[j] * pg2, hg1 = bvg[j] + w2g[j] * g1 + w1g[j] * g0 + w0g[j] * pg3;
;                     const float hg2 = bvg[j] + w2g[j] * g2 + w1g[j] * g1 + w0g[j] * g0, hg3 = bvg[j] + w2g[j] * g3 + w1g[j] * g2 + w0g[j] * g1;
;                     o[0][j] = hg0 * sigmoidf_(hg0) * hv0; o[1][j] = hg1 * sigmoidf_(hg1) * hv1; o[2][j] = hg2 * sigmoidf_(hg2) * hv2; o[3][j] = hg3 * sigmoidf_(hg3) * hv3; }
; #pragma unroll
;                 for (int m = 0; m < 4; ++m) { u32x2 w; w.x = cvt_pk_bf16(o[m][0], o[m][1]); w.y = cvt_pk_bf16(o[m][2], o[m][3]);
;                     *(u32x2*)(Aout + (size_t)(row0 + ai * 128 + m) * FH + hc0 + 4 * n) = w; } } }
.LBB0_771:
	s_or_b64 exec, exec, s[40:41]
	s_waitcnt lgkmcnt(0)
	v_mov_b32_dpp v70, v44 row_shr:1 row_mask:0xf bank_mask:0xf
	v_mov_b32_dpp v71, v45 row_shr:1 row_mask:0xf bank_mask:0xf
	s_waitcnt vmcnt(0)
	v_pk_fma_f32 v[84:85], v[56:57], v[120:121], v[124:125]
	v_mov_b32_dpp v78, v32 row_shr:1 row_mask:0xf bank_mask:0xf
	v_mov_b32_dpp v79, v33 row_shr:1 row_mask:0xf bank_mask:0xf
	v_pk_fma_f32 v[84:85], v[116:117], v[70:71], v[84:85]
	v_mov_b32_dpp v66, v52 row_shr:1 row_mask:0xf bank_mask:0xf
	v_pk_fma_f32 v[78:79], v[112:113], v[78:79], v[84:85]
	v_mov_b32_dpp v67, v53 row_shr:1 row_mask:0xf bank_mask:0xf
	v_mul_f32_e32 v65, 0xbfb8aa3b, v78
	v_exp_f32_e32 v65, v65
	v_mul_f32_e32 v84, 0xbfb8aa3b, v79
	v_exp_f32_e32 v85, v84
	v_pk_fma_f32 v[86:87], v[60:61], v[104:105], v[108:109]
	v_add_f32_e32 v65, 1.0, v65
	v_rcp_f32_e32 v84, v65
	v_add_f32_e32 v65, 1.0, v85
	v_rcp_f32_e32 v85, v65
	v_mov_b32_dpp v74, v40 row_shr:1 row_mask:0xf bank_mask:0xf
	v_mov_b32_dpp v75, v41 row_shr:1 row_mask:0xf bank_mask:0xf
	v_pk_fma_f32 v[86:87], v[100:101], v[66:67], v[86:87]
	v_pk_mul_f32 v[78:79], v[78:79], v[84:85]
	v_pk_fma_f32 v[74:75], v[96:97], v[74:75], v[86:87]
	v_mov_b32_dpp v72, v46 row_shr:1 row_mask:0xf bank_mask:0xf
	v_mov_b32_dpp v73, v47 row_shr:1 row_mask:0xf bank_mask:0xf
	v_pk_mul_f32 v[74:75], v[74:75], v[78:79]
	v_pk_fma_f32 v[78:79], v[58:59], v[122:123], v[126:127]
	v_mov_b32_dpp v80, v34 row_shr:1 row_mask:0xf bank_mask:0xf
	v_mov_b32_dpp v81, v35 row_shr:1 row_mask:0xf bank_mask:0xf
	v_pk_fma_f32 v[78:79], v[118:119], v[72:73], v[78:79]
	v_mov_b32_dpp v68, v54 row_shr:1 row_mask:0xf bank_mask:0xf
	v_pk_fma_f32 v[78:79], v[114:115], v[80:81], v[78:79]
	v_mov_b32_dpp v69, v55 row_shr:1 row_mask:0xf bank_mask:0xf
	v_mul_f32_e32 v65, 0xbfb8aa3b, v78
	v_exp_f32_e32 v65, v65
	v_mul_f32_e32 v80, 0xbfb8aa3b, v79
	v_exp_f32_e32 v81, v80
	v_pk_fma_f32 v[84:85], v[62:63], v[106:107], v[110:111]
	v_add_f32_e32 v65, 1.0, v65
	v_rcp_f32_e32 v80, v65
	v_add_f32_e32 v65, 1.0, v81
	v_rcp_f32_e32 v81, v65
	v_mov_b32_dpp v76, v42 row_shr:1 row_mask:0xf bank_mask:0xf
	v_mov_b32_dpp v77, v43 row_shr:1 row_mask:0xf bank_mask:0xf
	v_pk_fma_f32 v[84:85], v[102:103], v[68:69], v[84:85]
	v_pk_mul_f32 v[78:79], v[78:79], v[80:81]
	v_pk_fma_f32 v[76:77], v[98:99], v[76:77], v[84:85]
	v_cvt_pk_bf16_f32 v74, v74, v75
	v_pk_mul_f32 v[76:77], v[76:77], v[78:79]
	v_pk_fma_f32 v[44:45], v[44:45], v[120:121], v[124:125]
	v_cvt_pk_bf16_f32 v75, v76, v77
	v_pk_fma_f32 v[76:77], v[36:37], v[120:121], v[124:125]
	v_mov_b32_e32 v90, v247
	v_mov_b32_e32 v91, v248
	v_mov_b32_e32 v92, v74
	v_mov_b32_e32 v93, v75
	global_store_dwordx4 v[202:203], v[90:93], off
	v_pk_fma_f32 v[76:77], v[56:57], v[116:117], v[76:77]
	v_pk_fma_f32 v[52:53], v[52:53], v[104:105], v[108:109]
	v_pk_fma_f32 v[70:71], v[112:113], v[70:71], v[76:77]
	s_nop 0
	v_mul_f32_e32 v65, 0xbfb8aa3b, v70
	v_exp_f32_e32 v65, v65
	v_mul_f32_e32 v76, 0xbfb8aa3b, v71
	v_exp_f32_e32 v76, v76
	v_add_f32_e32 v65, 1.0, v65
	v_rcp_f32_e32 v74, v65
	v_add_f32_e32 v65, 1.0, v76
	v_rcp_f32_e32 v75, v65
	v_pk_fma_f32 v[76:77], v[48:49], v[104:105], v[108:109]
	v_pk_mul_f32 v[70:71], v[70:71], v[74:75]
	v_pk_fma_f32 v[76:77], v[60:61], v[100:101], v[76:77]
	v_pk_fma_f32 v[74:75], v[50:51], v[106:107], v[110:111]
	v_pk_fma_f32 v[66:67], v[96:97], v[66:67], v[76:77]
	v_pk_fma_f32 v[74:75], v[62:63], v[102:103], v[74:75]
	v_pk_mul_f32 v[66:67], v[66:67], v[70:71]
	v_pk_fma_f32 v[70:71], v[38:39], v[122:123], v[126:127]
	v_pk_fma_f32 v[68:69], v[98:99], v[68:69], v[74:75]
	v_pk_fma_f32 v[70:71], v[58:59], v[118:119], v[70:71]
	v_cvt_pk_bf16_f32 v66, v66, v67
	v_pk_fma_f32 v[70:71], v[114:115], v[72:73], v[70:71]
	s_nop 0
	v_mul_f32_e32 v65, 0xbfb8aa3b, v70
	v_exp_f32_e32 v65, v65
	v_mul_f32_e32 v72, 0xbfb8aa3b, v71
	v_exp_f32_e32 v73, v72
	v_add_f32_e32 v65, 1.0, v65
; #define LAS __attribute__((address_space(3)))
; __device__ __forceinline__ float sigmoidf_(float x) { return __builtin_amdgcn_rcpf(1.0f + __expf(-x)); }
;     __device__ __forceinline__ void operator()(AccRef acc, const Unit& u, int wr, int wc, int fr, int fq) const {
;     ...
;                 f32x4 h2v = (f32x4){0.f, 0.f, 0.f, 0.f}, h3v = h2v, h2g = h2v, h3g = h2v;
;                 const int pb = ai * 2 + wr - 1;
;                 if (pb >= 0 && fr == 0) { const LAS float* xp = xch + (pb * 2) * 256 + clb + 4 * n;
;                     h2v = *(const LAS f32x4*)(xp); h3v = *(const LAS f32x4*)(xp + 256); h2g = *(const LAS f32x4*)(xp + 128); h3g = *(const LAS f32x4*)(xp + 256 + 128); }
;                 float o[4][4];
; #pragma unroll
;                 for (int j = 0; j < 4; ++j) {
;                     const float v0 = acc[ai][0][0][n][j], v1 = acc[ai][0][1][n][j], v2 = acc[ai][0][2][n][j], v3 = acc[ai][0][3][n][j];
;                     const float g0 = acc[ai][1][0][n][j], g1 = acc[ai][1][1][n][j], g2 = acc[ai][1][2][n][j], g3 = acc[ai][1][3][n][j];
;                     const float pv3 = dpp_upd<0x111>(h3v[j], v3), pv2 = dpp_upd<0x111>(h2v[j], v2), pg3 = dpp_upd<0x111>(h3g[j], g3), pg2 = dpp_upd<0x111>(h2g[j], g2);
;                     const float hv0 = bvv[j] + w2v[j] * v0 + w1v[j] * pv3 + w0v[j] * pv2, hv1 = bvv[j] + w2v[j] * v1 + w1v[j] * v0 + w0v[j] * pv3;
;                     const float hv2 = bvv[j] + w2v[j] * v2 + w1v[j] * v1 + w0v[j] * v0, hv3 = bvv[j] + w2v[j] * v3 + w1v[j] * v2 + w0v[j] * v1;
;                     const float hg0 = bvg[j] + w2g[j] * g0 + w1g[j] * pg3 + w0g[j] * pg2, hg1 = bvg[j] + w2g[j] * g1 + w1g[j] * g0 + w0g[j] * pg3;
;                     const float hg2 = bvg[j] + w2g[j] * g2 + w1g[j] * g1 + w0g[j] * g0, hg3 = bvg[j] + w2g[j] * g3 + w1g[j] * g2 + w0g[j] * g1;
;                     o[0][j] = hg0 * sigmoidf_(hg0) * hv0; o[1][j] = hg1 * sigmoidf_(hg1) * hv1; o[2][j] = hg2 * sigmoidf_(hg2) * hv2; o[3][j] = hg3 * sigmoidf_(hg3) * hv3; }
; #pragma unroll
;                 for (int m = 0; m < 4; ++m) { u32x2 w; w.x = cvt_pk_bf16(o[m][0], o[m][1]); w.y = cvt_pk_bf16(o[m][2], o[m][3]);
;                     *(u32x2*)(Aout + (size_t)(row0 + ai * 128 + m) * FH + hc0 + 4 * n) = w; } } }
	v_rcp_f32_e32 v72, v65
	v_add_f32_e32 v65, 1.0, v73
	v_rcp_f32_e32 v73, v65
	s_nop 0
	v_pk_mul_f32 v[70:71], v[70:71], v[72:73]
	s_nop 0
	v_pk_mul_f32 v[68:69], v[68:69], v[70:71]
	s_nop 0
	v_cvt_pk_bf16_f32 v67, v68, v69
	v_pk_fma_f32 v[68:69], v[32:33], v[120:121], v[124:125]
	v_mov_b32_e32 v134, v249
	v_mov_b32_e32 v135, v250
	v_mov_b32_e32 v136, v66
	v_mov_b32_e32 v137, v67
	global_store_dwordx4 v[196:197], v[134:137], off
	v_pk_fma_f32 v[68:69], v[36:37], v[116:117], v[68:69]
	v_pk_fma_f32 v[32:33], v[32:33], v[116:117], v[44:45]
	v_pk_fma_f32 v[56:57], v[56:57], v[112:113], v[68:69]
	v_pk_fma_f32 v[32:33], v[36:37], v[112:113], v[32:33]
	v_mul_f32_e32 v65, 0xbfb8aa3b, v56
	v_exp_f32_e32 v65, v65
	v_mul_f32_e32 v68, 0xbfb8aa3b, v57
	v_exp_f32_e32 v68, v68
	v_mul_f32_e32 v36, 0xbfb8aa3b, v32
	v_add_f32_e32 v65, 1.0, v65
	v_rcp_f32_e32 v66, v65
	v_add_f32_e32 v65, 1.0, v68
	v_rcp_f32_e32 v67, v65
	v_pk_fma_f32 v[68:69], v[40:41], v[104:105], v[108:109]
	v_exp_f32_e32 v44, v36
	v_pk_fma_f32 v[68:69], v[48:49], v[100:101], v[68:69]
	v_pk_mul_f32 v[56:57], v[56:57], v[66:67]
	v_pk_fma_f32 v[60:61], v[60:61], v[96:97], v[68:69]
	v_pk_fma_f32 v[36:37], v[46:47], v[122:123], v[126:127]
	v_pk_mul_f32 v[56:57], v[60:61], v[56:57]
	v_pk_fma_f32 v[60:61], v[34:35], v[122:123], v[126:127]
	v_pk_fma_f32 v[34:35], v[34:35], v[118:119], v[36:37]
	v_pk_fma_f32 v[60:61], v[38:39], v[118:119], v[60:61]
	v_pk_fma_f32 v[34:35], v[38:39], v[114:115], v[34:35]
	v_pk_fma_f32 v[58:59], v[58:59], v[114:115], v[60:61]
	v_mul_f32_e32 v45, 0xbfb8aa3b, v33
	v_mul_f32_e32 v60, 0xbfb8aa3b, v58
	v_mul_f32_e32 v36, 0xbfb8aa3b, v34
	v_mul_f32_e32 v37, 0xbfb8aa3b, v35
	v_exp_f32_e32 v60, v60
	v_mul_f32_e32 v61, 0xbfb8aa3b, v59
	v_exp_f32_e32 v45, v45
	v_exp_f32_e32 v36, v36
	v_exp_f32_e32 v37, v37
	v_exp_f32_e32 v61, v61
	v_cvt_pk_bf16_f32 v56, v56, v57
	v_add_f32_e32 v57, 1.0, v60
	v_add_f32_e32 v44, 1.0, v44
	v_add_f32_e32 v45, 1.0, v45
	v_add_f32_e32 v36, 1.0, v36
	v_add_f32_e32 v37, 1.0, v37
	v_rcp_f32_e32 v60, v57
	v_add_f32_e32 v57, 1.0, v61
	v_rcp_f32_e32 v44, v44
	v_rcp_f32_e32 v45, v45
	v_rcp_f32_e32 v36, v36
	v_rcp_f32_e32 v37, v37
	v_rcp_f32_e32 v61, v57
	v_pk_fma_f32 v[46:47], v[54:55], v[106:107], v[110:111]
	v_pk_fma_f32 v[66:67], v[42:43], v[106:107], v[110:111]
	v_pk_fma_f32 v[40:41], v[40:41], v[100:101], v[52:53]
	v_pk_fma_f32 v[38:39], v[42:43], v[102:103], v[46:47]
	v_pk_fma_f32 v[66:67], v[50:51], v[102:103], v[66:67]
	v_pk_fma_f32 v[40:41], v[48:49], v[96:97], v[40:41]
	v_pk_mul_f32 v[32:33], v[32:33], v[44:45]
	v_pk_fma_f32 v[38:39], v[50:51], v[98:99], v[38:39]
	v_pk_mul_f32 v[34:35], v[34:35], v[36:37]
	v_pk_fma_f32 v[62:63], v[62:63], v[98:99], v[66:67]
	v_pk_mul_f32 v[58:59], v[58:59], v[60:61]
	v_pk_mul_f32 v[32:33], v[40:41], v[32:33]
	v_pk_mul_f32 v[34:35], v[38:39], v[34:35]
	v_pk_mul_f32 v[58:59], v[62:63], v[58:59]
	v_cvt_pk_bf16_f32 v32, v32, v33
	v_cvt_pk_bf16_f32 v33, v34, v35
	v_cvt_pk_bf16_f32 v57, v58, v59
	v_mov_b32_e32 v158, v251
	v_mov_b32_e32 v159, v253
	v_mov_b32_e32 v160, v32
	v_mov_b32_e32 v161, v33
	global_store_dwordx4 v[140:141], v[158:161], off
	v_mov_b32_e32 v65, 0
	v_mov_b32_e32 v66, 0
	v_mov_b32_e32 v67, 0
	v_mov_b32_e32 v40, 0
	v_mov_b32_e32 v41, 0
	v_mov_b32_e32 v42, 0
	v_mov_b32_e32 v43, 0
	v_mov_b32_e32 v32, 0
	v_mov_b32_e32 v33, 0
	v_mov_b32_e32 v34, 0
	v_mov_b32_e32 v35, 0
	v_mov_b32_e32 v36, 0
	v_mov_b32_e32 v37, 0
	v_mov_b32_e32 v38, 0
	v_mov_b32_e32 v39, 0
	v_mov_b32_e32 v162, v254
	v_mov_b32_e32 v163, v255
	v_mov_b32_e32 v164, v56
	v_mov_b32_e32 v165, v57
	global_store_dwordx4 v[152:153], v[162:165], off
	s_and_saveexec_b64 s[40:41], s[28:29]
	s_cbranch_execz .LBB0_754
	ds_read_b128 v[36:39], v237 offset:2064
	ds_read_b128 v[40:43], v237 offset:2576
	ds_read_b128 v[32:35], v237 offset:3088
	ds_read_b128 v[64:67], v237 offset:3600
	s_branch .LBB0_754

; #define LAS __attribute__((address_space(3)))
; __device__ __forceinline__ float sigmoidf_(float x) { return __builtin_amdgcn_rcpf(1.0f + __expf(-x)); }
;     __device__ __forceinline__ void operator()(AccRef acc, const Unit& u, int wr, int wc, int fr, int fq) const {
;     ...
;                 f32x4 h2v = (f32x4){0.f, 0.f, 0.f, 0.f}, h3v = h2v, h2g = h2v, h3g = h2v;
;                 const int pb = ai * 2 + wr - 1;
;                 if (pb >= 0 && fr == 0) { const LAS float* xp = xch + (pb * 2) * 256 + clb + 4 * n;
;                     h2v = *(const LAS f32x4*)(xp); h3v = *(const LAS f32x4*)(xp + 256); h2g = *(const LAS f32x4*)(xp + 128); h3g = *(const LAS f32x4*)(xp + 256 + 128); }
;                 float o[4][4];
; #pragma unroll
;                 for (int j = 0; j < 4; ++j) {
;                     const float v0 = acc[ai][0][0][n][j], v1 = acc[ai][0][1][n][j], v2 = acc[ai][0][2][n][j], v3 = acc[ai][0][3][n][j];
;                     const float g0 = acc[ai][1][0][n][j], g1 = acc[ai][1][1][n][j], g2 = acc[ai][1][2][n][j], g3 = acc[ai][1][3][n][j];
;                     const float pv3 = dpp_upd<0x111>(h3v[j], v3), pv2 = dpp_upd<0x111>(h2v[j], v2), pg3 = dpp_upd<0x111>(h3g[j], g3), pg2 = dpp_upd<0x111>(h2g[j], g2);
;                     const float hv0 = bvv[j] + w2v[j] * v0 + w1v[j] * pv3 + w0v[j] * pv2, hv1 = bvv[j] + w2v[j] * v1 + w1v[j] * v0 + w0v[j] * pv3;
;                     const float hv2 = bvv[j] + w2v[j] * v2 + w1v[j] * v1 + w0v[j] * v0, hv3 = bvv[j] + w2v[j] * v3 + w1v[j] * v2 + w0v[j] * v1;
;                     const float hg0 = bvg[j] + w2g[j] * g0 + w1g[j] * pg3 + w0g[j] * pg2, hg1 = bvg[j] + w2g[j] * g1 + w1g[j] * g0 + w0g[j] * pg3;
;                     const float hg2 = bvg[j] + w2g[j] * g2 + w1g[j] * g1 + w0g[j] * g0, hg3 = bvg[j] + w2g[j] * g3 + w1g[j] * g2 + w0g[j] * g1;
;                     o[0][j] = hg0 * sigmoidf_(hg0) * hv0; o[1][j] = hg1 * sigmoidf_(hg1) * hv1; o[2][j] = hg2 * sigmoidf_(hg2) * hv2; o[3][j] = hg3 * sigmoidf_(hg3) * hv3; }
; #pragma unroll
;                 for (int m = 0; m < 4; ++m) { u32x2 w; w.x = cvt_pk_bf16(o[m][0], o[m][1]); w.y = cvt_pk_bf16(o[m][2], o[m][3]);
;                     *(u32x2*)(Aout + (size_t)(row0 + ai * 128 + m) * FH + hc0 + 4 * n) = w; } } }
.LBB0_1355:
	s_or_b64 exec, exec, s[42:43]
	s_waitcnt lgkmcnt(0)
	v_mov_b32_dpp v64, v8 row_shr:1 row_mask:0xf bank_mask:0xf
	v_mov_b32_dpp v65, v9 row_shr:1 row_mask:0xf bank_mask:0xf
	v_pk_fma_f32 v[44:45], v[24:25], v[120:121], v[124:125]
	v_mov_b32_dpp v40, v0 row_shr:1 row_mask:0xf bank_mask:0xf
	v_mov_b32_dpp v41, v1 row_shr:1 row_mask:0xf bank_mask:0xf
	v_pk_fma_f32 v[44:45], v[116:117], v[64:65], v[44:45]
	v_mov_b32_dpp v32, v20 row_shr:1 row_mask:0xf bank_mask:0xf
	v_pk_fma_f32 v[40:41], v[112:113], v[40:41], v[44:45]
	v_mov_b32_dpp v33, v21 row_shr:1 row_mask:0xf bank_mask:0xf
	v_mul_f32_e32 v44, 0xbfb8aa3b, v40
	v_mul_f32_e32 v45, 0xbfb8aa3b, v41
	v_exp_f32_e32 v44, v44
	v_exp_f32_e32 v45, v45
	v_pk_fma_f32 v[46:47], v[28:29], v[104:105], v[108:109]
	v_mov_b32_dpp v36, v12 row_shr:1 row_mask:0xf bank_mask:0xf
	v_add_f32_e32 v44, 1.0, v44
	v_add_f32_e32 v45, 1.0, v45
	v_rcp_f32_e32 v44, v44
	v_rcp_f32_e32 v45, v45
	v_mov_b32_dpp v37, v13 row_shr:1 row_mask:0xf bank_mask:0xf
	v_pk_fma_f32 v[46:47], v[100:101], v[32:33], v[46:47]
	v_mov_b32_dpp v66, v10 row_shr:1 row_mask:0xf bank_mask:0xf
	v_pk_fma_f32 v[36:37], v[96:97], v[36:37], v[46:47]
	v_pk_mul_f32 v[40:41], v[40:41], v[44:45]
	v_mov_b32_dpp v67, v11 row_shr:1 row_mask:0xf bank_mask:0xf
	v_pk_mul_f32 v[36:37], v[36:37], v[40:41]
	v_pk_fma_f32 v[40:41], v[26:27], v[122:123], v[126:127]
	v_mov_b32_dpp v42, v2 row_shr:1 row_mask:0xf bank_mask:0xf
	v_mov_b32_dpp v43, v3 row_shr:1 row_mask:0xf bank_mask:0xf
	v_pk_fma_f32 v[40:41], v[118:119], v[66:67], v[40:41]
	v_cvt_pk_bf16_f32 v36, v36, v37
	v_pk_fma_f32 v[40:41], v[114:115], v[42:43], v[40:41]
	v_mov_b32_dpp v34, v22 row_shr:1 row_mask:0xf bank_mask:0xf
	v_mul_f32_e32 v42, 0xbfb8aa3b, v40
	v_exp_f32_e32 v42, v42
	v_mul_f32_e32 v43, 0xbfb8aa3b, v41
	v_exp_f32_e32 v43, v43
	v_mov_b32_dpp v35, v23 row_shr:1 row_mask:0xf bank_mask:0xf
	v_add_f32_e32 v37, 1.0, v42
	v_rcp_f32_e32 v42, v37
	v_add_f32_e32 v37, 1.0, v43
	v_rcp_f32_e32 v43, v37
	v_pk_fma_f32 v[44:45], v[30:31], v[106:107], v[110:111]
	v_mov_b32_dpp v38, v14 row_shr:1 row_mask:0xf bank_mask:0xf
	v_mov_b32_dpp v39, v15 row_shr:1 row_mask:0xf bank_mask:0xf
	v_pk_fma_f32 v[44:45], v[102:103], v[34:35], v[44:45]
	v_pk_mul_f32 v[40:41], v[40:41], v[42:43]
	v_pk_fma_f32 v[38:39], v[98:99], v[38:39], v[44:45]
	v_pk_fma_f32 v[8:9], v[8:9], v[120:121], v[124:125]
	v_pk_mul_f32 v[38:39], v[38:39], v[40:41]
	v_pk_fma_f32 v[20:21], v[20:21], v[104:105], v[108:109]
	v_cvt_pk_bf16_f32 v37, v38, v39
	v_pk_fma_f32 v[38:39], v[4:5], v[120:121], v[124:125]
	v_mov_b32_e32 v146, v36
	v_mov_b32_e32 v147, v37
	global_store_dwordx4 v[132:133], v[144:147], off
	v_pk_fma_f32 v[38:39], v[24:25], v[116:117], v[38:39]
	s_and_b64 vcc, exec, s[14:15]
	v_pk_fma_f32 v[38:39], v[112:113], v[64:65], v[38:39]
	s_mov_b32 s43, s34
	v_mul_f32_e32 v40, 0xbfb8aa3b, v38
	v_mul_f32_e32 v41, 0xbfb8aa3b, v39
	v_exp_f32_e32 v40, v40
	v_exp_f32_e32 v41, v41
	s_mov_b32 s42, s36
	s_mov_b64 s[46:47], s[40:41]
	v_add_f32_e32 v36, 1.0, v40
	v_add_f32_e32 v37, 1.0, v41
	v_rcp_f32_e32 v36, v36
	v_rcp_f32_e32 v37, v37
	v_pk_fma_f32 v[40:41], v[16:17], v[104:105], v[108:109]
	s_mov_b64 s[44:45], s[38:39]
	v_pk_fma_f32 v[40:41], v[28:29], v[100:101], v[40:41]
	v_pk_mul_f32 v[36:37], v[38:39], v[36:37]
	v_pk_fma_f32 v[32:33], v[96:97], v[32:33], v[40:41]
	v_pk_fma_f32 v[40:41], v[18:19], v[106:107], v[110:111]
	v_pk_mul_f32 v[32:33], v[32:33], v[36:37]
	v_pk_fma_f32 v[36:37], v[6:7], v[122:123], v[126:127]
	v_cvt_pk_bf16_f32 v32, v32, v33
	v_pk_fma_f32 v[36:37], v[26:27], v[118:119], v[36:37]
	v_pk_fma_f32 v[40:41], v[30:31], v[102:103], v[40:41]
	v_pk_fma_f32 v[36:37], v[114:115], v[66:67], v[36:37]
	v_pk_fma_f32 v[34:35], v[98:99], v[34:35], v[40:41]
	v_mul_f32_e32 v38, 0xbfb8aa3b, v36
	v_exp_f32_e32 v38, v38
	v_mul_f32_e32 v39, 0xbfb8aa3b, v37
	v_exp_f32_e32 v39, v39
	v_add_f32_e32 v33, 1.0, v38
	v_rcp_f32_e32 v38, v33
	v_add_f32_e32 v33, 1.0, v39
	v_rcp_f32_e32 v39, v33
	s_nop 0
	v_pk_mul_f32 v[36:37], v[36:37], v[38:39]
	s_nop 0
	v_pk_mul_f32 v[34:35], v[34:35], v[36:37]
	s_nop 0
	v_cvt_pk_bf16_f32 v33, v34, v35
	v_pk_fma_f32 v[34:35], v[0:1], v[120:121], v[124:125]
	v_mov_b32_e32 v156, v32
	v_mov_b32_e32 v157, v33
	global_store_dwordx4 v[128:129], v[154:157], off
	v_pk_fma_f32 v[34:35], v[4:5], v[116:117], v[34:35]
	v_pk_fma_f32 v[0:1], v[0:1], v[116:117], v[8:9]
	v_pk_fma_f32 v[24:25], v[24:25], v[112:113], v[34:35]
	v_pk_fma_f32 v[0:1], v[4:5], v[112:113], v[0:1]
	v_mul_f32_e32 v34, 0xbfb8aa3b, v24
	v_mul_f32_e32 v35, 0xbfb8aa3b, v25
	v_exp_f32_e32 v34, v34
	v_exp_f32_e32 v35, v35
	v_mul_f32_e32 v4, 0xbfb8aa3b, v0
	v_exp_f32_e32 v8, v4
	v_add_f32_e32 v32, 1.0, v34
	v_add_f32_e32 v33, 1.0, v35
	v_rcp_f32_e32 v32, v32
	v_rcp_f32_e32 v33, v33
	v_pk_fma_f32 v[34:35], v[12:13], v[104:105], v[108:109]
	v_pk_fma_f32 v[4:5], v[10:11], v[122:123], v[126:127]
	v_pk_fma_f32 v[34:35], v[16:17], v[100:101], v[34:35]
	v_pk_mul_f32 v[24:25], v[24:25], v[32:33]
	v_pk_fma_f32 v[28:29], v[28:29], v[96:97], v[34:35]
	v_mul_f32_e32 v9, 0xbfb8aa3b, v1
	v_pk_mul_f32 v[24:25], v[28:29], v[24:25]
	v_pk_fma_f32 v[28:29], v[2:3], v[122:123], v[126:127]
	v_pk_fma_f32 v[2:3], v[2:3], v[118:119], v[4:5]
	v_pk_fma_f32 v[28:29], v[6:7], v[118:119], v[28:29]
	v_pk_fma_f32 v[2:3], v[6:7], v[114:115], v[2:3]
	v_pk_fma_f32 v[26:27], v[26:27], v[114:115], v[28:29]
	v_mul_f32_e32 v4, 0xbfb8aa3b, v2
	v_mul_f32_e32 v28, 0xbfb8aa3b, v26
	v_exp_f32_e32 v28, v28
	v_mul_f32_e32 v29, 0xbfb8aa3b, v27
	v_mul_f32_e32 v5, 0xbfb8aa3b, v3
	v_exp_f32_e32 v29, v29
	v_exp_f32_e32 v9, v9
	v_exp_f32_e32 v4, v4
	v_exp_f32_e32 v5, v5
	v_cvt_pk_bf16_f32 v24, v24, v25
	v_add_f32_e32 v25, 1.0, v28
	v_rcp_f32_e32 v28, v25
	v_add_f32_e32 v25, 1.0, v29
	v_add_f32_e32 v8, 1.0, v8
	v_add_f32_e32 v9, 1.0, v9
	v_add_f32_e32 v4, 1.0, v4
	v_add_f32_e32 v5, 1.0, v5
	v_rcp_f32_e32 v29, v25
	v_rcp_f32_e32 v8, v8
	v_rcp_f32_e32 v9, v9
	v_rcp_f32_e32 v4, v4
	v_rcp_f32_e32 v5, v5
	v_pk_fma_f32 v[32:33], v[14:15], v[106:107], v[110:111]
	v_pk_fma_f32 v[10:11], v[22:23], v[106:107], v[110:111]
	v_pk_fma_f32 v[32:33], v[18:19], v[102:103], v[32:33]
	v_pk_fma_f32 v[12:13], v[12:13], v[100:101], v[20:21]
	v_pk_fma_f32 v[6:7], v[14:15], v[102:103], v[10:11]
	v_pk_fma_f32 v[30:31], v[30:31], v[98:99], v[32:33]
	v_pk_mul_f32 v[26:27], v[26:27], v[28:29]
	v_pk_fma_f32 v[12:13], v[16:17], v[96:97], v[12:13]
	v_pk_mul_f32 v[0:1], v[0:1], v[8:9]
	v_pk_fma_f32 v[6:7], v[18:19], v[98:99], v[6:7]
	v_pk_mul_f32 v[2:3], v[2:3], v[4:5]
	v_pk_mul_f32 v[26:27], v[30:31], v[26:27]
	v_pk_mul_f32 v[0:1], v[12:13], v[0:1]
	v_pk_mul_f32 v[2:3], v[6:7], v[2:3]
	v_cvt_pk_bf16_f32 v25, v26, v27
	v_cvt_pk_bf16_f32 v0, v0, v1
	v_cvt_pk_bf16_f32 v1, v2, v3
	v_mov_b32_e32 v200, v24
	v_mov_b32_e32 v201, v25
	global_store_dwordx4 v[88:89], v[198:201], off
	v_mov_b32_e32 v150, v0
	v_mov_b32_e32 v151, v1
	global_store_dwordx4 v[82:83], v[148:151], off
	s_cbranch_vccnz .LBB0_1374

; #define LAS __attribute__((address_space(3)))
;     __device__ __forceinline__ void operator()(AccRef acc, const Unit& u, int wr, int wc, int fr, int fq) const {
;     ...
;         const int hc0 = 128 * u.pn + clb, row0 = u.pm * 256 + wr * 64 + 4 * fr;
; #pragma unroll
;         for (int n = 0; n < 2; ++n) {
;             const f32x4 w0v = cwv[n][0], w1v = cwv[n][1], w2v = cwv[n][2], bvv = cwv[n][3], w0g = cwv[n][4], w1g = cwv[n][5], w2g = cwv[n][6], bvg = cwv[n][7];
; #pragma unroll
;             for (int ai = 0; ai < 2; ++ai) {
;                 if (n == 0 && ai == 0) {
;                     asm volatile("" ::: "memory");
;                     const float* cv = cw + hc0 + 4; const float* cg = cv + FH; const float* bp = cb + hc0 + 4;
;                     cwv[1][0] = *(const f32x4*)(cv); cwv[1][1] = *(const f32x4*)(cv + F2); cwv[1][2] = *(const f32x4*)(cv + 2 * F2); cwv[1][3] = *(const f32x4*)(bp);
;                     cwv[1][4] = *(const f32x4*)(cg); cwv[1][5] = *(const f32x4*)(cg + F2); cwv[1][6] = *(const f32x4*)(cg + 2 * F2); cwv[1][7] = *(const f32x4*)(bp + FH);
;                     asm volatile("" ::: "memory"); }
;                 f32x4 h2v = (f32x4){0.f, 0.f, 0.f, 0.f}, h3v = h2v, h2g = h2v, h3g = h2v;
;                 const int pb = ai * 2 + wr - 1;
;                 if (pb >= 0 && fr == 0) { const LAS float* xp = xch + (pb * 2) * 256 + clb + 4 * n;
;                     h2v = *(const LAS f32x4*)(xp); h3v = *(const LAS f32x4*)(xp + 256); h2g = *(const LAS f32x4*)(xp + 128); h3g = *(const LAS f32x4*)(xp + 256 + 128); }
;                 float o[4][4];
; #pragma unroll
;                 for (int j = 0; j < 4; ++j) {
;                     const float v0 = acc[ai][0][0][n][j], v1 = acc[ai][0][1][n][j], v2 = acc[ai][0][2][n][j], v3 = acc[ai][0][3][n][j];
;                     const float g0 = acc[ai][1][0][n][j], g1 = acc[ai][1][1][n][j], g2 = acc[ai][1][2][n][j], g3 = acc[ai][1][3][n][j];
;                     const float pv3 = dpp_upd<0x111>(h3v[j], v3), pv2 = dpp_upd<0x111>(h2v[j], v2), pg3 = dpp_upd<0x111>(h3g[j], g3), pg2 = dpp_upd<0x111>(h2g[j], g2);
;                     const float hv0 = bvv[j] + w2v[j] * v0 + w1v[j] * pv3 + w0v[j] * pv2, hv1 = bvv[j] + w2v[j] * v1 + w1v[j] * v0 + w0v[j] * pv3;
;                     const float hv2 = bvv[j] + w2v[j] * v2 + w1v[j] * v1 + w0v[j] * v0, hv3 = bvv[j] + w2v[j] * v3 + w1v[j] * v2 + w0v[j] * v1;
.LBB0_1366:
	s_or_b64 exec, exec, s[48:49]
	v_pk_fma_f32 v[248:249], v[152:153], v[184:185], v[188:189]
	v_mov_b32_dpp v206, v128 row_shr:1 row_mask:0xf bank_mask:0xf
	v_mov_b32_dpp v207, v129 row_shr:1 row_mask:0xf bank_mask:0xf
	v_pk_fma_f32 v[248:249], v[180:181], v[198:199], v[248:249]
	v_mov_b32_dpp v194, v148 row_shr:1 row_mask:0xf bank_mask:0xf
	v_pk_fma_f32 v[206:207], v[176:177], v[206:207], v[248:249]
	v_mov_b32_dpp v195, v149 row_shr:1 row_mask:0xf bank_mask:0xf
	v_mul_f32_e32 v193, 0xbfb8aa3b, v206
	v_exp_f32_e32 v193, v193
	v_mul_f32_e32 v247, 0xbfb8aa3b, v207
	v_exp_f32_e32 v247, v247
	v_pk_fma_f32 v[250:251], v[156:157], v[168:169], v[172:173]
	v_add_f32_e32 v193, 1.0, v193
	v_rcp_f32_e32 v248, v193
	v_add_f32_e32 v193, 1.0, v247
	v_rcp_f32_e32 v249, v193
	v_mov_b32_dpp v202, v136 row_shr:1 row_mask:0xf bank_mask:0xf
	v_mov_b32_dpp v203, v137 row_shr:1 row_mask:0xf bank_mask:0xf
	v_pk_fma_f32 v[250:251], v[164:165], v[194:195], v[250:251]
	v_pk_mul_f32 v[206:207], v[206:207], v[248:249]
	v_pk_fma_f32 v[202:203], v[160:161], v[202:203], v[250:251]
	v_mov_b32_dpp v200, v142 row_shr:1 row_mask:0xf bank_mask:0xf
	v_mov_b32_dpp v201, v143 row_shr:1 row_mask:0xf bank_mask:0xf
	v_pk_mul_f32 v[202:203], v[202:203], v[206:207]
	v_pk_fma_f32 v[206:207], v[154:155], v[186:187], v[190:191]
	v_mov_b32_dpp v208, v130 row_shr:1 row_mask:0xf bank_mask:0xf
	v_mov_b32_dpp v209, v131 row_shr:1 row_mask:0xf bank_mask:0xf
	v_pk_fma_f32 v[206:207], v[182:183], v[200:201], v[206:207]
	v_mov_b32_dpp v196, v150 row_shr:1 row_mask:0xf bank_mask:0xf
	v_pk_fma_f32 v[206:207], v[178:179], v[208:209], v[206:207]
	v_mov_b32_dpp v197, v151 row_shr:1 row_mask:0xf bank_mask:0xf
	v_mul_f32_e32 v193, 0xbfb8aa3b, v206
	v_exp_f32_e32 v193, v193
	v_mul_f32_e32 v208, 0xbfb8aa3b, v207
	v_exp_f32_e32 v209, v208
	v_cvt_pk_bf16_f32 v208, v202, v203
	v_add_f32_e32 v193, 1.0, v193
	v_rcp_f32_e32 v202, v193
	v_add_f32_e32 v193, 1.0, v209
	v_rcp_f32_e32 v203, v193
	v_pk_fma_f32 v[248:249], v[158:159], v[170:171], v[174:175]
	v_mov_b32_dpp v204, v138 row_shr:1 row_mask:0xf bank_mask:0xf
	v_mov_b32_dpp v205, v139 row_shr:1 row_mask:0xf bank_mask:0xf
	v_pk_fma_f32 v[248:249], v[166:167], v[196:197], v[248:249]
	v_pk_mul_f32 v[202:203], v[206:207], v[202:203]
	v_pk_fma_f32 v[204:205], v[162:163], v[204:205], v[248:249]
	v_lshl_add_u32 v246, s42, 8, v236
	v_pk_mul_f32 v[202:203], v[204:205], v[202:203]
	v_lshlrev_b64 v[204:205], 1, v[232:233]
	v_pk_fma_f32 v[232:233], v[132:133], v[184:185], v[188:189]
	v_mov_b64_e32 v[206:207], s[60:61]
	v_pk_fma_f32 v[232:233], v[152:153], v[180:181], v[232:233]
	v_cvt_pk_bf16_f32 v209, v202, v203
	v_pk_fma_f32 v[198:199], v[176:177], v[198:199], v[232:233]
	v_mad_i64_i32 v[202:203], s[42:43], v246, s82, v[206:207]
	v_mul_f32_e32 v193, 0xbfb8aa3b, v198
	v_exp_f32_e32 v193, v193
	v_mul_f32_e32 v232, 0xbfb8aa3b, v199
	v_exp_f32_e32 v232, v232
	v_lshl_add_u64 v[202:203], v[202:203], 0, v[204:205]
	v_add_f32_e32 v193, 1.0, v193
	v_mov_b32_e32 v247, v208
	v_mov_b32_e32 v248, v209
	v_rcp_f32_e32 v208, v193
	v_add_f32_e32 v193, 1.0, v232
	v_rcp_f32_e32 v209, v193
	v_pk_fma_f32 v[232:233], v[144:145], v[168:169], v[172:173]
	v_pk_fma_f32 v[140:141], v[140:141], v[184:185], v[188:189]
	v_pk_fma_f32 v[232:233], v[156:157], v[164:165], v[232:233]
	v_pk_mul_f32 v[198:199], v[198:199], v[208:209]
	v_pk_fma_f32 v[194:195], v[160:161], v[194:195], v[232:233]
	v_pk_fma_f32 v[208:209], v[146:147], v[170:171], v[174:175]
	v_pk_mul_f32 v[194:195], v[194:195], v[198:199]
	v_pk_fma_f32 v[198:199], v[134:135], v[186:187], v[190:191]
	v_pk_fma_f32 v[208:209], v[158:159], v[166:167], v[208:209]
	v_pk_fma_f32 v[198:199], v[154:155], v[182:183], v[198:199]
	v_pk_fma_f32 v[196:197], v[162:163], v[196:197], v[208:209]
	v_pk_fma_f32 v[198:199], v[178:179], v[200:201], v[198:199]
	v_cvt_pk_bf16_f32 v194, v194, v195
	v_mul_f32_e32 v193, 0xbfb8aa3b, v198
	v_exp_f32_e32 v193, v193
	v_mul_f32_e32 v200, 0xbfb8aa3b, v199
	v_exp_f32_e32 v201, v200
	v_pk_fma_f32 v[148:149], v[148:149], v[168:169], v[172:173]
	v_add_f32_e32 v193, 1.0, v193
	v_rcp_f32_e32 v200, v193
	v_add_f32_e32 v193, 1.0, v201
	v_rcp_f32_e32 v201, v193
	v_or_b32_e32 v193, 1, v246
	v_pk_mul_f32 v[198:199], v[198:199], v[200:201]
	s_nop 0
	v_pk_mul_f32 v[196:197], v[196:197], v[198:199]
	v_pk_fma_f32 v[198:199], v[128:129], v[184:185], v[188:189]
	v_cvt_pk_bf16_f32 v195, v196, v197
	v_pk_fma_f32 v[198:199], v[132:133], v[180:181], v[198:199]
	v_mad_i64_i32 v[196:197], s[42:43], v193, s82, v[206:207]
	v_pk_fma_f32 v[152:153], v[152:153], v[176:177], v[198:199]
	v_lshl_add_u64 v[196:197], v[196:197], 0, v[204:205]
	v_mul_f32_e32 v193, 0xbfb8aa3b, v152
	v_exp_f32_e32 v193, v193
	v_mul_f32_e32 v198, 0xbfb8aa3b, v153
	v_exp_f32_e32 v198, v198
	v_mov_b32_e32 v249, v194
	v_mov_b32_e32 v250, v195
	v_add_f32_e32 v193, 1.0, v193
	v_rcp_f32_e32 v194, v193
	v_add_f32_e32 v193, 1.0, v198
	v_rcp_f32_e32 v195, v193
	v_pk_fma_f32 v[198:199], v[136:137], v[168:169], v[172:173]
	v_pk_fma_f32 v[128:129], v[128:129], v[180:181], v[140:141]
	v_pk_fma_f32 v[198:199], v[144:145], v[164:165], v[198:199]
	v_pk_fma_f32 v[128:129], v[132:133], v[176:177], v[128:129]
	v_pk_fma_f32 v[156:157], v[156:157], v[160:161], v[198:199]
	v_pk_mul_f32 v[152:153], v[152:153], v[194:195]
	v_mul_f32_e32 v132, 0xbfb8aa3b, v128
	v_pk_mul_f32 v[152:153], v[156:157], v[152:153]
	v_pk_fma_f32 v[156:157], v[130:131], v[186:187], v[190:191]
	v_exp_f32_e32 v140, v132
	v_pk_fma_f32 v[132:133], v[142:143], v[186:187], v[190:191]
	v_pk_fma_f32 v[156:157], v[134:135], v[182:183], v[156:157]
	v_pk_fma_f32 v[130:131], v[130:131], v[182:183], v[132:133]
; #define LAS __attribute__((address_space(3)))
; __device__ __forceinline__ float sigmoidf_(float x) { return __builtin_amdgcn_rcpf(1.0f + __expf(-x)); }
;     __device__ __forceinline__ void operator()(AccRef acc, const Unit& u, int wr, int wc, int fr, int fq) const {
;     ...
;                 f32x4 h2v = (f32x4){0.f, 0.f, 0.f, 0.f}, h3v = h2v, h2g = h2v, h3g = h2v;
;                 const int pb = ai * 2 + wr - 1;
;                 if (pb >= 0 && fr == 0) { const LAS float* xp = xch + (pb * 2) * 256 + clb + 4 * n;
;                     h2v = *(const LAS f32x4*)(xp); h3v = *(const LAS f32x4*)(xp + 256); h2g = *(const LAS f32x4*)(xp + 128); h3g = *(const LAS f32x4*)(xp + 256 + 128); }
;                 float o[4][4];
; #pragma unroll
;                 for (int j = 0; j < 4; ++j) {
;                     const float v0 = acc[ai][0][0][n][j], v1 = acc[ai][0][1][n][j], v2 = acc[ai][0][2][n][j], v3 = acc[ai][0][3][n][j];
;                     const float g0 = acc[ai][1][0][n][j], g1 = acc[ai][1][1][n][j], g2 = acc[ai][1][2][n][j], g3 = acc[ai][1][3][n][j];
;                     const float pv3 = dpp_upd<0x111>(h3v[j], v3), pv2 = dpp_upd<0x111>(h2v[j], v2), pg3 = dpp_upd<0x111>(h3g[j], g3), pg2 = dpp_upd<0x111>(h2g[j], g2);
;                     const float hv0 = bvv[j] + w2v[j] * v0 + w1v[j] * pv3 + w0v[j] * pv2, hv1 = bvv[j] + w2v[j] * v1 + w1v[j] * v0 + w0v[j] * pv3;
;                     const float hv2 = bvv[j] + w2v[j] * v2 + w1v[j] * v1 + w0v[j] * v0, hv3 = bvv[j] + w2v[j] * v3 + w1v[j] * v2 + w0v[j] * v1;
;                     const float hg0 = bvg[j] + w2g[j] * g0 + w1g[j] * pg3 + w0g[j] * pg2, hg1 = bvg[j] + w2g[j] * g1 + w1g[j] * g0 + w0g[j] * pg3;
;                     const float hg2 = bvg[j] + w2g[j] * g2 + w1g[j] * g1 + w0g[j] * g0, hg3 = bvg[j] + w2g[j] * g3 + w1g[j] * g2 + w0g[j] * g1;
;                     o[0][j] = hg0 * sigmoidf_(hg0) * hv0; o[1][j] = hg1 * sigmoidf_(hg1) * hv1; o[2][j] = hg2 * sigmoidf_(hg2) * hv2; o[3][j] = hg3 * sigmoidf_(hg3) * hv3; }
; #pragma unroll
;                 for (int m = 0; m < 4; ++m) { u32x2 w; w.x = cvt_pk_bf16(o[m][0], o[m][1]); w.y = cvt_pk_bf16(o[m][2], o[m][3]);
;                     *(u32x2*)(Aout + (size_t)(row0 + ai * 128 + m) * FH + hc0 + 4 * n) = w; } } }
	v_pk_fma_f32 v[154:155], v[154:155], v[178:179], v[156:157]
	v_pk_fma_f32 v[130:131], v[134:135], v[178:179], v[130:131]
	v_mul_f32_e32 v156, 0xbfb8aa3b, v154
	v_mul_f32_e32 v141, 0xbfb8aa3b, v129
	v_mul_f32_e32 v132, 0xbfb8aa3b, v130
	v_mul_f32_e32 v133, 0xbfb8aa3b, v131
	v_exp_f32_e32 v157, v156
	v_mul_f32_e32 v156, 0xbfb8aa3b, v155
	v_exp_f32_e32 v141, v141
	v_exp_f32_e32 v132, v132
	v_exp_f32_e32 v133, v133
	v_exp_f32_e32 v193, v156
	v_add_f32_e32 v140, 1.0, v140
	v_add_f32_e32 v141, 1.0, v141
	v_add_f32_e32 v132, 1.0, v132
	v_add_f32_e32 v133, 1.0, v133
	v_cvt_pk_bf16_f32 v156, v152, v153
	v_add_f32_e32 v152, 1.0, v157
	v_add_f32_e32 v153, 1.0, v193
	v_rcp_f32_e32 v140, v140
	v_rcp_f32_e32 v141, v141
	v_rcp_f32_e32 v132, v132
	v_rcp_f32_e32 v133, v133
	v_rcp_f32_e32 v152, v152
	v_rcp_f32_e32 v153, v153
	v_pk_fma_f32 v[142:143], v[150:151], v[170:171], v[174:175]
	v_pk_fma_f32 v[194:195], v[138:139], v[170:171], v[174:175]
	v_pk_fma_f32 v[136:137], v[136:137], v[164:165], v[148:149]
	v_pk_fma_f32 v[134:135], v[138:139], v[166:167], v[142:143]
	v_pk_fma_f32 v[194:195], v[146:147], v[166:167], v[194:195]
	v_pk_fma_f32 v[136:137], v[144:145], v[160:161], v[136:137]
	v_pk_mul_f32 v[128:129], v[128:129], v[140:141]
	v_pk_fma_f32 v[134:135], v[146:147], v[162:163], v[134:135]
	v_pk_mul_f32 v[130:131], v[130:131], v[132:133]
	v_pk_fma_f32 v[158:159], v[158:159], v[162:163], v[194:195]
	v_pk_mul_f32 v[152:153], v[154:155], v[152:153]
	v_pk_mul_f32 v[128:129], v[136:137], v[128:129]
	v_pk_mul_f32 v[130:131], v[134:135], v[130:131]
	v_pk_mul_f32 v[152:153], v[158:159], v[152:153]
	v_cvt_pk_bf16_f32 v128, v128, v129
	v_cvt_pk_bf16_f32 v129, v130, v131
	v_or_b32_e32 v130, 3, v246
	v_cvt_pk_bf16_f32 v157, v152, v153
	v_or_b32_e32 v152, 2, v246
	v_mad_i64_i32 v[130:131], s[42:43], v130, s82, v[206:207]
	v_mad_i64_i32 v[152:153], s[42:43], v152, s82, v[206:207]
	v_lshl_add_u64 v[140:141], v[130:131], 0, v[204:205]
	v_lshl_add_u64 v[152:153], v[152:153], 0, v[204:205]
	v_mov_b32_e32 v251, v128
	v_mov_b32_e32 v253, v129
	v_mov_b32_e32 v193, 0
	v_mov_b32_e32 v194, 0
	v_mov_b32_e32 v195, 0
	v_mov_b32_e32 v136, 0
	v_mov_b32_e32 v137, 0
	v_mov_b32_e32 v138, 0
	v_mov_b32_e32 v139, 0
	v_mov_b32_e32 v128, 0
	v_mov_b32_e32 v129, 0
	v_mov_b32_e32 v130, 0
	v_mov_b32_e32 v131, 0
	v_mov_b32_e32 v132, 0
	v_mov_b32_e32 v133, 0
	v_mov_b32_e32 v134, 0
	v_mov_b32_e32 v135, 0
	v_mov_b32_e32 v254, v156
	v_mov_b32_e32 v255, v157
	s_and_saveexec_b64 s[42:43], s[30:31]
	s_cbranch_execz .LBB0_1370
	ds_read_b128 v[132:135], v237 offset:2048
	ds_read_b128 v[136:139], v237 offset:2560
	ds_read_b128 v[128:131], v237 offset:3072
	ds_read_b128 v[192:195], v237 offset:3584
.LBB0_1370:
	s_or_b64 exec, exec, s[42:43]
	s_waitcnt lgkmcnt(0)
	v_mov_b32_dpp v192, v72 row_shr:1 row_mask:0xf bank_mask:0xf
	v_mov_b32_dpp v193, v73 row_shr:1 row_mask:0xf bank_mask:0xf
	v_pk_fma_f32 v[142:143], v[88:89], v[184:185], v[188:189]
	v_mov_b32_dpp v136, v64 row_shr:1 row_mask:0xf bank_mask:0xf
	v_mov_b32_dpp v137, v65 row_shr:1 row_mask:0xf bank_mask:0xf
	v_pk_fma_f32 v[142:143], v[180:181], v[192:193], v[142:143]
	v_mov_b32_dpp v128, v84 row_shr:1 row_mask:0xf bank_mask:0xf
	v_pk_fma_f32 v[136:137], v[176:177], v[136:137], v[142:143]
	v_mov_b32_dpp v129, v85 row_shr:1 row_mask:0xf bank_mask:0xf
	v_mul_f32_e32 v142, 0xbfb8aa3b, v136
	v_mul_f32_e32 v143, 0xbfb8aa3b, v137
	v_exp_f32_e32 v142, v142
	v_exp_f32_e32 v143, v143
	v_pk_fma_f32 v[144:145], v[92:93], v[168:169], v[172:173]
	v_mov_b32_dpp v132, v76 row_shr:1 row_mask:0xf bank_mask:0xf
	v_add_f32_e32 v142, 1.0, v142
	v_add_f32_e32 v143, 1.0, v143
	v_rcp_f32_e32 v142, v142
	v_rcp_f32_e32 v143, v143
	v_mov_b32_dpp v133, v77 row_shr:1 row_mask:0xf bank_mask:0xf
	v_pk_fma_f32 v[144:145], v[164:165], v[128:129], v[144:145]
	v_mov_b32_dpp v194, v74 row_shr:1 row_mask:0xf bank_mask:0xf
	v_pk_fma_f32 v[132:133], v[160:161], v[132:133], v[144:145]
	v_pk_mul_f32 v[136:137], v[136:137], v[142:143]
	v_mov_b32_dpp v195, v75 row_shr:1 row_mask:0xf bank_mask:0xf
	v_pk_mul_f32 v[132:133], v[132:133], v[136:137]
	v_pk_fma_f32 v[136:137], v[90:91], v[186:187], v[190:191]
	v_mov_b32_dpp v138, v66 row_shr:1 row_mask:0xf bank_mask:0xf
	v_mov_b32_dpp v139, v67 row_shr:1 row_mask:0xf bank_mask:0xf
	v_pk_fma_f32 v[136:137], v[182:183], v[194:195], v[136:137]
	v_mov_b32_dpp v130, v86 row_shr:1 row_mask:0xf bank_mask:0xf
	v_pk_fma_f32 v[136:137], v[178:179], v[138:139], v[136:137]
	v_mov_b32_dpp v131, v87 row_shr:1 row_mask:0xf bank_mask:0xf
	v_mul_f32_e32 v138, 0xbfb8aa3b, v136
	v_exp_f32_e32 v139, v138
	v_mul_f32_e32 v138, 0xbfb8aa3b, v137
	v_exp_f32_e32 v142, v138
	v_cvt_pk_bf16_f32 v138, v132, v133
	v_add_f32_e32 v132, 1.0, v139
	v_rcp_f32_e32 v132, v132
	v_add_f32_e32 v133, 1.0, v142
	v_rcp_f32_e32 v133, v133
	v_pk_fma_f32 v[142:143], v[94:95], v[170:171], v[174:175]
	v_mov_b32_dpp v134, v78 row_shr:1 row_mask:0xf bank_mask:0xf
	v_mov_b32_dpp v135, v79 row_shr:1 row_mask:0xf bank_mask:0xf
	v_pk_mul_f32 v[132:133], v[136:137], v[132:133]
	v_pk_fma_f32 v[136:137], v[68:69], v[184:185], v[188:189]
	v_pk_fma_f32 v[142:143], v[166:167], v[130:131], v[142:143]
	v_pk_fma_f32 v[136:137], v[88:89], v[180:181], v[136:137]
	v_pk_fma_f32 v[134:135], v[162:163], v[134:135], v[142:143]
	v_pk_fma_f32 v[136:137], v[176:177], v[192:193], v[136:137]
	v_add_u32_e32 v146, 0x80, v246
	v_mul_f32_e32 v142, 0xbfb8aa3b, v136
	v_mul_f32_e32 v143, 0xbfb8aa3b, v137
	v_exp_f32_e32 v142, v142
	v_exp_f32_e32 v143, v143
	v_pk_mul_f32 v[132:133], v[134:135], v[132:133]
	v_mov_b64_e32 v[134:135], s[60:61]
	v_cvt_pk_bf16_f32 v139, v132, v133
	v_mad_i64_i32 v[132:133], s[42:43], v146, s82, v[134:135]
; #define LAS __attribute__((address_space(3)))
; __device__ __forceinline__ float sigmoidf_(float x) { return __builtin_amdgcn_rcpf(1.0f + __expf(-x)); }
;     __device__ __forceinline__ void operator()(AccRef acc, const Unit& u, int wr, int wc, int fr, int fq) const {
;     ...
;                 f32x4 h2v = (f32x4){0.f, 0.f, 0.f, 0.f}, h3v = h2v, h2g = h2v, h3g = h2v;
;                 const int pb = ai * 2 + wr - 1;
;                 if (pb >= 0 && fr == 0) { const LAS float* xp = xch + (pb * 2) * 256 + clb + 4 * n;
;                     h2v = *(const LAS f32x4*)(xp); h3v = *(const LAS f32x4*)(xp + 256); h2g = *(const LAS f32x4*)(xp + 128); h3g = *(const LAS f32x4*)(xp + 256 + 128); }
;                 float o[4][4];
; #pragma unroll
;                 for (int j = 0; j < 4; ++j) {
;                     const float v0 = acc[ai][0][0][n][j], v1 = acc[ai][0][1][n][j], v2 = acc[ai][0][2][n][j], v3 = acc[ai][0][3][n][j];
;                     const float g0 = acc[ai][1][0][n][j], g1 = acc[ai][1][1][n][j], g2 = acc[ai][1][2][n][j], g3 = acc[ai][1][3][n][j];
;                     const float pv3 = dpp_upd<0x111>(h3v[j], v3), pv2 = dpp_upd<0x111>(h2v[j], v2), pg3 = dpp_upd<0x111>(h3g[j], g3), pg2 = dpp_upd<0x111>(h2g[j], g2);
;                     const float hv0 = bvv[j] + w2v[j] * v0 + w1v[j] * pv3 + w0v[j] * pv2, hv1 = bvv[j] + w2v[j] * v1 + w1v[j] * v0 + w0v[j] * pv3;
;                     const float hv2 = bvv[j] + w2v[j] * v2 + w1v[j] * v1 + w0v[j] * v0, hv3 = bvv[j] + w2v[j] * v3 + w1v[j] * v2 + w0v[j] * v1;
;                     const float hg0 = bvg[j] + w2g[j] * g0 + w1g[j] * pg3 + w0g[j] * pg2, hg1 = bvg[j] + w2g[j] * g1 + w1g[j] * g0 + w0g[j] * pg3;
;                     const float hg2 = bvg[j] + w2g[j] * g2 + w1g[j] * g1 + w0g[j] * g0, hg3 = bvg[j] + w2g[j] * g3 + w1g[j] * g2 + w0g[j] * g1;
;                     o[0][j] = hg0 * sigmoidf_(hg0) * hv0; o[1][j] = hg1 * sigmoidf_(hg1) * hv1; o[2][j] = hg2 * sigmoidf_(hg2) * hv2; o[3][j] = hg3 * sigmoidf_(hg3) * hv3; }
; #pragma unroll
;                 for (int m = 0; m < 4; ++m) { u32x2 w; w.x = cvt_pk_bf16(o[m][0], o[m][1]); w.y = cvt_pk_bf16(o[m][2], o[m][3]);
;                     *(u32x2*)(Aout + (size_t)(row0 + ai * 128 + m) * FH + hc0 + 4 * n) = w; } } }
	v_lshl_add_u64 v[132:133], v[132:133], 0, v[204:205]
	v_mov_b32_e32 v144, v138
	v_mov_b32_e32 v145, v139
	v_add_f32_e32 v138, 1.0, v142
	v_add_f32_e32 v139, 1.0, v143
	v_rcp_f32_e32 v138, v138
	v_rcp_f32_e32 v139, v139
	v_pk_fma_f32 v[142:143], v[80:81], v[168:169], v[172:173]
	v_pk_fma_f32 v[72:73], v[72:73], v[184:185], v[188:189]
	v_pk_fma_f32 v[142:143], v[92:93], v[164:165], v[142:143]
	v_pk_mul_f32 v[136:137], v[136:137], v[138:139]
	v_pk_fma_f32 v[128:129], v[160:161], v[128:129], v[142:143]
	v_pk_fma_f32 v[84:85], v[84:85], v[168:169], v[172:173]
	v_pk_mul_f32 v[128:129], v[128:129], v[136:137]
	v_pk_fma_f32 v[136:137], v[70:71], v[186:187], v[190:191]
	s_nop 0
	v_pk_fma_f32 v[136:137], v[90:91], v[182:183], v[136:137]
	s_nop 0
	v_pk_fma_f32 v[136:137], v[178:179], v[194:195], v[136:137]
	s_nop 0
	v_mul_f32_e32 v138, 0xbfb8aa3b, v136
	v_exp_f32_e32 v139, v138
	v_mul_f32_e32 v138, 0xbfb8aa3b, v137
	v_exp_f32_e32 v142, v138
	v_cvt_pk_bf16_f32 v138, v128, v129
	v_add_f32_e32 v128, 1.0, v139
	v_rcp_f32_e32 v128, v128
	v_add_f32_e32 v129, 1.0, v142
	v_rcp_f32_e32 v129, v129
	v_pk_fma_f32 v[142:143], v[82:83], v[170:171], v[174:175]
	v_pk_mul_f32 v[128:129], v[136:137], v[128:129]
	v_pk_fma_f32 v[142:143], v[94:95], v[166:167], v[142:143]
	v_pk_fma_f32 v[136:137], v[76:77], v[168:169], v[172:173]
	v_pk_fma_f32 v[130:131], v[162:163], v[130:131], v[142:143]
	v_pk_fma_f32 v[136:137], v[80:81], v[164:165], v[136:137]
	v_pk_mul_f32 v[128:129], v[130:131], v[128:129]
	v_pk_fma_f32 v[130:131], v[64:65], v[184:185], v[188:189]
	v_pk_fma_f32 v[64:65], v[64:65], v[180:181], v[72:73]
	v_pk_fma_f32 v[130:131], v[68:69], v[180:181], v[130:131]
	v_pk_fma_f32 v[64:65], v[68:69], v[176:177], v[64:65]
	v_pk_fma_f32 v[88:89], v[88:89], v[176:177], v[130:131]
	v_pk_fma_f32 v[92:93], v[92:93], v[160:161], v[136:137]
	v_mul_f32_e32 v130, 0xbfb8aa3b, v88
	v_mul_f32_e32 v131, 0xbfb8aa3b, v89
	v_exp_f32_e32 v130, v130
	v_exp_f32_e32 v131, v131
	v_mul_f32_e32 v68, 0xbfb8aa3b, v64
	v_exp_f32_e32 v72, v68
	v_add_f32_e32 v130, 1.0, v130
	v_add_f32_e32 v131, 1.0, v131
	v_rcp_f32_e32 v130, v130
	v_rcp_f32_e32 v131, v131
	v_pk_fma_f32 v[68:69], v[74:75], v[186:187], v[190:191]
	v_mul_f32_e32 v73, 0xbfb8aa3b, v65
	v_exp_f32_e32 v73, v73
	v_pk_mul_f32 v[88:89], v[88:89], v[130:131]
	v_add_f32_e32 v72, 1.0, v72
	v_pk_mul_f32 v[88:89], v[92:93], v[88:89]
	v_pk_fma_f32 v[92:93], v[66:67], v[186:187], v[190:191]
	v_pk_fma_f32 v[66:67], v[66:67], v[182:183], v[68:69]
	v_pk_fma_f32 v[92:93], v[70:71], v[182:183], v[92:93]
	v_pk_fma_f32 v[66:67], v[70:71], v[178:179], v[66:67]
	v_pk_fma_f32 v[90:91], v[90:91], v[178:179], v[92:93]
	v_mul_f32_e32 v68, 0xbfb8aa3b, v66
	v_mul_f32_e32 v92, 0xbfb8aa3b, v90
	v_mul_f32_e32 v69, 0xbfb8aa3b, v67
	v_exp_f32_e32 v93, v92
	v_mul_f32_e32 v92, 0xbfb8aa3b, v91
	v_exp_f32_e32 v68, v68
	v_exp_f32_e32 v69, v69
	v_exp_f32_e32 v130, v92
	v_add_f32_e32 v73, 1.0, v73
	v_add_f32_e32 v68, 1.0, v68
	v_add_f32_e32 v69, 1.0, v69
	v_cvt_pk_bf16_f32 v92, v88, v89
	v_add_f32_e32 v88, 1.0, v93
	v_add_f32_e32 v89, 1.0, v130
	v_rcp_f32_e32 v72, v72
	v_rcp_f32_e32 v73, v73
	v_rcp_f32_e32 v68, v68
	v_rcp_f32_e32 v69, v69
	v_rcp_f32_e32 v88, v88
	v_rcp_f32_e32 v89, v89
	v_pk_fma_f32 v[74:75], v[86:87], v[170:171], v[174:175]
	v_pk_fma_f32 v[130:131], v[78:79], v[170:171], v[174:175]
	v_pk_fma_f32 v[76:77], v[76:77], v[164:165], v[84:85]
	v_pk_fma_f32 v[70:71], v[78:79], v[166:167], v[74:75]
	v_pk_fma_f32 v[130:131], v[82:83], v[166:167], v[130:131]
	v_pk_fma_f32 v[76:77], v[80:81], v[160:161], v[76:77]
	v_pk_mul_f32 v[64:65], v[64:65], v[72:73]
	v_pk_fma_f32 v[70:71], v[82:83], v[162:163], v[70:71]
	v_pk_mul_f32 v[66:67], v[66:67], v[68:69]
	v_pk_fma_f32 v[94:95], v[94:95], v[162:163], v[130:131]
	v_pk_mul_f32 v[88:89], v[90:91], v[88:89]
	v_pk_mul_f32 v[64:65], v[76:77], v[64:65]
	v_pk_mul_f32 v[66:67], v[70:71], v[66:67]
	v_pk_mul_f32 v[88:89], v[94:95], v[88:89]
	v_cvt_pk_bf16_f32 v64, v64, v65
	v_cvt_pk_bf16_f32 v65, v66, v67
	v_add_u32_e32 v66, 0x83, v246
	v_cvt_pk_bf16_f32 v139, v128, v129
	v_add_u32_e32 v128, 0x81, v246
	v_cvt_pk_bf16_f32 v93, v88, v89
	v_add_u32_e32 v88, 0x82, v246
	v_mad_i64_i32 v[66:67], s[42:43], v66, s82, v[134:135]
	v_mad_i64_i32 v[128:129], s[42:43], v128, s82, v[134:135]
	v_mad_i64_i32 v[88:89], s[42:43], v88, s82, v[134:135]
	v_lshl_add_u64 v[82:83], v[66:67], 0, v[204:205]
	v_lshl_add_u64 v[128:129], v[128:129], 0, v[204:205]
	v_lshl_add_u64 v[88:89], v[88:89], 0, v[204:205]
	v_mov_b32_e32 v148, v64
	v_mov_b32_e32 v149, v65
	v_mov_b32_e32 v64, 0
	v_mov_b32_e32 v70, 0
	v_mov_b32_e32 v71, 0
	v_mov_b32_e32 v72, 0
	v_mov_b32_e32 v73, 0
	v_mov_b32_e32 v78, 0
	v_mov_b32_e32 v79, 0
	v_mov_b32_e32 v80, 0
	v_mov_b32_e32 v81, 0
	v_mov_b32_e32 v66, 0
	v_mov_b32_e32 v67, 0
	v_mov_b32_e32 v68, 0
	v_mov_b32_e32 v69, 0
	v_mov_b32_e32 v74, 0
	v_mov_b32_e32 v75, 0
	v_mov_b32_e32 v76, 0
	v_mov_b32_e32 v77, 0
	v_mov_b32_e32 v154, v138
	v_mov_b32_e32 v155, v139
	v_mov_b32_e32 v198, v92
	v_mov_b32_e32 v199, v93
	s_and_saveexec_b64 s[42:43], s[28:29]
	s_cbranch_execz .LBB0_1372
	ds_read_b128 v[74:77], v242
	ds_read_b128 v[66:69], v241
	ds_read_b128 v[78:81], v240
	ds_read_b128 v[70:73], v239
; #define LAS __attribute__((address_space(3)))
; __device__ __forceinline__ float sigmoidf_(float x) { return __builtin_amdgcn_rcpf(1.0f + __expf(-x)); }
;     __device__ __forceinline__ void operator()(AccRef acc, const Unit& u, int wr, int wc, int fr, int fq) const {
;     ...
;                 f32x4 h2v = (f32x4){0.f, 0.f, 0.f, 0.f}, h3v = h2v, h2g = h2v, h3g = h2v;
;                 const int pb = ai * 2 + wr - 1;
;                 if (pb >= 0 && fr == 0) { const LAS float* xp = xch + (pb * 2) * 256 + clb + 4 * n;
;                     h2v = *(const LAS f32x4*)(xp); h3v = *(const LAS f32x4*)(xp + 256); h2g = *(const LAS f32x4*)(xp + 128); h3g = *(const LAS f32x4*)(xp + 256 + 128); }
;                 float o[4][4];
; #pragma unroll
;                 for (int j = 0; j < 4; ++j) {
;                     const float v0 = acc[ai][0][0][n][j], v1 = acc[ai][0][1][n][j], v2 = acc[ai][0][2][n][j], v3 = acc[ai][0][3][n][j];
;                     const float g0 = acc[ai][1][0][n][j], g1 = acc[ai][1][1][n][j], g2 = acc[ai][1][2][n][j], g3 = acc[ai][1][3][n][j];
;                     const float pv3 = dpp_upd<0x111>(h3v[j], v3), pv2 = dpp_upd<0x111>(h2v[j], v2), pg3 = dpp_upd<0x111>(h3g[j], g3), pg2 = dpp_upd<0x111>(h2g[j], g2);
;                     const float hv0 = bvv[j] + w2v[j] * v0 + w1v[j] * pv3 + w0v[j] * pv2, hv1 = bvv[j] + w2v[j] * v1 + w1v[j] * v0 + w0v[j] * pv3;
;                     const float hv2 = bvv[j] + w2v[j] * v2 + w1v[j] * v1 + w0v[j] * v0, hv3 = bvv[j] + w2v[j] * v3 + w1v[j] * v2 + w0v[j] * v1;
;                     const float hg0 = bvg[j] + w2g[j] * g0 + w1g[j] * pg3 + w0g[j] * pg2, hg1 = bvg[j] + w2g[j] * g1 + w1g[j] * g0 + w0g[j] * pg3;
;                     const float hg2 = bvg[j] + w2g[j] * g2 + w1g[j] * g1 + w0g[j] * g0, hg3 = bvg[j] + w2g[j] * g3 + w1g[j] * g2 + w0g[j] * g1;
;                     o[0][j] = hg0 * sigmoidf_(hg0) * hv0; o[1][j] = hg1 * sigmoidf_(hg1) * hv1; o[2][j] = hg2 * sigmoidf_(hg2) * hv2; o[3][j] = hg3 * sigmoidf_(hg3) * hv3; }
; #pragma unroll
;                 for (int m = 0; m < 4; ++m) { u32x2 w; w.x = cvt_pk_bf16(o[m][0], o[m][1]); w.y = cvt_pk_bf16(o[m][2], o[m][3]);
;                     *(u32x2*)(Aout + (size_t)(row0 + ai * 128 + m) * FH + hc0 + 4 * n) = w; } } }
.LBB0_1372:
	s_or_b64 exec, exec, s[42:43]
	s_waitcnt lgkmcnt(0)
	v_mov_b32_dpp v70, v44 row_shr:1 row_mask:0xf bank_mask:0xf
	v_mov_b32_dpp v71, v45 row_shr:1 row_mask:0xf bank_mask:0xf
	s_waitcnt vmcnt(0)
	v_pk_fma_f32 v[84:85], v[56:57], v[120:121], v[124:125]
	v_mov_b32_dpp v78, v32 row_shr:1 row_mask:0xf bank_mask:0xf
	v_mov_b32_dpp v79, v33 row_shr:1 row_mask:0xf bank_mask:0xf
	v_pk_fma_f32 v[84:85], v[116:117], v[70:71], v[84:85]
	v_mov_b32_dpp v66, v52 row_shr:1 row_mask:0xf bank_mask:0xf
	v_pk_fma_f32 v[78:79], v[112:113], v[78:79], v[84:85]
	v_mov_b32_dpp v67, v53 row_shr:1 row_mask:0xf bank_mask:0xf
	v_mul_f32_e32 v65, 0xbfb8aa3b, v78
	v_exp_f32_e32 v65, v65
	v_mul_f32_e32 v84, 0xbfb8aa3b, v79
	v_exp_f32_e32 v85, v84
	v_pk_fma_f32 v[86:87], v[60:61], v[104:105], v[108:109]
	v_add_f32_e32 v65, 1.0, v65
	v_rcp_f32_e32 v84, v65
	v_add_f32_e32 v65, 1.0, v85
	v_rcp_f32_e32 v85, v65
	v_mov_b32_dpp v74, v40 row_shr:1 row_mask:0xf bank_mask:0xf
	v_mov_b32_dpp v75, v41 row_shr:1 row_mask:0xf bank_mask:0xf
	v_pk_fma_f32 v[86:87], v[100:101], v[66:67], v[86:87]
	v_pk_mul_f32 v[78:79], v[78:79], v[84:85]
	v_pk_fma_f32 v[74:75], v[96:97], v[74:75], v[86:87]
	v_mov_b32_dpp v72, v46 row_shr:1 row_mask:0xf bank_mask:0xf
	v_mov_b32_dpp v73, v47 row_shr:1 row_mask:0xf bank_mask:0xf
	v_pk_mul_f32 v[74:75], v[74:75], v[78:79]
	v_pk_fma_f32 v[78:79], v[58:59], v[122:123], v[126:127]
	v_mov_b32_dpp v80, v34 row_shr:1 row_mask:0xf bank_mask:0xf
	v_mov_b32_dpp v81, v35 row_shr:1 row_mask:0xf bank_mask:0xf
	v_pk_fma_f32 v[78:79], v[118:119], v[72:73], v[78:79]
	v_mov_b32_dpp v68, v54 row_shr:1 row_mask:0xf bank_mask:0xf
	v_pk_fma_f32 v[78:79], v[114:115], v[80:81], v[78:79]
	v_mov_b32_dpp v69, v55 row_shr:1 row_mask:0xf bank_mask:0xf
	v_mul_f32_e32 v65, 0xbfb8aa3b, v78
	v_exp_f32_e32 v65, v65
	v_mul_f32_e32 v80, 0xbfb8aa3b, v79
	v_exp_f32_e32 v81, v80
	v_pk_fma_f32 v[84:85], v[62:63], v[106:107], v[110:111]
	v_add_f32_e32 v65, 1.0, v65
	v_rcp_f32_e32 v80, v65
	v_add_f32_e32 v65, 1.0, v81
	v_rcp_f32_e32 v81, v65
	v_mov_b32_dpp v76, v42 row_shr:1 row_mask:0xf bank_mask:0xf
	v_mov_b32_dpp v77, v43 row_shr:1 row_mask:0xf bank_mask:0xf
	v_pk_fma_f32 v[84:85], v[102:103], v[68:69], v[84:85]
	v_pk_mul_f32 v[78:79], v[78:79], v[80:81]
	v_pk_fma_f32 v[76:77], v[98:99], v[76:77], v[84:85]
	v_cvt_pk_bf16_f32 v74, v74, v75
	v_pk_mul_f32 v[76:77], v[76:77], v[78:79]
	v_pk_fma_f32 v[44:45], v[44:45], v[120:121], v[124:125]
	v_cvt_pk_bf16_f32 v75, v76, v77
	v_pk_fma_f32 v[76:77], v[36:37], v[120:121], v[124:125]
	v_mov_b32_e32 v90, v247
	v_mov_b32_e32 v91, v248
	v_mov_b32_e32 v92, v74
	v_mov_b32_e32 v93, v75
	global_store_dwordx4 v[202:203], v[90:93], off
	v_pk_fma_f32 v[76:77], v[56:57], v[116:117], v[76:77]
	v_pk_fma_f32 v[52:53], v[52:53], v[104:105], v[108:109]
	v_pk_fma_f32 v[70:71], v[112:113], v[70:71], v[76:77]
	s_nop 0
	v_mul_f32_e32 v65, 0xbfb8aa3b, v70
	v_exp_f32_e32 v65, v65
	v_mul_f32_e32 v76, 0xbfb8aa3b, v71
	v_exp_f32_e32 v76, v76
	v_add_f32_e32 v65, 1.0, v65
	v_rcp_f32_e32 v74, v65
	v_add_f32_e32 v65, 1.0, v76
	v_rcp_f32_e32 v75, v65
	v_pk_fma_f32 v[76:77], v[48:49], v[104:105], v[108:109]
	v_pk_mul_f32 v[70:71], v[70:71], v[74:75]
	v_pk_fma_f32 v[76:77], v[60:61], v[100:101], v[76:77]
	v_pk_fma_f32 v[74:75], v[50:51], v[106:107], v[110:111]
	v_pk_fma_f32 v[66:67], v[96:97], v[66:67], v[76:77]
	v_pk_fma_f32 v[74:75], v[62:63], v[102:103], v[74:75]
	v_pk_mul_f32 v[66:67], v[66:67], v[70:71]
	v_pk_fma_f32 v[70:71], v[38:39], v[122:123], v[126:127]
	v_pk_fma_f32 v[68:69], v[98:99], v[68:69], v[74:75]
	v_pk_fma_f32 v[70:71], v[58:59], v[118:119], v[70:71]
	v_cvt_pk_bf16_f32 v66, v66, v67
	v_pk_fma_f32 v[70:71], v[114:115], v[72:73], v[70:71]
	s_nop 0
	v_mul_f32_e32 v65, 0xbfb8aa3b, v70
	v_exp_f32_e32 v65, v65
	v_mul_f32_e32 v72, 0xbfb8aa3b, v71
	v_exp_f32_e32 v73, v72
	v_add_f32_e32 v65, 1.0, v65
; #define LAS __attribute__((address_space(3)))
; __device__ __forceinline__ float sigmoidf_(float x) { return __builtin_amdgcn_rcpf(1.0f + __expf(-x)); }
;     __device__ __forceinline__ void operator()(AccRef acc, const Unit& u, int wr, int wc, int fr, int fq) const {
;     ...
;                 f32x4 h2v = (f32x4){0.f, 0.f, 0.f, 0.f}, h3v = h2v, h2g = h2v, h3g = h2v;
;                 const int pb = ai * 2 + wr - 1;
;                 if (pb >= 0 && fr == 0) { const LAS float* xp = xch + (pb * 2) * 256 + clb + 4 * n;
;                     h2v = *(const LAS f32x4*)(xp); h3v = *(const LAS f32x4*)(xp + 256); h2g = *(const LAS f32x4*)(xp + 128); h3g = *(const LAS f32x4*)(xp + 256 + 128); }
;                 float o[4][4];
; #pragma unroll
;                 for (int j = 0; j < 4; ++j) {
;                     const float v0 = acc[ai][0][0][n][j], v1 = acc[ai][0][1][n][j], v2 = acc[ai][0][2][n][j], v3 = acc[ai][0][3][n][j];
;                     const float g0 = acc[ai][1][0][n][j], g1 = acc[ai][1][1][n][j], g2 = acc[ai][1][2][n][j], g3 = acc[ai][1][3][n][j];
;                     const float pv3 = dpp_upd<0x111>(h3v[j], v3), pv2 = dpp_upd<0x111>(h2v[j], v2), pg3 = dpp_upd<0x111>(h3g[j], g3), pg2 = dpp_upd<0x111>(h2g[j], g2);
;                     const float hv0 = bvv[j] + w2v[j] * v0 + w1v[j] * pv3 + w0v[j] * pv2, hv1 = bvv[j] + w2v[j] * v1 + w1v[j] * v0 + w0v[j] * pv3;
;                     const float hv2 = bvv[j] + w2v[j] * v2 + w1v[j] * v1 + w0v[j] * v0, hv3 = bvv[j] + w2v[j] * v3 + w1v[j] * v2 + w0v[j] * v1;
;                     const float hg0 = bvg[j] + w2g[j] * g0 + w1g[j] * pg3 + w0g[j] * pg2, hg1 = bvg[j] + w2g[j] * g1 + w1g[j] * g0 + w0g[j] * pg3;
;                     const float hg2 = bvg[j] + w2g[j] * g2 + w1g[j] * g1 + w0g[j] * g0, hg3 = bvg[j] + w2g[j] * g3 + w1g[j] * g2 + w0g[j] * g1;
;                     o[0][j] = hg0 * sigmoidf_(hg0) * hv0; o[1][j] = hg1 * sigmoidf_(hg1) * hv1; o[2][j] = hg2 * sigmoidf_(hg2) * hv2; o[3][j] = hg3 * sigmoidf_(hg3) * hv3; }
; #pragma unroll
;                 for (int m = 0; m < 4; ++m) { u32x2 w; w.x = cvt_pk_bf16(o[m][0], o[m][1]); w.y = cvt_pk_bf16(o[m][2], o[m][3]);
;                     *(u32x2*)(Aout + (size_t)(row0 + ai * 128 + m) * FH + hc0 + 4 * n) = w; } } }
	v_rcp_f32_e32 v72, v65
	v_add_f32_e32 v65, 1.0, v73
	v_rcp_f32_e32 v73, v65
	s_nop 0
	v_pk_mul_f32 v[70:71], v[70:71], v[72:73]
	s_nop 0
	v_pk_mul_f32 v[68:69], v[68:69], v[70:71]
	s_nop 0
	v_cvt_pk_bf16_f32 v67, v68, v69
	v_pk_fma_f32 v[68:69], v[32:33], v[120:121], v[124:125]
	v_mov_b32_e32 v134, v249
	v_mov_b32_e32 v135, v250
	v_mov_b32_e32 v136, v66
	v_mov_b32_e32 v137, v67
	global_store_dwordx4 v[196:197], v[134:137], off
	v_pk_fma_f32 v[68:69], v[36:37], v[116:117], v[68:69]
	v_pk_fma_f32 v[32:33], v[32:33], v[116:117], v[44:45]
	v_pk_fma_f32 v[56:57], v[56:57], v[112:113], v[68:69]
	v_pk_fma_f32 v[32:33], v[36:37], v[112:113], v[32:33]
	v_mul_f32_e32 v65, 0xbfb8aa3b, v56
	v_exp_f32_e32 v65, v65
	v_mul_f32_e32 v68, 0xbfb8aa3b, v57
	v_exp_f32_e32 v68, v68
	v_mul_f32_e32 v36, 0xbfb8aa3b, v32
	v_add_f32_e32 v65, 1.0, v65
	v_rcp_f32_e32 v66, v65
	v_add_f32_e32 v65, 1.0, v68
	v_rcp_f32_e32 v67, v65
	v_pk_fma_f32 v[68:69], v[40:41], v[104:105], v[108:109]
	v_exp_f32_e32 v44, v36
	v_pk_fma_f32 v[68:69], v[48:49], v[100:101], v[68:69]
	v_pk_mul_f32 v[56:57], v[56:57], v[66:67]
	v_pk_fma_f32 v[60:61], v[60:61], v[96:97], v[68:69]
	v_pk_fma_f32 v[36:37], v[46:47], v[122:123], v[126:127]
	v_pk_mul_f32 v[56:57], v[60:61], v[56:57]
	v_pk_fma_f32 v[60:61], v[34:35], v[122:123], v[126:127]
	v_pk_fma_f32 v[34:35], v[34:35], v[118:119], v[36:37]
	v_pk_fma_f32 v[60:61], v[38:39], v[118:119], v[60:61]
	v_pk_fma_f32 v[34:35], v[38:39], v[114:115], v[34:35]
	v_pk_fma_f32 v[58:59], v[58:59], v[114:115], v[60:61]
	v_mul_f32_e32 v45, 0xbfb8aa3b, v33
	v_mul_f32_e32 v60, 0xbfb8aa3b, v58
	v_mul_f32_e32 v36, 0xbfb8aa3b, v34
	v_mul_f32_e32 v37, 0xbfb8aa3b, v35
	v_exp_f32_e32 v60, v60
	v_mul_f32_e32 v61, 0xbfb8aa3b, v59
	v_exp_f32_e32 v45, v45
	v_exp_f32_e32 v36, v36
	v_exp_f32_e32 v37, v37
	v_exp_f32_e32 v61, v61
	v_cvt_pk_bf16_f32 v56, v56, v57
	v_add_f32_e32 v57, 1.0, v60
	v_add_f32_e32 v44, 1.0, v44
	v_add_f32_e32 v45, 1.0, v45
	v_add_f32_e32 v36, 1.0, v36
	v_add_f32_e32 v37, 1.0, v37
	v_rcp_f32_e32 v60, v57
	v_add_f32_e32 v57, 1.0, v61
	v_rcp_f32_e32 v44, v44
	v_rcp_f32_e32 v45, v45
	v_rcp_f32_e32 v36, v36
	v_rcp_f32_e32 v37, v37
	v_rcp_f32_e32 v61, v57
	v_pk_fma_f32 v[46:47], v[54:55], v[106:107], v[110:111]
	v_pk_fma_f32 v[66:67], v[42:43], v[106:107], v[110:111]
	v_pk_fma_f32 v[40:41], v[40:41], v[100:101], v[52:53]
	v_pk_fma_f32 v[38:39], v[42:43], v[102:103], v[46:47]
	v_pk_fma_f32 v[66:67], v[50:51], v[102:103], v[66:67]
	v_pk_fma_f32 v[40:41], v[48:49], v[96:97], v[40:41]
	v_pk_mul_f32 v[32:33], v[32:33], v[44:45]
	v_pk_fma_f32 v[38:39], v[50:51], v[98:99], v[38:39]
	v_pk_mul_f32 v[34:35], v[34:35], v[36:37]
	v_pk_fma_f32 v[62:63], v[62:63], v[98:99], v[66:67]
	v_pk_mul_f32 v[58:59], v[58:59], v[60:61]
	v_pk_mul_f32 v[32:33], v[40:41], v[32:33]
	v_pk_mul_f32 v[34:35], v[38:39], v[34:35]
	v_pk_mul_f32 v[58:59], v[62:63], v[58:59]
	v_cvt_pk_bf16_f32 v32, v32, v33
	v_cvt_pk_bf16_f32 v33, v34, v35
	v_cvt_pk_bf16_f32 v57, v58, v59
	v_mov_b32_e32 v158, v251
	v_mov_b32_e32 v159, v253
	v_mov_b32_e32 v160, v32
	v_mov_b32_e32 v161, v33
	global_store_dwordx4 v[140:141], v[158:161], off
	v_mov_b32_e32 v65, 0
	v_mov_b32_e32 v66, 0
	v_mov_b32_e32 v67, 0
	v_mov_b32_e32 v40, 0
	v_mov_b32_e32 v41, 0
	v_mov_b32_e32 v42, 0
	v_mov_b32_e32 v43, 0
	v_mov_b32_e32 v32, 0
	v_mov_b32_e32 v33, 0
	v_mov_b32_e32 v34, 0
	v_mov_b32_e32 v35, 0
	v_mov_b32_e32 v36, 0
	v_mov_b32_e32 v37, 0
	v_mov_b32_e32 v38, 0
	v_mov_b32_e32 v39, 0
	v_mov_b32_e32 v162, v254
	v_mov_b32_e32 v163, v255
	v_mov_b32_e32 v164, v56
	v_mov_b32_e32 v165, v57
	global_store_dwordx4 v[152:153], v[162:165], off
	s_and_saveexec_b64 s[42:43], s[30:31]
	s_cbranch_execz .LBB0_1355
	ds_read_b128 v[36:39], v237 offset:2064
	ds_read_b128 v[40:43], v237 offset:2576
	ds_read_b128 v[32:35], v237 offset:3088
	ds_read_b128 v[64:67], v237 offset:3600
	s_branch .LBB0_1355

; #define LAS __attribute__((address_space(3)))
; __device__ __forceinline__ float sigmoidf_(float x) { return __builtin_amdgcn_rcpf(1.0f + __expf(-x)); }
;     __device__ __forceinline__ void operator()(AccRef acc, const Unit& u, int wr, int wc, int fr, int fq) const {
;     ...
;                 f32x4 h2v = (f32x4){0.f, 0.f, 0.f, 0.f}, h3v = h2v, h2g = h2v, h3g = h2v;
;                 const int pb = ai * 2 + wr - 1;
;                 if (pb >= 0 && fr == 0) { const LAS float* xp = xch + (pb * 2) * 256 + clb + 4 * n;
;                     h2v = *(const LAS f32x4*)(xp); h3v = *(const LAS f32x4*)(xp + 256); h2g = *(const LAS f32x4*)(xp + 128); h3g = *(const LAS f32x4*)(xp + 256 + 128); }
;                 float o[4][4];
; #pragma unroll
;                 for (int j = 0; j < 4; ++j) {
;                     const float v0 = acc[ai][0][0][n][j], v1 = acc[ai][0][1][n][j], v2 = acc[ai][0][2][n][j], v3 = acc[ai][0][3][n][j];
;                     const float g0 = acc[ai][1][0][n][j], g1 = acc[ai][1][1][n][j], g2 = acc[ai][1][2][n][j], g3 = acc[ai][1][3][n][j];
;                     const float pv3 = dpp_upd<0x111>(h3v[j], v3), pv2 = dpp_upd<0x111>(h2v[j], v2), pg3 = dpp_upd<0x111>(h3g[j], g3), pg2 = dpp_upd<0x111>(h2g[j], g2);
;                     const float hv0 = bvv[j] + w2v[j] * v0 + w1v[j] * pv3 + w0v[j] * pv2, hv1 = bvv[j] + w2v[j] * v1 + w1v[j] * v0 + w0v[j] * pv3;
;                     const float hv2 = bvv[j] + w2v[j] * v2 + w1v[j] * v1 + w0v[j] * v0, hv3 = bvv[j] + w2v[j] * v3 + w1v[j] * v2 + w0v[j] * v1;
;                     const float hg0 = bvg[j] + w2g[j] * g0 + w1g[j] * pg3 + w0g[j] * pg2, hg1 = bvg[j] + w2g[j] * g1 + w1g[j] * g0 + w0g[j] * pg3;
;                     const float hg2 = bvg[j] + w2g[j] * g2 + w1g[j] * g1 + w0g[j] * g0, hg3 = bvg[j] + w2g[j] * g3 + w1g[j] * g2 + w0g[j] * g1;
;                     o[0][j] = hg0 * sigmoidf_(hg0) * hv0; o[1][j] = hg1 * sigmoidf_(hg1) * hv1; o[2][j] = hg2 * sigmoidf_(hg2) * hv2; o[3][j] = hg3 * sigmoidf_(hg3) * hv3; }
; #pragma unroll
;                 for (int m = 0; m < 4; ++m) { u32x2 w; w.x = cvt_pk_bf16(o[m][0], o[m][1]); w.y = cvt_pk_bf16(o[m][2], o[m][3]);
;                     *(u32x2*)(Aout + (size_t)(row0 + ai * 128 + m) * FH + hc0 + 4 * n) = w; } } }
.LBB0_1936:
	s_or_b64 exec, exec, s[34:35]
	s_waitcnt lgkmcnt(0)
	v_mov_b32_dpp v64, v8 row_shr:1 row_mask:0xf bank_mask:0xf
	v_mov_b32_dpp v65, v9 row_shr:1 row_mask:0xf bank_mask:0xf
	v_pk_fma_f32 v[44:45], v[24:25], v[120:121], v[124:125]
	v_mov_b32_dpp v40, v0 row_shr:1 row_mask:0xf bank_mask:0xf
	v_mov_b32_dpp v41, v1 row_shr:1 row_mask:0xf bank_mask:0xf
	v_pk_fma_f32 v[44:45], v[116:117], v[64:65], v[44:45]
	v_mov_b32_dpp v32, v20 row_shr:1 row_mask:0xf bank_mask:0xf
	v_pk_fma_f32 v[40:41], v[112:113], v[40:41], v[44:45]
	v_mov_b32_dpp v33, v21 row_shr:1 row_mask:0xf bank_mask:0xf
	v_mul_f32_e32 v44, 0xbfb8aa3b, v40
	v_mul_f32_e32 v45, 0xbfb8aa3b, v41
	v_exp_f32_e32 v44, v44
	v_exp_f32_e32 v45, v45
	v_pk_fma_f32 v[46:47], v[28:29], v[104:105], v[108:109]
	v_mov_b32_dpp v36, v12 row_shr:1 row_mask:0xf bank_mask:0xf
	v_add_f32_e32 v44, 1.0, v44
	v_add_f32_e32 v45, 1.0, v45
	v_rcp_f32_e32 v44, v44
	v_rcp_f32_e32 v45, v45
	v_mov_b32_dpp v37, v13 row_shr:1 row_mask:0xf bank_mask:0xf
	v_pk_fma_f32 v[46:47], v[100:101], v[32:33], v[46:47]
	v_mov_b32_dpp v66, v10 row_shr:1 row_mask:0xf bank_mask:0xf
	v_pk_fma_f32 v[36:37], v[96:97], v[36:37], v[46:47]
	v_pk_mul_f32 v[40:41], v[40:41], v[44:45]
	v_mov_b32_dpp v67, v11 row_shr:1 row_mask:0xf bank_mask:0xf
	v_pk_mul_f32 v[36:37], v[36:37], v[40:41]
	v_pk_fma_f32 v[40:41], v[26:27], v[122:123], v[126:127]
	v_mov_b32_dpp v42, v2 row_shr:1 row_mask:0xf bank_mask:0xf
	v_mov_b32_dpp v43, v3 row_shr:1 row_mask:0xf bank_mask:0xf
	v_pk_fma_f32 v[40:41], v[118:119], v[66:67], v[40:41]
	v_cvt_pk_bf16_f32 v36, v36, v37
	v_pk_fma_f32 v[40:41], v[114:115], v[42:43], v[40:41]
	v_mov_b32_dpp v34, v22 row_shr:1 row_mask:0xf bank_mask:0xf
	v_mul_f32_e32 v42, 0xbfb8aa3b, v40
	v_exp_f32_e32 v42, v42
	v_mul_f32_e32 v43, 0xbfb8aa3b, v41
	v_exp_f32_e32 v43, v43
	v_mov_b32_dpp v35, v23 row_shr:1 row_mask:0xf bank_mask:0xf
	v_add_f32_e32 v37, 1.0, v42
	v_rcp_f32_e32 v42, v37
	v_add_f32_e32 v37, 1.0, v43
	v_rcp_f32_e32 v43, v37
	v_pk_fma_f32 v[44:45], v[30:31], v[106:107], v[110:111]
	v_mov_b32_dpp v38, v14 row_shr:1 row_mask:0xf bank_mask:0xf
	v_mov_b32_dpp v39, v15 row_shr:1 row_mask:0xf bank_mask:0xf
	v_pk_fma_f32 v[44:45], v[102:103], v[34:35], v[44:45]
	v_pk_mul_f32 v[40:41], v[40:41], v[42:43]
	v_pk_fma_f32 v[38:39], v[98:99], v[38:39], v[44:45]
	v_pk_fma_f32 v[8:9], v[8:9], v[120:121], v[124:125]
	v_pk_mul_f32 v[38:39], v[38:39], v[40:41]
	v_pk_fma_f32 v[20:21], v[20:21], v[104:105], v[108:109]
	v_cvt_pk_bf16_f32 v37, v38, v39
	v_pk_fma_f32 v[38:39], v[4:5], v[120:121], v[124:125]
	v_mov_b32_e32 v146, v36
	v_mov_b32_e32 v147, v37
	global_store_dwordx4 v[132:133], v[144:147], off
	v_pk_fma_f32 v[38:39], v[24:25], v[116:117], v[38:39]
	s_and_b64 vcc, exec, s[10:11]
	v_pk_fma_f32 v[38:39], v[112:113], v[64:65], v[38:39]
	s_mov_b32 s35, s24
	v_mul_f32_e32 v40, 0xbfb8aa3b, v38
	v_mul_f32_e32 v41, 0xbfb8aa3b, v39
	v_exp_f32_e32 v40, v40
	v_exp_f32_e32 v41, v41
	s_mov_b32 s34, s26
	s_mov_b64 s[38:39], s[30:31]
	v_add_f32_e32 v36, 1.0, v40
	v_add_f32_e32 v37, 1.0, v41
	v_rcp_f32_e32 v36, v36
	v_rcp_f32_e32 v37, v37
	v_pk_fma_f32 v[40:41], v[16:17], v[104:105], v[108:109]
	s_mov_b64 s[36:37], s[28:29]
	v_pk_fma_f32 v[40:41], v[28:29], v[100:101], v[40:41]
	v_pk_mul_f32 v[36:37], v[38:39], v[36:37]
	v_pk_fma_f32 v[32:33], v[96:97], v[32:33], v[40:41]
	v_pk_fma_f32 v[40:41], v[18:19], v[106:107], v[110:111]
	v_pk_mul_f32 v[32:33], v[32:33], v[36:37]
	v_pk_fma_f32 v[36:37], v[6:7], v[122:123], v[126:127]
	v_cvt_pk_bf16_f32 v32, v32, v33
	v_pk_fma_f32 v[36:37], v[26:27], v[118:119], v[36:37]
	v_pk_fma_f32 v[40:41], v[30:31], v[102:103], v[40:41]
	v_pk_fma_f32 v[36:37], v[114:115], v[66:67], v[36:37]
	v_pk_fma_f32 v[34:35], v[98:99], v[34:35], v[40:41]
	v_mul_f32_e32 v38, 0xbfb8aa3b, v36
	v_exp_f32_e32 v38, v38
	v_mul_f32_e32 v39, 0xbfb8aa3b, v37
	v_exp_f32_e32 v39, v39
	v_add_f32_e32 v33, 1.0, v38
	v_rcp_f32_e32 v38, v33
	v_add_f32_e32 v33, 1.0, v39
	v_rcp_f32_e32 v39, v33
	s_nop 0
	v_pk_mul_f32 v[36:37], v[36:37], v[38:39]
	s_nop 0
	v_pk_mul_f32 v[34:35], v[34:35], v[36:37]
	s_nop 0
	v_cvt_pk_bf16_f32 v33, v34, v35
	v_pk_fma_f32 v[34:35], v[0:1], v[120:121], v[124:125]
	v_mov_b32_e32 v156, v32
	v_mov_b32_e32 v157, v33
	global_store_dwordx4 v[128:129], v[154:157], off
	v_pk_fma_f32 v[34:35], v[4:5], v[116:117], v[34:35]
	v_pk_fma_f32 v[0:1], v[0:1], v[116:117], v[8:9]
	v_pk_fma_f32 v[24:25], v[24:25], v[112:113], v[34:35]
	v_pk_fma_f32 v[0:1], v[4:5], v[112:113], v[0:1]
	v_mul_f32_e32 v34, 0xbfb8aa3b, v24
	v_mul_f32_e32 v35, 0xbfb8aa3b, v25
	v_exp_f32_e32 v34, v34
	v_exp_f32_e32 v35, v35
	v_mul_f32_e32 v4, 0xbfb8aa3b, v0
	v_exp_f32_e32 v8, v4
	v_add_f32_e32 v32, 1.0, v34
	v_add_f32_e32 v33, 1.0, v35
	v_rcp_f32_e32 v32, v32
	v_rcp_f32_e32 v33, v33
	v_pk_fma_f32 v[34:35], v[12:13], v[104:105], v[108:109]
	v_pk_fma_f32 v[4:5], v[10:11], v[122:123], v[126:127]
	v_pk_fma_f32 v[34:35], v[16:17], v[100:101], v[34:35]
	v_pk_mul_f32 v[24:25], v[24:25], v[32:33]
	v_pk_fma_f32 v[28:29], v[28:29], v[96:97], v[34:35]
	v_mul_f32_e32 v9, 0xbfb8aa3b, v1
	v_pk_mul_f32 v[24:25], v[28:29], v[24:25]
	v_pk_fma_f32 v[28:29], v[2:3], v[122:123], v[126:127]
	v_pk_fma_f32 v[2:3], v[2:3], v[118:119], v[4:5]
	v_pk_fma_f32 v[28:29], v[6:7], v[118:119], v[28:29]
	v_pk_fma_f32 v[2:3], v[6:7], v[114:115], v[2:3]
	v_pk_fma_f32 v[26:27], v[26:27], v[114:115], v[28:29]
	v_mul_f32_e32 v4, 0xbfb8aa3b, v2
	v_mul_f32_e32 v28, 0xbfb8aa3b, v26
	v_exp_f32_e32 v28, v28
	v_mul_f32_e32 v29, 0xbfb8aa3b, v27
	v_mul_f32_e32 v5, 0xbfb8aa3b, v3
	v_exp_f32_e32 v29, v29
	v_exp_f32_e32 v9, v9
	v_exp_f32_e32 v4, v4
	v_exp_f32_e32 v5, v5
	v_cvt_pk_bf16_f32 v24, v24, v25
	v_add_f32_e32 v25, 1.0, v28
	v_rcp_f32_e32 v28, v25
	v_add_f32_e32 v25, 1.0, v29
	v_add_f32_e32 v8, 1.0, v8
	v_add_f32_e32 v9, 1.0, v9
	v_add_f32_e32 v4, 1.0, v4
	v_add_f32_e32 v5, 1.0, v5
	v_rcp_f32_e32 v29, v25
	v_rcp_f32_e32 v8, v8
	v_rcp_f32_e32 v9, v9
	v_rcp_f32_e32 v4, v4
	v_rcp_f32_e32 v5, v5
	v_pk_fma_f32 v[32:33], v[14:15], v[106:107], v[110:111]
	v_pk_fma_f32 v[10:11], v[22:23], v[106:107], v[110:111]
	v_pk_fma_f32 v[32:33], v[18:19], v[102:103], v[32:33]
	v_pk_fma_f32 v[12:13], v[12:13], v[100:101], v[20:21]
	v_pk_fma_f32 v[6:7], v[14:15], v[102:103], v[10:11]
	v_pk_fma_f32 v[30:31], v[30:31], v[98:99], v[32:33]
	v_pk_mul_f32 v[26:27], v[26:27], v[28:29]
	v_pk_fma_f32 v[12:13], v[16:17], v[96:97], v[12:13]
	v_pk_mul_f32 v[0:1], v[0:1], v[8:9]
	v_pk_fma_f32 v[6:7], v[18:19], v[98:99], v[6:7]
	v_pk_mul_f32 v[2:3], v[2:3], v[4:5]
	v_pk_mul_f32 v[26:27], v[30:31], v[26:27]
	v_pk_mul_f32 v[0:1], v[12:13], v[0:1]
	v_pk_mul_f32 v[2:3], v[6:7], v[2:3]
	v_cvt_pk_bf16_f32 v25, v26, v27
	v_cvt_pk_bf16_f32 v0, v0, v1
	v_cvt_pk_bf16_f32 v1, v2, v3
	v_mov_b32_e32 v200, v24
	v_mov_b32_e32 v201, v25
	global_store_dwordx4 v[88:89], v[198:201], off
	v_mov_b32_e32 v150, v0
	v_mov_b32_e32 v151, v1
	global_store_dwordx4 v[82:83], v[148:151], off
	s_cbranch_vccnz .LBB0_1955

; #define LAS __attribute__((address_space(3)))
;     __device__ __forceinline__ void operator()(AccRef acc, const Unit& u, int wr, int wc, int fr, int fq) const {
;     ...
;         const int hc0 = 128 * u.pn + clb, row0 = u.pm * 256 + wr * 64 + 4 * fr;
; #pragma unroll
;         for (int n = 0; n < 2; ++n) {
;             const f32x4 w0v = cwv[n][0], w1v = cwv[n][1], w2v = cwv[n][2], bvv = cwv[n][3], w0g = cwv[n][4], w1g = cwv[n][5], w2g = cwv[n][6], bvg = cwv[n][7];
; #pragma unroll
;             for (int ai = 0; ai < 2; ++ai) {
;                 if (n == 0 && ai == 0) {
;                     asm volatile("" ::: "memory");
;                     const float* cv = cw + hc0 + 4; const float* cg = cv + FH; const float* bp = cb + hc0 + 4;
;                     cwv[1][0] = *(const f32x4*)(cv); cwv[1][1] = *(const f32x4*)(cv + F2); cwv[1][2] = *(const f32x4*)(cv + 2 * F2); cwv[1][3] = *(const f32x4*)(bp);
;                     cwv[1][4] = *(const f32x4*)(cg); cwv[1][5] = *(const f32x4*)(cg + F2); cwv[1][6] = *(const f32x4*)(cg + 2 * F2); cwv[1][7] = *(const f32x4*)(bp + FH);
;                     asm volatile("" ::: "memory"); }
;                 f32x4 h2v = (f32x4){0.f, 0.f, 0.f, 0.f}, h3v = h2v, h2g = h2v, h3g = h2v;
;                 const int pb = ai * 2 + wr - 1;
;                 if (pb >= 0 && fr == 0) { const LAS float* xp = xch + (pb * 2) * 256 + clb + 4 * n;
;                     h2v = *(const LAS f32x4*)(xp); h3v = *(const LAS f32x4*)(xp + 256); h2g = *(const LAS f32x4*)(xp + 128); h3g = *(const LAS f32x4*)(xp + 256 + 128); }
;                 float o[4][4];
; #pragma unroll
;                 for (int j = 0; j < 4; ++j) {
;                     const float v0 = acc[ai][0][0][n][j], v1 = acc[ai][0][1][n][j], v2 = acc[ai][0][2][n][j], v3 = acc[ai][0][3][n][j];
;                     const float g0 = acc[ai][1][0][n][j], g1 = acc[ai][1][1][n][j], g2 = acc[ai][1][2][n][j], g3 = acc[ai][1][3][n][j];
;                     const float pv3 = dpp_upd<0x111>(h3v[j], v3), pv2 = dpp_upd<0x111>(h2v[j], v2), pg3 = dpp_upd<0x111>(h3g[j], g3), pg2 = dpp_upd<0x111>(h2g[j], g2);
;                     const float hv0 = bvv[j] + w2v[j] * v0 + w1v[j] * pv3 + w0v[j] * pv2, hv1 = bvv[j] + w2v[j] * v1 + w1v[j] * v0 + w0v[j] * pv3;
;                     const float hv2 = bvv[j] + w2v[j] * v2 + w1v[j] * v1 + w0v[j] * v0, hv3 = bvv[j] + w2v[j] * v3 + w1v[j] * v2 + w0v[j] * v1;
.LBB0_1947:
	s_or_b64 exec, exec, s[40:41]
	v_pk_fma_f32 v[246:247], v[152:153], v[184:185], v[188:189]
	v_mov_b32_dpp v206, v128 row_shr:1 row_mask:0xf bank_mask:0xf
	v_mov_b32_dpp v207, v129 row_shr:1 row_mask:0xf bank_mask:0xf
	v_pk_fma_f32 v[246:247], v[180:181], v[198:199], v[246:247]
	v_mov_b32_dpp v194, v148 row_shr:1 row_mask:0xf bank_mask:0xf
	v_pk_fma_f32 v[206:207], v[176:177], v[206:207], v[246:247]
	v_mov_b32_dpp v195, v149 row_shr:1 row_mask:0xf bank_mask:0xf
	v_mul_f32_e32 v193, 0xbfb8aa3b, v206
	v_exp_f32_e32 v193, v193
	v_mul_f32_e32 v246, 0xbfb8aa3b, v207
	v_exp_f32_e32 v247, v246
	v_pk_fma_f32 v[248:249], v[156:157], v[168:169], v[172:173]
	v_add_f32_e32 v193, 1.0, v193
	v_rcp_f32_e32 v246, v193
	v_add_f32_e32 v193, 1.0, v247
	v_rcp_f32_e32 v247, v193
	v_mov_b32_dpp v202, v136 row_shr:1 row_mask:0xf bank_mask:0xf
	v_mov_b32_dpp v203, v137 row_shr:1 row_mask:0xf bank_mask:0xf
	v_pk_fma_f32 v[248:249], v[164:165], v[194:195], v[248:249]
	v_pk_mul_f32 v[206:207], v[206:207], v[246:247]
	v_pk_fma_f32 v[202:203], v[160:161], v[202:203], v[248:249]
	v_mov_b32_dpp v200, v142 row_shr:1 row_mask:0xf bank_mask:0xf
	v_mov_b32_dpp v201, v143 row_shr:1 row_mask:0xf bank_mask:0xf
	v_pk_mul_f32 v[202:203], v[202:203], v[206:207]
	v_pk_fma_f32 v[206:207], v[154:155], v[186:187], v[190:191]
	v_mov_b32_dpp v208, v130 row_shr:1 row_mask:0xf bank_mask:0xf
	v_mov_b32_dpp v209, v131 row_shr:1 row_mask:0xf bank_mask:0xf
	v_pk_fma_f32 v[206:207], v[182:183], v[200:201], v[206:207]
	v_mov_b32_dpp v196, v150 row_shr:1 row_mask:0xf bank_mask:0xf
	v_pk_fma_f32 v[206:207], v[178:179], v[208:209], v[206:207]
	v_mov_b32_dpp v197, v151 row_shr:1 row_mask:0xf bank_mask:0xf
	v_mul_f32_e32 v193, 0xbfb8aa3b, v206
	v_exp_f32_e32 v193, v193
	v_mul_f32_e32 v208, 0xbfb8aa3b, v207
	v_exp_f32_e32 v209, v208
	v_cvt_pk_bf16_f32 v208, v202, v203
	v_add_f32_e32 v193, 1.0, v193
	v_rcp_f32_e32 v202, v193
	v_add_f32_e32 v193, 1.0, v209
	v_rcp_f32_e32 v203, v193
	v_pk_fma_f32 v[246:247], v[158:159], v[170:171], v[174:175]
	v_mov_b32_dpp v204, v138 row_shr:1 row_mask:0xf bank_mask:0xf
	v_mov_b32_dpp v205, v139 row_shr:1 row_mask:0xf bank_mask:0xf
	v_pk_fma_f32 v[246:247], v[166:167], v[196:197], v[246:247]
	v_pk_mul_f32 v[202:203], v[206:207], v[202:203]
	v_pk_fma_f32 v[204:205], v[162:163], v[204:205], v[246:247]
	v_lshl_add_u32 v245, s34, 8, v235
	v_pk_mul_f32 v[202:203], v[204:205], v[202:203]
	v_lshlrev_b64 v[204:205], 1, v[232:233]
	v_pk_fma_f32 v[232:233], v[132:133], v[184:185], v[188:189]
	v_mov_b64_e32 v[206:207], s[60:61]
	v_pk_fma_f32 v[232:233], v[152:153], v[180:181], v[232:233]
	v_cvt_pk_bf16_f32 v209, v202, v203
	v_pk_fma_f32 v[198:199], v[176:177], v[198:199], v[232:233]
	v_mad_i64_i32 v[202:203], s[34:35], v245, s63, v[206:207]
	v_mul_f32_e32 v193, 0xbfb8aa3b, v198
	v_exp_f32_e32 v193, v193
	v_mul_f32_e32 v232, 0xbfb8aa3b, v199
	v_exp_f32_e32 v232, v232
	v_lshl_add_u64 v[202:203], v[202:203], 0, v[204:205]
	v_add_f32_e32 v193, 1.0, v193
	v_mov_b32_e32 v246, v208
	v_mov_b32_e32 v247, v209
	v_rcp_f32_e32 v208, v193
	v_add_f32_e32 v193, 1.0, v232
	v_rcp_f32_e32 v209, v193
	v_pk_fma_f32 v[232:233], v[144:145], v[168:169], v[172:173]
	v_pk_fma_f32 v[140:141], v[140:141], v[184:185], v[188:189]
	v_pk_fma_f32 v[232:233], v[156:157], v[164:165], v[232:233]
	v_pk_mul_f32 v[198:199], v[198:199], v[208:209]
	v_pk_fma_f32 v[194:195], v[160:161], v[194:195], v[232:233]
	v_pk_fma_f32 v[208:209], v[146:147], v[170:171], v[174:175]
	v_pk_mul_f32 v[194:195], v[194:195], v[198:199]
	v_pk_fma_f32 v[198:199], v[134:135], v[186:187], v[190:191]
	v_pk_fma_f32 v[208:209], v[158:159], v[166:167], v[208:209]
	v_pk_fma_f32 v[198:199], v[154:155], v[182:183], v[198:199]
	v_pk_fma_f32 v[196:197], v[162:163], v[196:197], v[208:209]
	v_pk_fma_f32 v[198:199], v[178:179], v[200:201], v[198:199]
	v_cvt_pk_bf16_f32 v194, v194, v195
	v_mul_f32_e32 v193, 0xbfb8aa3b, v198
	v_exp_f32_e32 v193, v193
	v_mul_f32_e32 v200, 0xbfb8aa3b, v199
	v_exp_f32_e32 v201, v200
	v_pk_fma_f32 v[148:149], v[148:149], v[168:169], v[172:173]
	v_add_f32_e32 v193, 1.0, v193
	v_rcp_f32_e32 v200, v193
	v_add_f32_e32 v193, 1.0, v201
	v_rcp_f32_e32 v201, v193
	v_or_b32_e32 v193, 1, v245
	v_pk_mul_f32 v[198:199], v[198:199], v[200:201]
	s_nop 0
	v_pk_mul_f32 v[196:197], v[196:197], v[198:199]
	v_pk_fma_f32 v[198:199], v[128:129], v[184:185], v[188:189]
	v_cvt_pk_bf16_f32 v195, v196, v197
	v_pk_fma_f32 v[198:199], v[132:133], v[180:181], v[198:199]
	v_mad_i64_i32 v[196:197], s[34:35], v193, s63, v[206:207]
	v_pk_fma_f32 v[152:153], v[152:153], v[176:177], v[198:199]
	v_lshl_add_u64 v[196:197], v[196:197], 0, v[204:205]
	v_mul_f32_e32 v193, 0xbfb8aa3b, v152
	v_exp_f32_e32 v193, v193
	v_mul_f32_e32 v198, 0xbfb8aa3b, v153
	v_exp_f32_e32 v198, v198
	v_mov_b32_e32 v248, v194
	v_mov_b32_e32 v249, v195
	v_add_f32_e32 v193, 1.0, v193
	v_rcp_f32_e32 v194, v193
	v_add_f32_e32 v193, 1.0, v198
	v_rcp_f32_e32 v195, v193
	v_pk_fma_f32 v[198:199], v[136:137], v[168:169], v[172:173]
	v_pk_fma_f32 v[128:129], v[128:129], v[180:181], v[140:141]
	v_pk_fma_f32 v[198:199], v[144:145], v[164:165], v[198:199]
	v_pk_fma_f32 v[128:129], v[132:133], v[176:177], v[128:129]
	v_pk_fma_f32 v[156:157], v[156:157], v[160:161], v[198:199]
	v_pk_mul_f32 v[152:153], v[152:153], v[194:195]
	v_mul_f32_e32 v132, 0xbfb8aa3b, v128
	v_pk_mul_f32 v[152:153], v[156:157], v[152:153]
	v_pk_fma_f32 v[156:157], v[130:131], v[186:187], v[190:191]
	v_exp_f32_e32 v140, v132
	v_pk_fma_f32 v[132:133], v[142:143], v[186:187], v[190:191]
	v_pk_fma_f32 v[156:157], v[134:135], v[182:183], v[156:157]
	v_pk_fma_f32 v[130:131], v[130:131], v[182:183], v[132:133]
; #define LAS __attribute__((address_space(3)))
; __device__ __forceinline__ float sigmoidf_(float x) { return __builtin_amdgcn_rcpf(1.0f + __expf(-x)); }
;     __device__ __forceinline__ void operator()(AccRef acc, const Unit& u, int wr, int wc, int fr, int fq) const {
;     ...
;                 f32x4 h2v = (f32x4){0.f, 0.f, 0.f, 0.f}, h3v = h2v, h2g = h2v, h3g = h2v;
;                 const int pb = ai * 2 + wr - 1;
;                 if (pb >= 0 && fr == 0) { const LAS float* xp = xch + (pb * 2) * 256 + clb + 4 * n;
;                     h2v = *(const LAS f32x4*)(xp); h3v = *(const LAS f32x4*)(xp + 256); h2g = *(const LAS f32x4*)(xp + 128); h3g = *(const LAS f32x4*)(xp + 256 + 128); }
;                 float o[4][4];
; #pragma unroll
;                 for (int j = 0; j < 4; ++j) {
;                     const float v0 = acc[ai][0][0][n][j], v1 = acc[ai][0][1][n][j], v2 = acc[ai][0][2][n][j], v3 = acc[ai][0][3][n][j];
;                     const float g0 = acc[ai][1][0][n][j], g1 = acc[ai][1][1][n][j], g2 = acc[ai][1][2][n][j], g3 = acc[ai][1][3][n][j];
;                     const float pv3 = dpp_upd<0x111>(h3v[j], v3), pv2 = dpp_upd<0x111>(h2v[j], v2), pg3 = dpp_upd<0x111>(h3g[j], g3), pg2 = dpp_upd<0x111>(h2g[j], g2);
;                     const float hv0 = bvv[j] + w2v[j] * v0 + w1v[j] * pv3 + w0v[j] * pv2, hv1 = bvv[j] + w2v[j] * v1 + w1v[j] * v0 + w0v[j] * pv3;
;                     const float hv2 = bvv[j] + w2v[j] * v2 + w1v[j] * v1 + w0v[j] * v0, hv3 = bvv[j] + w2v[j] * v3 + w1v[j] * v2 + w0v[j] * v1;
;                     const float hg0 = bvg[j] + w2g[j] * g0 + w1g[j] * pg3 + w0g[j] * pg2, hg1 = bvg[j] + w2g[j] * g1 + w1g[j] * g0 + w0g[j] * pg3;
;                     const float hg2 = bvg[j] + w2g[j] * g2 + w1g[j] * g1 + w0g[j] * g0, hg3 = bvg[j] + w2g[j] * g3 + w1g[j] * g2 + w0g[j] * g1;
;                     o[0][j] = hg0 * sigmoidf_(hg0) * hv0; o[1][j] = hg1 * sigmoidf_(hg1) * hv1; o[2][j] = hg2 * sigmoidf_(hg2) * hv2; o[3][j] = hg3 * sigmoidf_(hg3) * hv3; }
; #pragma unroll
;                 for (int m = 0; m < 4; ++m) { u32x2 w; w.x = cvt_pk_bf16(o[m][0], o[m][1]); w.y = cvt_pk_bf16(o[m][2], o[m][3]);
;                     *(u32x2*)(Aout + (size_t)(row0 + ai * 128 + m) * FH + hc0 + 4 * n) = w; } } }
	v_pk_fma_f32 v[154:155], v[154:155], v[178:179], v[156:157]
	v_pk_fma_f32 v[130:131], v[134:135], v[178:179], v[130:131]
	v_mul_f32_e32 v156, 0xbfb8aa3b, v154
	v_mul_f32_e32 v141, 0xbfb8aa3b, v129
	v_mul_f32_e32 v132, 0xbfb8aa3b, v130
	v_mul_f32_e32 v133, 0xbfb8aa3b, v131
	v_exp_f32_e32 v157, v156
	v_mul_f32_e32 v156, 0xbfb8aa3b, v155
	v_exp_f32_e32 v141, v141
	v_exp_f32_e32 v132, v132
	v_exp_f32_e32 v133, v133
	v_exp_f32_e32 v193, v156
	v_add_f32_e32 v140, 1.0, v140
	v_add_f32_e32 v141, 1.0, v141
	v_add_f32_e32 v132, 1.0, v132
	v_add_f32_e32 v133, 1.0, v133
	v_cvt_pk_bf16_f32 v156, v152, v153
	v_add_f32_e32 v152, 1.0, v157
	v_add_f32_e32 v153, 1.0, v193
	v_rcp_f32_e32 v140, v140
	v_rcp_f32_e32 v141, v141
	v_rcp_f32_e32 v132, v132
	v_rcp_f32_e32 v133, v133
	v_rcp_f32_e32 v152, v152
	v_rcp_f32_e32 v153, v153
	v_pk_fma_f32 v[142:143], v[150:151], v[170:171], v[174:175]
	v_pk_fma_f32 v[194:195], v[138:139], v[170:171], v[174:175]
	v_pk_fma_f32 v[136:137], v[136:137], v[164:165], v[148:149]
	v_pk_fma_f32 v[134:135], v[138:139], v[166:167], v[142:143]
	v_pk_fma_f32 v[194:195], v[146:147], v[166:167], v[194:195]
	v_pk_fma_f32 v[136:137], v[144:145], v[160:161], v[136:137]
	v_pk_mul_f32 v[128:129], v[128:129], v[140:141]
	v_pk_fma_f32 v[134:135], v[146:147], v[162:163], v[134:135]
	v_pk_mul_f32 v[130:131], v[130:131], v[132:133]
	v_pk_fma_f32 v[158:159], v[158:159], v[162:163], v[194:195]
	v_pk_mul_f32 v[152:153], v[154:155], v[152:153]
	v_pk_mul_f32 v[128:129], v[136:137], v[128:129]
	v_pk_mul_f32 v[130:131], v[134:135], v[130:131]
	v_pk_mul_f32 v[152:153], v[158:159], v[152:153]
	v_cvt_pk_bf16_f32 v128, v128, v129
	v_cvt_pk_bf16_f32 v129, v130, v131
	v_or_b32_e32 v130, 3, v245
	v_cvt_pk_bf16_f32 v157, v152, v153
	v_or_b32_e32 v152, 2, v245
	v_mad_i64_i32 v[130:131], s[34:35], v130, s63, v[206:207]
	v_mad_i64_i32 v[152:153], s[34:35], v152, s63, v[206:207]
	v_lshl_add_u64 v[140:141], v[130:131], 0, v[204:205]
	v_lshl_add_u64 v[152:153], v[152:153], 0, v[204:205]
	v_mov_b32_e32 v250, v128
	v_mov_b32_e32 v251, v129
	v_mov_b32_e32 v193, 0
	v_mov_b32_e32 v194, 0
	v_mov_b32_e32 v195, 0
	v_mov_b32_e32 v136, 0
	v_mov_b32_e32 v137, 0
	v_mov_b32_e32 v138, 0
	v_mov_b32_e32 v139, 0
	v_mov_b32_e32 v128, 0
	v_mov_b32_e32 v129, 0
	v_mov_b32_e32 v130, 0
	v_mov_b32_e32 v131, 0
	v_mov_b32_e32 v132, 0
	v_mov_b32_e32 v133, 0
	v_mov_b32_e32 v134, 0
	v_mov_b32_e32 v135, 0
	v_mov_b32_e32 v253, v156
	v_mov_b32_e32 v254, v157
	s_and_saveexec_b64 s[34:35], s[22:23]
	s_cbranch_execz .LBB0_1951
	ds_read_b128 v[132:135], v236 offset:2048
	ds_read_b128 v[136:139], v236 offset:2560
	ds_read_b128 v[128:131], v236 offset:3072
	ds_read_b128 v[192:195], v236 offset:3584
.LBB0_1951:
	s_or_b64 exec, exec, s[34:35]
	s_waitcnt lgkmcnt(0)
	v_mov_b32_dpp v192, v72 row_shr:1 row_mask:0xf bank_mask:0xf
	v_mov_b32_dpp v193, v73 row_shr:1 row_mask:0xf bank_mask:0xf
	v_pk_fma_f32 v[142:143], v[88:89], v[184:185], v[188:189]
	v_mov_b32_dpp v136, v64 row_shr:1 row_mask:0xf bank_mask:0xf
	v_mov_b32_dpp v137, v65 row_shr:1 row_mask:0xf bank_mask:0xf
	v_pk_fma_f32 v[142:143], v[180:181], v[192:193], v[142:143]
	v_mov_b32_dpp v128, v84 row_shr:1 row_mask:0xf bank_mask:0xf
	v_pk_fma_f32 v[136:137], v[176:177], v[136:137], v[142:143]
	v_mov_b32_dpp v129, v85 row_shr:1 row_mask:0xf bank_mask:0xf
	v_mul_f32_e32 v142, 0xbfb8aa3b, v136
	v_mul_f32_e32 v143, 0xbfb8aa3b, v137
	v_exp_f32_e32 v142, v142
	v_exp_f32_e32 v143, v143
	v_pk_fma_f32 v[144:145], v[92:93], v[168:169], v[172:173]
	v_mov_b32_dpp v132, v76 row_shr:1 row_mask:0xf bank_mask:0xf
	v_add_f32_e32 v142, 1.0, v142
	v_add_f32_e32 v143, 1.0, v143
	v_rcp_f32_e32 v142, v142
	v_rcp_f32_e32 v143, v143
	v_mov_b32_dpp v133, v77 row_shr:1 row_mask:0xf bank_mask:0xf
	v_pk_fma_f32 v[144:145], v[164:165], v[128:129], v[144:145]
	v_mov_b32_dpp v194, v74 row_shr:1 row_mask:0xf bank_mask:0xf
	v_pk_fma_f32 v[132:133], v[160:161], v[132:133], v[144:145]
	v_pk_mul_f32 v[136:137], v[136:137], v[142:143]
	v_mov_b32_dpp v195, v75 row_shr:1 row_mask:0xf bank_mask:0xf
	v_pk_mul_f32 v[132:133], v[132:133], v[136:137]
	v_pk_fma_f32 v[136:137], v[90:91], v[186:187], v[190:191]
	v_mov_b32_dpp v138, v66 row_shr:1 row_mask:0xf bank_mask:0xf
	v_mov_b32_dpp v139, v67 row_shr:1 row_mask:0xf bank_mask:0xf
	v_pk_fma_f32 v[136:137], v[182:183], v[194:195], v[136:137]
	v_mov_b32_dpp v130, v86 row_shr:1 row_mask:0xf bank_mask:0xf
	v_pk_fma_f32 v[136:137], v[178:179], v[138:139], v[136:137]
	v_mov_b32_dpp v131, v87 row_shr:1 row_mask:0xf bank_mask:0xf
	v_mul_f32_e32 v138, 0xbfb8aa3b, v136
	v_exp_f32_e32 v139, v138
	v_mul_f32_e32 v138, 0xbfb8aa3b, v137
	v_exp_f32_e32 v142, v138
	v_cvt_pk_bf16_f32 v138, v132, v133
	v_add_f32_e32 v132, 1.0, v139
	v_rcp_f32_e32 v132, v132
	v_add_f32_e32 v133, 1.0, v142
	v_rcp_f32_e32 v133, v133
	v_pk_fma_f32 v[142:143], v[94:95], v[170:171], v[174:175]
	v_mov_b32_dpp v134, v78 row_shr:1 row_mask:0xf bank_mask:0xf
	v_mov_b32_dpp v135, v79 row_shr:1 row_mask:0xf bank_mask:0xf
	v_pk_mul_f32 v[132:133], v[136:137], v[132:133]
	v_pk_fma_f32 v[136:137], v[68:69], v[184:185], v[188:189]
	v_pk_fma_f32 v[142:143], v[166:167], v[130:131], v[142:143]
	v_pk_fma_f32 v[136:137], v[88:89], v[180:181], v[136:137]
	v_pk_fma_f32 v[134:135], v[162:163], v[134:135], v[142:143]
	v_pk_fma_f32 v[136:137], v[176:177], v[192:193], v[136:137]
	v_add_u32_e32 v146, 0x80, v245
	v_mul_f32_e32 v142, 0xbfb8aa3b, v136
	v_mul_f32_e32 v143, 0xbfb8aa3b, v137
	v_exp_f32_e32 v142, v142
	v_exp_f32_e32 v143, v143
	v_pk_mul_f32 v[132:133], v[134:135], v[132:133]
	v_mov_b64_e32 v[134:135], s[60:61]
	v_cvt_pk_bf16_f32 v139, v132, v133
	v_mad_i64_i32 v[132:133], s[34:35], v146, s63, v[134:135]
; #define LAS __attribute__((address_space(3)))
; __device__ __forceinline__ float sigmoidf_(float x) { return __builtin_amdgcn_rcpf(1.0f + __expf(-x)); }
;     __device__ __forceinline__ void operator()(AccRef acc, const Unit& u, int wr, int wc, int fr, int fq) const {
;     ...
;                 f32x4 h2v = (f32x4){0.f, 0.f, 0.f, 0.f}, h3v = h2v, h2g = h2v, h3g = h2v;
;                 const int pb = ai * 2 + wr - 1;
;                 if (pb >= 0 && fr == 0) { const LAS float* xp = xch + (pb * 2) * 256 + clb + 4 * n;
;                     h2v = *(const LAS f32x4*)(xp); h3v = *(const LAS f32x4*)(xp + 256); h2g = *(const LAS f32x4*)(xp + 128); h3g = *(const LAS f32x4*)(xp + 256 + 128); }
;                 float o[4][4];
; #pragma unroll
;                 for (int j = 0; j < 4; ++j) {
;                     const float v0 = acc[ai][0][0][n][j], v1 = acc[ai][0][1][n][j], v2 = acc[ai][0][2][n][j], v3 = acc[ai][0][3][n][j];
;                     const float g0 = acc[ai][1][0][n][j], g1 = acc[ai][1][1][n][j], g2 = acc[ai][1][2][n][j], g3 = acc[ai][1][3][n][j];
;                     const float pv3 = dpp_upd<0x111>(h3v[j], v3), pv2 = dpp_upd<0x111>(h2v[j], v2), pg3 = dpp_upd<0x111>(h3g[j], g3), pg2 = dpp_upd<0x111>(h2g[j], g2);
;                     const float hv0 = bvv[j] + w2v[j] * v0 + w1v[j] * pv3 + w0v[j] * pv2, hv1 = bvv[j] + w2v[j] * v1 + w1v[j] * v0 + w0v[j] * pv3;
;                     const float hv2 = bvv[j] + w2v[j] * v2 + w1v[j] * v1 + w0v[j] * v0, hv3 = bvv[j] + w2v[j] * v3 + w1v[j] * v2 + w0v[j] * v1;
;                     const float hg0 = bvg[j] + w2g[j] * g0 + w1g[j] * pg3 + w0g[j] * pg2, hg1 = bvg[j] + w2g[j] * g1 + w1g[j] * g0 + w0g[j] * pg3;
;                     const float hg2 = bvg[j] + w2g[j] * g2 + w1g[j] * g1 + w0g[j] * g0, hg3 = bvg[j] + w2g[j] * g3 + w1g[j] * g2 + w0g[j] * g1;
;                     o[0][j] = hg0 * sigmoidf_(hg0) * hv0; o[1][j] = hg1 * sigmoidf_(hg1) * hv1; o[2][j] = hg2 * sigmoidf_(hg2) * hv2; o[3][j] = hg3 * sigmoidf_(hg3) * hv3; }
; #pragma unroll
;                 for (int m = 0; m < 4; ++m) { u32x2 w; w.x = cvt_pk_bf16(o[m][0], o[m][1]); w.y = cvt_pk_bf16(o[m][2], o[m][3]);
;                     *(u32x2*)(Aout + (size_t)(row0 + ai * 128 + m) * FH + hc0 + 4 * n) = w; } } }
	v_lshl_add_u64 v[132:133], v[132:133], 0, v[204:205]
	v_mov_b32_e32 v144, v138
	v_mov_b32_e32 v145, v139
	v_add_f32_e32 v138, 1.0, v142
	v_add_f32_e32 v139, 1.0, v143
	v_rcp_f32_e32 v138, v138
	v_rcp_f32_e32 v139, v139
	v_pk_fma_f32 v[142:143], v[80:81], v[168:169], v[172:173]
	v_pk_fma_f32 v[72:73], v[72:73], v[184:185], v[188:189]
	v_pk_fma_f32 v[142:143], v[92:93], v[164:165], v[142:143]
	v_pk_mul_f32 v[136:137], v[136:137], v[138:139]
	v_pk_fma_f32 v[128:129], v[160:161], v[128:129], v[142:143]
	v_pk_fma_f32 v[84:85], v[84:85], v[168:169], v[172:173]
	v_pk_mul_f32 v[128:129], v[128:129], v[136:137]
	v_pk_fma_f32 v[136:137], v[70:71], v[186:187], v[190:191]
	s_nop 0
	v_pk_fma_f32 v[136:137], v[90:91], v[182:183], v[136:137]
	s_nop 0
	v_pk_fma_f32 v[136:137], v[178:179], v[194:195], v[136:137]
	s_nop 0
	v_mul_f32_e32 v138, 0xbfb8aa3b, v136
	v_exp_f32_e32 v139, v138
	v_mul_f32_e32 v138, 0xbfb8aa3b, v137
	v_exp_f32_e32 v142, v138
	v_cvt_pk_bf16_f32 v138, v128, v129
	v_add_f32_e32 v128, 1.0, v139
	v_rcp_f32_e32 v128, v128
	v_add_f32_e32 v129, 1.0, v142
	v_rcp_f32_e32 v129, v129
	v_pk_fma_f32 v[142:143], v[82:83], v[170:171], v[174:175]
	v_pk_mul_f32 v[128:129], v[136:137], v[128:129]
	v_pk_fma_f32 v[142:143], v[94:95], v[166:167], v[142:143]
	v_pk_fma_f32 v[136:137], v[76:77], v[168:169], v[172:173]
	v_pk_fma_f32 v[130:131], v[162:163], v[130:131], v[142:143]
	v_pk_fma_f32 v[136:137], v[80:81], v[164:165], v[136:137]
	v_pk_mul_f32 v[128:129], v[130:131], v[128:129]
	v_pk_fma_f32 v[130:131], v[64:65], v[184:185], v[188:189]
	v_pk_fma_f32 v[64:65], v[64:65], v[180:181], v[72:73]
	v_pk_fma_f32 v[130:131], v[68:69], v[180:181], v[130:131]
	v_pk_fma_f32 v[64:65], v[68:69], v[176:177], v[64:65]
	v_pk_fma_f32 v[88:89], v[88:89], v[176:177], v[130:131]
	v_pk_fma_f32 v[92:93], v[92:93], v[160:161], v[136:137]
	v_mul_f32_e32 v130, 0xbfb8aa3b, v88
	v_mul_f32_e32 v131, 0xbfb8aa3b, v89
	v_exp_f32_e32 v130, v130
	v_exp_f32_e32 v131, v131
	v_mul_f32_e32 v68, 0xbfb8aa3b, v64
	v_exp_f32_e32 v72, v68
	v_add_f32_e32 v130, 1.0, v130
	v_add_f32_e32 v131, 1.0, v131
	v_rcp_f32_e32 v130, v130
	v_rcp_f32_e32 v131, v131
	v_pk_fma_f32 v[68:69], v[74:75], v[186:187], v[190:191]
	v_mul_f32_e32 v73, 0xbfb8aa3b, v65
	v_exp_f32_e32 v73, v73
	v_pk_mul_f32 v[88:89], v[88:89], v[130:131]
	v_add_f32_e32 v72, 1.0, v72
	v_pk_mul_f32 v[88:89], v[92:93], v[88:89]
	v_pk_fma_f32 v[92:93], v[66:67], v[186:187], v[190:191]
	v_pk_fma_f32 v[66:67], v[66:67], v[182:183], v[68:69]
	v_pk_fma_f32 v[92:93], v[70:71], v[182:183], v[92:93]
	v_pk_fma_f32 v[66:67], v[70:71], v[178:179], v[66:67]
	v_pk_fma_f32 v[90:91], v[90:91], v[178:179], v[92:93]
	v_mul_f32_e32 v68, 0xbfb8aa3b, v66
	v_mul_f32_e32 v92, 0xbfb8aa3b, v90
	v_mul_f32_e32 v69, 0xbfb8aa3b, v67
	v_exp_f32_e32 v93, v92
	v_mul_f32_e32 v92, 0xbfb8aa3b, v91
	v_exp_f32_e32 v68, v68
	v_exp_f32_e32 v69, v69
	v_exp_f32_e32 v130, v92
	v_add_f32_e32 v73, 1.0, v73
	v_add_f32_e32 v68, 1.0, v68
	v_add_f32_e32 v69, 1.0, v69
	v_cvt_pk_bf16_f32 v92, v88, v89
	v_add_f32_e32 v88, 1.0, v93
	v_add_f32_e32 v89, 1.0, v130
	v_rcp_f32_e32 v72, v72
	v_rcp_f32_e32 v73, v73
	v_rcp_f32_e32 v68, v68
	v_rcp_f32_e32 v69, v69
	v_rcp_f32_e32 v88, v88
	v_rcp_f32_e32 v89, v89
	v_pk_fma_f32 v[74:75], v[86:87], v[170:171], v[174:175]
	v_pk_fma_f32 v[130:131], v[78:79], v[170:171], v[174:175]
	v_pk_fma_f32 v[76:77], v[76:77], v[164:165], v[84:85]
	v_pk_fma_f32 v[70:71], v[78:79], v[166:167], v[74:75]
	v_pk_fma_f32 v[130:131], v[82:83], v[166:167], v[130:131]
	v_pk_fma_f32 v[76:77], v[80:81], v[160:161], v[76:77]
	v_pk_mul_f32 v[64:65], v[64:65], v[72:73]
	v_pk_fma_f32 v[70:71], v[82:83], v[162:163], v[70:71]
	v_pk_mul_f32 v[66:67], v[66:67], v[68:69]
	v_pk_fma_f32 v[94:95], v[94:95], v[162:163], v[130:131]
	v_pk_mul_f32 v[88:89], v[90:91], v[88:89]
	v_pk_mul_f32 v[64:65], v[76:77], v[64:65]
	v_pk_mul_f32 v[66:67], v[70:71], v[66:67]
	v_pk_mul_f32 v[88:89], v[94:95], v[88:89]
	v_cvt_pk_bf16_f32 v64, v64, v65
	v_cvt_pk_bf16_f32 v65, v66, v67
	v_add_u32_e32 v66, 0x83, v245
	v_cvt_pk_bf16_f32 v139, v128, v129
	v_add_u32_e32 v128, 0x81, v245
	v_cvt_pk_bf16_f32 v93, v88, v89
	v_add_u32_e32 v88, 0x82, v245
	v_mad_i64_i32 v[66:67], s[34:35], v66, s63, v[134:135]
	v_mad_i64_i32 v[128:129], s[34:35], v128, s63, v[134:135]
	v_mad_i64_i32 v[88:89], s[34:35], v88, s63, v[134:135]
	v_lshl_add_u64 v[82:83], v[66:67], 0, v[204:205]
	v_lshl_add_u64 v[128:129], v[128:129], 0, v[204:205]
	v_lshl_add_u64 v[88:89], v[88:89], 0, v[204:205]
	v_mov_b32_e32 v148, v64
	v_mov_b32_e32 v149, v65
	v_mov_b32_e32 v64, 0
	v_mov_b32_e32 v70, 0
	v_mov_b32_e32 v71, 0
	v_mov_b32_e32 v72, 0
	v_mov_b32_e32 v73, 0
	v_mov_b32_e32 v78, 0
	v_mov_b32_e32 v79, 0
	v_mov_b32_e32 v80, 0
	v_mov_b32_e32 v81, 0
	v_mov_b32_e32 v66, 0
	v_mov_b32_e32 v67, 0
	v_mov_b32_e32 v68, 0
	v_mov_b32_e32 v69, 0
	v_mov_b32_e32 v74, 0
	v_mov_b32_e32 v75, 0
	v_mov_b32_e32 v76, 0
	v_mov_b32_e32 v77, 0
	v_mov_b32_e32 v154, v138
	v_mov_b32_e32 v155, v139
	v_mov_b32_e32 v198, v92
	v_mov_b32_e32 v199, v93
	s_and_saveexec_b64 s[34:35], s[20:21]
	s_cbranch_execz .LBB0_1953
	ds_read_b128 v[74:77], v241
	ds_read_b128 v[66:69], v240
	ds_read_b128 v[78:81], v239
	ds_read_b128 v[70:73], v238
; #define LAS __attribute__((address_space(3)))
; __device__ __forceinline__ float sigmoidf_(float x) { return __builtin_amdgcn_rcpf(1.0f + __expf(-x)); }
;     __device__ __forceinline__ void operator()(AccRef acc, const Unit& u, int wr, int wc, int fr, int fq) const {
;     ...
;                 f32x4 h2v = (f32x4){0.f, 0.f, 0.f, 0.f}, h3v = h2v, h2g = h2v, h3g = h2v;
;                 const int pb = ai * 2 + wr - 1;
;                 if (pb >= 0 && fr == 0) { const LAS float* xp = xch + (pb * 2) * 256 + clb + 4 * n;
;                     h2v = *(const LAS f32x4*)(xp); h3v = *(const LAS f32x4*)(xp + 256); h2g = *(const LAS f32x4*)(xp + 128); h3g = *(const LAS f32x4*)(xp + 256 + 128); }
;                 float o[4][4];
; #pragma unroll
;                 for (int j = 0; j < 4; ++j) {
;                     const float v0 = acc[ai][0][0][n][j], v1 = acc[ai][0][1][n][j], v2 = acc[ai][0][2][n][j], v3 = acc[ai][0][3][n][j];
;                     const float g0 = acc[ai][1][0][n][j], g1 = acc[ai][1][1][n][j], g2 = acc[ai][1][2][n][j], g3 = acc[ai][1][3][n][j];
;                     const float pv3 = dpp_upd<0x111>(h3v[j], v3), pv2 = dpp_upd<0x111>(h2v[j], v2), pg3 = dpp_upd<0x111>(h3g[j], g3), pg2 = dpp_upd<0x111>(h2g[j], g2);
;                     const float hv0 = bvv[j] + w2v[j] * v0 + w1v[j] * pv3 + w0v[j] * pv2, hv1 = bvv[j] + w2v[j] * v1 + w1v[j] * v0 + w0v[j] * pv3;
;                     const float hv2 = bvv[j] + w2v[j] * v2 + w1v[j] * v1 + w0v[j] * v0, hv3 = bvv[j] + w2v[j] * v3 + w1v[j] * v2 + w0v[j] * v1;
;                     const float hg0 = bvg[j] + w2g[j] * g0 + w1g[j] * pg3 + w0g[j] * pg2, hg1 = bvg[j] + w2g[j] * g1 + w1g[j] * g0 + w0g[j] * pg3;
;                     const float hg2 = bvg[j] + w2g[j] * g2 + w1g[j] * g1 + w0g[j] * g0, hg3 = bvg[j] + w2g[j] * g3 + w1g[j] * g2 + w0g[j] * g1;
;                     o[0][j] = hg0 * sigmoidf_(hg0) * hv0; o[1][j] = hg1 * sigmoidf_(hg1) * hv1; o[2][j] = hg2 * sigmoidf_(hg2) * hv2; o[3][j] = hg3 * sigmoidf_(hg3) * hv3; }
; #pragma unroll
;                 for (int m = 0; m < 4; ++m) { u32x2 w; w.x = cvt_pk_bf16(o[m][0], o[m][1]); w.y = cvt_pk_bf16(o[m][2], o[m][3]);
;                     *(u32x2*)(Aout + (size_t)(row0 + ai * 128 + m) * FH + hc0 + 4 * n) = w; } } }
.LBB0_1953:
	s_or_b64 exec, exec, s[34:35]
	s_waitcnt lgkmcnt(0)
	v_mov_b32_dpp v70, v44 row_shr:1 row_mask:0xf bank_mask:0xf
	v_mov_b32_dpp v71, v45 row_shr:1 row_mask:0xf bank_mask:0xf
	s_waitcnt vmcnt(0)
	v_pk_fma_f32 v[84:85], v[56:57], v[120:121], v[124:125]
	v_mov_b32_dpp v78, v32 row_shr:1 row_mask:0xf bank_mask:0xf
	v_mov_b32_dpp v79, v33 row_shr:1 row_mask:0xf bank_mask:0xf
	v_pk_fma_f32 v[84:85], v[116:117], v[70:71], v[84:85]
	v_mov_b32_dpp v66, v52 row_shr:1 row_mask:0xf bank_mask:0xf
	v_pk_fma_f32 v[78:79], v[112:113], v[78:79], v[84:85]
	v_mov_b32_dpp v67, v53 row_shr:1 row_mask:0xf bank_mask:0xf
	v_mul_f32_e32 v65, 0xbfb8aa3b, v78
	v_exp_f32_e32 v65, v65
	v_mul_f32_e32 v84, 0xbfb8aa3b, v79
	v_exp_f32_e32 v85, v84
	v_pk_fma_f32 v[86:87], v[60:61], v[104:105], v[108:109]
	v_add_f32_e32 v65, 1.0, v65
	v_rcp_f32_e32 v84, v65
	v_add_f32_e32 v65, 1.0, v85
	v_rcp_f32_e32 v85, v65
	v_mov_b32_dpp v74, v40 row_shr:1 row_mask:0xf bank_mask:0xf
	v_mov_b32_dpp v75, v41 row_shr:1 row_mask:0xf bank_mask:0xf
	v_pk_fma_f32 v[86:87], v[100:101], v[66:67], v[86:87]
	v_pk_mul_f32 v[78:79], v[78:79], v[84:85]
	v_pk_fma_f32 v[74:75], v[96:97], v[74:75], v[86:87]
	v_mov_b32_dpp v72, v46 row_shr:1 row_mask:0xf bank_mask:0xf
	v_mov_b32_dpp v73, v47 row_shr:1 row_mask:0xf bank_mask:0xf
	v_pk_mul_f32 v[74:75], v[74:75], v[78:79]
	v_pk_fma_f32 v[78:79], v[58:59], v[122:123], v[126:127]
	v_mov_b32_dpp v80, v34 row_shr:1 row_mask:0xf bank_mask:0xf
	v_mov_b32_dpp v81, v35 row_shr:1 row_mask:0xf bank_mask:0xf
	v_pk_fma_f32 v[78:79], v[118:119], v[72:73], v[78:79]
	v_mov_b32_dpp v68, v54 row_shr:1 row_mask:0xf bank_mask:0xf
	v_pk_fma_f32 v[78:79], v[114:115], v[80:81], v[78:79]
	v_mov_b32_dpp v69, v55 row_shr:1 row_mask:0xf bank_mask:0xf
	v_mul_f32_e32 v65, 0xbfb8aa3b, v78
	v_exp_f32_e32 v65, v65
	v_mul_f32_e32 v80, 0xbfb8aa3b, v79
	v_exp_f32_e32 v81, v80
	v_pk_fma_f32 v[84:85], v[62:63], v[106:107], v[110:111]
	v_add_f32_e32 v65, 1.0, v65
	v_rcp_f32_e32 v80, v65
	v_add_f32_e32 v65, 1.0, v81
	v_rcp_f32_e32 v81, v65
	v_mov_b32_dpp v76, v42 row_shr:1 row_mask:0xf bank_mask:0xf
	v_mov_b32_dpp v77, v43 row_shr:1 row_mask:0xf bank_mask:0xf
	v_pk_fma_f32 v[84:85], v[102:103], v[68:69], v[84:85]
	v_pk_mul_f32 v[78:79], v[78:79], v[80:81]
	v_pk_fma_f32 v[76:77], v[98:99], v[76:77], v[84:85]
	v_cvt_pk_bf16_f32 v74, v74, v75
	v_pk_mul_f32 v[76:77], v[76:77], v[78:79]
	v_pk_fma_f32 v[44:45], v[44:45], v[120:121], v[124:125]
	v_cvt_pk_bf16_f32 v75, v76, v77
	v_pk_fma_f32 v[76:77], v[36:37], v[120:121], v[124:125]
	v_mov_b32_e32 v90, v246
	v_mov_b32_e32 v91, v247
	v_mov_b32_e32 v92, v74
	v_mov_b32_e32 v93, v75
	global_store_dwordx4 v[202:203], v[90:93], off
	v_pk_fma_f32 v[76:77], v[56:57], v[116:117], v[76:77]
	v_pk_fma_f32 v[52:53], v[52:53], v[104:105], v[108:109]
	v_pk_fma_f32 v[70:71], v[112:113], v[70:71], v[76:77]
	s_nop 0
	v_mul_f32_e32 v65, 0xbfb8aa3b, v70
	v_exp_f32_e32 v65, v65
	v_mul_f32_e32 v76, 0xbfb8aa3b, v71
	v_exp_f32_e32 v76, v76
	v_add_f32_e32 v65, 1.0, v65
	v_rcp_f32_e32 v74, v65
	v_add_f32_e32 v65, 1.0, v76
	v_rcp_f32_e32 v75, v65
	v_pk_fma_f32 v[76:77], v[48:49], v[104:105], v[108:109]
	v_pk_mul_f32 v[70:71], v[70:71], v[74:75]
	v_pk_fma_f32 v[76:77], v[60:61], v[100:101], v[76:77]
	v_pk_fma_f32 v[74:75], v[50:51], v[106:107], v[110:111]
	v_pk_fma_f32 v[66:67], v[96:97], v[66:67], v[76:77]
	v_pk_fma_f32 v[74:75], v[62:63], v[102:103], v[74:75]
	v_pk_mul_f32 v[66:67], v[66:67], v[70:71]
	v_pk_fma_f32 v[70:71], v[38:39], v[122:123], v[126:127]
	v_pk_fma_f32 v[68:69], v[98:99], v[68:69], v[74:75]
	v_pk_fma_f32 v[70:71], v[58:59], v[118:119], v[70:71]
	v_cvt_pk_bf16_f32 v66, v66, v67
	v_pk_fma_f32 v[70:71], v[114:115], v[72:73], v[70:71]
	s_nop 0
	v_mul_f32_e32 v65, 0xbfb8aa3b, v70
	v_exp_f32_e32 v65, v65
	v_mul_f32_e32 v72, 0xbfb8aa3b, v71
	v_exp_f32_e32 v73, v72
	v_add_f32_e32 v65, 1.0, v65
; #define LAS __attribute__((address_space(3)))
; __device__ __forceinline__ float sigmoidf_(float x) { return __builtin_amdgcn_rcpf(1.0f + __expf(-x)); }
;     __device__ __forceinline__ void operator()(AccRef acc, const Unit& u, int wr, int wc, int fr, int fq) const {
;     ...
;                 f32x4 h2v = (f32x4){0.f, 0.f, 0.f, 0.f}, h3v = h2v, h2g = h2v, h3g = h2v;
;                 const int pb = ai * 2 + wr - 1;
;                 if (pb >= 0 && fr == 0) { const LAS float* xp = xch + (pb * 2) * 256 + clb + 4 * n;
;                     h2v = *(const LAS f32x4*)(xp); h3v = *(const LAS f32x4*)(xp + 256); h2g = *(const LAS f32x4*)(xp + 128); h3g = *(const LAS f32x4*)(xp + 256 + 128); }
;                 float o[4][4];
; #pragma unroll
;                 for (int j = 0; j < 4; ++j) {
;                     const float v0 = acc[ai][0][0][n][j], v1 = acc[ai][0][1][n][j], v2 = acc[ai][0][2][n][j], v3 = acc[ai][0][3][n][j];
;                     const float g0 = acc[ai][1][0][n][j], g1 = acc[ai][1][1][n][j], g2 = acc[ai][1][2][n][j], g3 = acc[ai][1][3][n][j];
;                     const float pv3 = dpp_upd<0x111>(h3v[j], v3), pv2 = dpp_upd<0x111>(h2v[j], v2), pg3 = dpp_upd<0x111>(h3g[j], g3), pg2 = dpp_upd<0x111>(h2g[j], g2);
;                     const float hv0 = bvv[j] + w2v[j] * v0 + w1v[j] * pv3 + w0v[j] * pv2, hv1 = bvv[j] + w2v[j] * v1 + w1v[j] * v0 + w0v[j] * pv3;
;                     const float hv2 = bvv[j] + w2v[j] * v2 + w1v[j] * v1 + w0v[j] * v0, hv3 = bvv[j] + w2v[j] * v3 + w1v[j] * v2 + w0v[j] * v1;
;                     const float hg0 = bvg[j] + w2g[j] * g0 + w1g[j] * pg3 + w0g[j] * pg2, hg1 = bvg[j] + w2g[j] * g1 + w1g[j] * g0 + w0g[j] * pg3;
;                     const float hg2 = bvg[j] + w2g[j] * g2 + w1g[j] * g1 + w0g[j] * g0, hg3 = bvg[j] + w2g[j] * g3 + w1g[j] * g2 + w0g[j] * g1;
;                     o[0][j] = hg0 * sigmoidf_(hg0) * hv0; o[1][j] = hg1 * sigmoidf_(hg1) * hv1; o[2][j] = hg2 * sigmoidf_(hg2) * hv2; o[3][j] = hg3 * sigmoidf_(hg3) * hv3; }
; #pragma unroll
;                 for (int m = 0; m < 4; ++m) { u32x2 w; w.x = cvt_pk_bf16(o[m][0], o[m][1]); w.y = cvt_pk_bf16(o[m][2], o[m][3]);
;                     *(u32x2*)(Aout + (size_t)(row0 + ai * 128 + m) * FH + hc0 + 4 * n) = w; } } }
	v_rcp_f32_e32 v72, v65
	v_add_f32_e32 v65, 1.0, v73
	v_rcp_f32_e32 v73, v65
	s_nop 0
	v_pk_mul_f32 v[70:71], v[70:71], v[72:73]
	s_nop 0
	v_pk_mul_f32 v[68:69], v[68:69], v[70:71]
	s_nop 0
	v_cvt_pk_bf16_f32 v67, v68, v69
	v_pk_fma_f32 v[68:69], v[32:33], v[120:121], v[124:125]
	v_mov_b32_e32 v134, v248
	v_mov_b32_e32 v135, v249
	v_mov_b32_e32 v136, v66
	v_mov_b32_e32 v137, v67
	global_store_dwordx4 v[196:197], v[134:137], off
	v_pk_fma_f32 v[68:69], v[36:37], v[116:117], v[68:69]
	v_pk_fma_f32 v[32:33], v[32:33], v[116:117], v[44:45]
	v_pk_fma_f32 v[56:57], v[56:57], v[112:113], v[68:69]
	v_pk_fma_f32 v[32:33], v[36:37], v[112:113], v[32:33]
	v_mul_f32_e32 v65, 0xbfb8aa3b, v56
	v_exp_f32_e32 v65, v65
	v_mul_f32_e32 v68, 0xbfb8aa3b, v57
	v_exp_f32_e32 v68, v68
	v_mul_f32_e32 v36, 0xbfb8aa3b, v32
	v_add_f32_e32 v65, 1.0, v65
	v_rcp_f32_e32 v66, v65
	v_add_f32_e32 v65, 1.0, v68
	v_rcp_f32_e32 v67, v65
	v_pk_fma_f32 v[68:69], v[40:41], v[104:105], v[108:109]
	v_exp_f32_e32 v44, v36
	v_pk_fma_f32 v[68:69], v[48:49], v[100:101], v[68:69]
	v_pk_mul_f32 v[56:57], v[56:57], v[66:67]
	v_pk_fma_f32 v[60:61], v[60:61], v[96:97], v[68:69]
	v_pk_fma_f32 v[36:37], v[46:47], v[122:123], v[126:127]
	v_pk_mul_f32 v[56:57], v[60:61], v[56:57]
	v_pk_fma_f32 v[60:61], v[34:35], v[122:123], v[126:127]
	v_pk_fma_f32 v[34:35], v[34:35], v[118:119], v[36:37]
	v_pk_fma_f32 v[60:61], v[38:39], v[118:119], v[60:61]
	v_pk_fma_f32 v[34:35], v[38:39], v[114:115], v[34:35]
	v_pk_fma_f32 v[58:59], v[58:59], v[114:115], v[60:61]
	v_mul_f32_e32 v45, 0xbfb8aa3b, v33
	v_mul_f32_e32 v60, 0xbfb8aa3b, v58
	v_mul_f32_e32 v36, 0xbfb8aa3b, v34
	v_mul_f32_e32 v37, 0xbfb8aa3b, v35
	v_exp_f32_e32 v60, v60
	v_mul_f32_e32 v61, 0xbfb8aa3b, v59
	v_exp_f32_e32 v45, v45
	v_exp_f32_e32 v36, v36
	v_exp_f32_e32 v37, v37
	v_exp_f32_e32 v61, v61
	v_cvt_pk_bf16_f32 v56, v56, v57
	v_add_f32_e32 v57, 1.0, v60
	v_add_f32_e32 v44, 1.0, v44
	v_add_f32_e32 v45, 1.0, v45
	v_add_f32_e32 v36, 1.0, v36
	v_add_f32_e32 v37, 1.0, v37
	v_rcp_f32_e32 v60, v57
	v_add_f32_e32 v57, 1.0, v61
	v_rcp_f32_e32 v44, v44
	v_rcp_f32_e32 v45, v45
	v_rcp_f32_e32 v36, v36
	v_rcp_f32_e32 v37, v37
	v_rcp_f32_e32 v61, v57
	v_pk_fma_f32 v[46:47], v[54:55], v[106:107], v[110:111]
	v_pk_fma_f32 v[66:67], v[42:43], v[106:107], v[110:111]
	v_pk_fma_f32 v[40:41], v[40:41], v[100:101], v[52:53]
	v_pk_fma_f32 v[38:39], v[42:43], v[102:103], v[46:47]
	v_pk_fma_f32 v[66:67], v[50:51], v[102:103], v[66:67]
	v_pk_fma_f32 v[40:41], v[48:49], v[96:97], v[40:41]
	v_pk_mul_f32 v[32:33], v[32:33], v[44:45]
	v_pk_fma_f32 v[38:39], v[50:51], v[98:99], v[38:39]
	v_pk_mul_f32 v[34:35], v[34:35], v[36:37]
	v_pk_fma_f32 v[62:63], v[62:63], v[98:99], v[66:67]
	v_pk_mul_f32 v[58:59], v[58:59], v[60:61]
	v_pk_mul_f32 v[32:33], v[40:41], v[32:33]
	v_pk_mul_f32 v[34:35], v[38:39], v[34:35]
	v_pk_mul_f32 v[58:59], v[62:63], v[58:59]
	v_cvt_pk_bf16_f32 v32, v32, v33
	v_cvt_pk_bf16_f32 v33, v34, v35
	v_cvt_pk_bf16_f32 v57, v58, v59
	v_mov_b32_e32 v158, v250
	v_mov_b32_e32 v159, v251
	v_mov_b32_e32 v160, v32
	v_mov_b32_e32 v161, v33
	global_store_dwordx4 v[140:141], v[158:161], off
	v_mov_b32_e32 v65, 0
	v_mov_b32_e32 v66, 0
	v_mov_b32_e32 v67, 0
	v_mov_b32_e32 v40, 0
	v_mov_b32_e32 v41, 0
	v_mov_b32_e32 v42, 0
	v_mov_b32_e32 v43, 0
	v_mov_b32_e32 v32, 0
	v_mov_b32_e32 v33, 0
	v_mov_b32_e32 v34, 0
	v_mov_b32_e32 v35, 0
	v_mov_b32_e32 v36, 0
	v_mov_b32_e32 v37, 0
	v_mov_b32_e32 v38, 0
	v_mov_b32_e32 v39, 0
	v_mov_b32_e32 v162, v253
	v_mov_b32_e32 v163, v254
	v_mov_b32_e32 v164, v56
	v_mov_b32_e32 v165, v57
	global_store_dwordx4 v[152:153], v[162:165], off
	s_and_saveexec_b64 s[34:35], s[22:23]
	s_cbranch_execz .LBB0_1936
	ds_read_b128 v[36:39], v236 offset:2064
	ds_read_b128 v[40:43], v236 offset:2576
	ds_read_b128 v[32:35], v236 offset:3088
	ds_read_b128 v[64:67], v236 offset:3600
	s_branch .LBB0_1936
